# GEMM k-loops: 100 LDS-DMA pieces issued in SGPR-base form (no 64-bit VALU address add per piece)
# speedup vs baseline: 1.0078x; 1.0018x over previous
; #define PG8_STAGE(bufoff, gbase, voff) do { _Pragma("unroll") for (int _i = 0; _i < 2; ++_i) \
;         __builtin_amdgcn_global_load_lds((const unsigned*)((const char*)(gbase) + (voff)[_i]), (PG8_LAS unsigned*)(lds + (bufoff) + ldsw + _i * 8192), 16, 0, 0); } while (0)
; #define PG8_LDA(dst, b, h) do { _Pragma("unroll") for (int m = 0; m < 4; ++m) _Pragma("unroll") for (int k = 0; k < 2; ++k) dst[m][k] = *(const PG8_LAS bf16x8*)(lds + PG8_SA(b, h) + aoff + m * 2048 + k * 1024); } while (0)
; #define PG8_LDB(dst, b, h) do { _Pragma("unroll") for (int n = 0; n < 2; ++n) _Pragma("unroll") for (int k = 0; k < 2; ++k) dst[n][k] = *(const PG8_LAS bf16x8*)(lds + PG8_SB(b, h) + boff + n * 2048 + k * 1024); } while (0)
; #define PG8_MMA(ai, bj, At, Bt) do { __builtin_amdgcn_s_setprio(1); _Pragma("unroll") for (int m = 0; m < 4; ++m) _Pragma("unroll") for (int n = 0; n < 2; ++n) _Pragma("unroll") for (int k = 0; k < 2; ++k) \
;         acc[ai][bj][m][n] = __builtin_amdgcn_mfma_f32_16x16x32_bf16(Bt[n][k], At[m][k], acc[ai][bj][m][n], 0, 0, 0); __builtin_amdgcn_s_setprio(0); } while (0)
; #define PG8_WAIT_V(n) asm volatile("s_waitcnt vmcnt(" #n ")" ::: "memory")
; #define PG8_BAR __builtin_amdgcn_s_barrier()
; template <class Epi, class Sched, bool ALIGN_EPI = false, bool SP2 = false>
; __device__ __forceinline__ void gemm_phase(PG8_LAS unsigned char* lds, const Gemm g, const Sched& S, const Epi& E) {
;     ...
;         for (int t = 0; t < nt; t += 2) {
;             const bool last = (t == nt - 2);
;             const char* a1 = cA + (size_t)(t + 1) * kstep;
;             const char* a2 = last ? nA : cA + (size_t)(t + 2) * kstep; const char* b2 = last ? nB : cB + (size_t)(t + 2) * kstep;
;             const char* a3 = a2 + kstep; const char* b3 = b2 + kstep;
;             if (last && has_next) S.a_ready(nxt);
;             if constexpr (SP2) {
;             PG8_LDB(B0, 0, 0); PG8_LDB(B1, 0, 1); PG8_SCHED; PG8_LDA(At, 0, 0); PG8_STAGE(PG8_SA(1, 1), a1 + hstep, voffA);
;             PG8_WAIT_V(8); PG8_WAIT_L(0); PG8_BAR; PG8_MMA(0, 0, At, B0); PG8_MMA(0, 1, At, B1); PG8_BAR; PG8_SCHED;
;             PG8_LDA(At, 0, 1); PG8_STAGE(PG8_SB(0, 0), b2, voffB); PG8_STAGE(PG8_SB(0, 1), b2 + hstep, voffB); PG8_STAGE(PG8_SA(0, 0), a2, voffA);
;             PG8_WAIT_V(8); PG8_WAIT_L(0); PG8_BAR; PG8_MMA(1, 0, At, B0); PG8_MMA(1, 1, At, B1); PG8_BAR; PG8_SCHED;
.LBB0_218:
	ds_read_b128 v[148:151], v157
	ds_read_b128 v[166:169], v157 offset:1024
	ds_read_b128 v[172:175], v157 offset:2048
	ds_read_b128 v[176:179], v157 offset:3072
	ds_read_b128 v[180:183], v158
	ds_read_b128 v[184:187], v158 offset:1024
	ds_read_b128 v[188:191], v158 offset:2048
	ds_read_b128 v[196:199], v158 offset:3072
	s_add_u32 s6, s52, 0xfffc0080
	s_addc_u32 s7, s53, -1
	s_cmp_eq_u32 s72, 12
	s_cselect_b32 s57, s4, s7
	s_cselect_b32 s56, s41, s6
	s_cselect_b32 s55, s39, s33
	s_cselect_b32 s54, s78, s79
	s_add_i32 m0, s37, 0xc000
	ds_read_b128 v[200:203], v159
	ds_read_b128 v[204:207], v159 offset:1024
	ds_read_b128 v[208:211], v159 offset:2048
	ds_read_b128 v[212:215], v159 offset:3072
	ds_read_b128 v[216:219], v159 offset:4096
	ds_read_b128 v[220:223], v159 offset:5120
	ds_read_b128 v[224:227], v159 offset:6144
	ds_read_b128 v[228:231], v159 offset:7168
	global_load_lds_dwordx4 v140, s[52:53]
	s_add_i32 m0, s37, 0xe000
	s_nop 0
	global_load_lds_dwordx4 v142, s[52:53]
	s_waitcnt vmcnt(8)
	s_waitcnt lgkmcnt(0)
	s_barrier
	s_waitcnt lgkmcnt(0)
	v_mfma_f32_16x16x32_bf16 v[124:127], v[148:151], v[200:203], v[124:127]
	v_mfma_f32_16x16x32_bf16 v[116:119], v[172:175], v[200:203], v[116:119]
	v_mfma_f32_16x16x32_bf16 v[108:111], v[148:151], v[208:211], v[108:111]
	v_mfma_f32_16x16x32_bf16 v[100:103], v[172:175], v[208:211], v[100:103]
	v_mfma_f32_16x16x32_bf16 v[92:95], v[148:151], v[216:219], v[92:95]
	v_mfma_f32_16x16x32_bf16 v[84:87], v[172:175], v[216:219], v[84:87]
	v_mfma_f32_16x16x32_bf16 v[76:79], v[148:151], v[224:227], v[76:79]
	v_mfma_f32_16x16x32_bf16 v[68:71], v[172:175], v[224:227], v[68:71]
	v_mfma_f32_16x16x32_bf16 v[124:127], v[166:169], v[204:207], v[124:127]
	v_mfma_f32_16x16x32_bf16 v[116:119], v[176:179], v[204:207], v[116:119]
	v_mfma_f32_16x16x32_bf16 v[108:111], v[166:169], v[212:215], v[108:111]
	v_mfma_f32_16x16x32_bf16 v[100:103], v[176:179], v[212:215], v[100:103]
	v_mfma_f32_16x16x32_bf16 v[92:95], v[166:169], v[220:223], v[92:95]
	v_mfma_f32_16x16x32_bf16 v[84:87], v[176:179], v[220:223], v[84:87]
	v_mfma_f32_16x16x32_bf16 v[76:79], v[166:169], v[228:231], v[76:79]
	v_mfma_f32_16x16x32_bf16 v[68:71], v[176:179], v[228:231], v[68:71]
	v_mfma_f32_16x16x32_bf16 v[120:123], v[180:183], v[200:203], v[120:123]
	v_mfma_f32_16x16x32_bf16 v[112:115], v[188:191], v[200:203], v[112:115]
	v_mfma_f32_16x16x32_bf16 v[104:107], v[180:183], v[208:211], v[104:107]
	v_mfma_f32_16x16x32_bf16 v[96:99], v[188:191], v[208:211], v[96:99]
	v_mfma_f32_16x16x32_bf16 v[88:91], v[180:183], v[216:219], v[88:91]
	v_mfma_f32_16x16x32_bf16 v[80:83], v[188:191], v[216:219], v[80:83]
	v_mfma_f32_16x16x32_bf16 v[72:75], v[180:183], v[224:227], v[72:75]
	v_mfma_f32_16x16x32_bf16 v[64:67], v[188:191], v[224:227], v[64:67]
	v_mfma_f32_16x16x32_bf16 v[120:123], v[184:187], v[204:207], v[120:123]
	v_mfma_f32_16x16x32_bf16 v[112:115], v[196:199], v[204:207], v[112:115]
	v_mfma_f32_16x16x32_bf16 v[104:107], v[184:187], v[212:215], v[104:107]
	v_mfma_f32_16x16x32_bf16 v[96:99], v[196:199], v[212:215], v[96:99]
	v_mfma_f32_16x16x32_bf16 v[88:91], v[184:187], v[220:223], v[88:91]
	v_mfma_f32_16x16x32_bf16 v[80:83], v[196:199], v[220:223], v[80:83]
	v_mfma_f32_16x16x32_bf16 v[72:75], v[184:187], v[228:231], v[72:75]
	v_mfma_f32_16x16x32_bf16 v[64:67], v[196:199], v[228:231], v[64:67]
	s_barrier
	s_add_i32 s6, s69, s36
	v_lshl_add_u64 v[152:153], s[54:55], 0, v[136:137]
	s_mov_b32 m0, s6
	ds_read_b128 v[200:203], v159 offset:16384
	ds_read_b128 v[204:207], v159 offset:17408
	ds_read_b128 v[208:211], v159 offset:18432
	ds_read_b128 v[212:215], v159 offset:19456
	ds_read_b128 v[216:219], v159 offset:20480
	ds_read_b128 v[220:223], v159 offset:21504
	ds_read_b128 v[224:227], v159 offset:22528
	ds_read_b128 v[228:231], v159 offset:23552
	global_load_lds_dwordx4 v[152:153], off
	s_add_i32 m0, s6, 0x2000
	s_add_u32 s6, s54, 0x40000
	v_lshl_add_u64 v[162:163], s[54:55], 0, v[132:133]
	s_addc_u32 s7, s55, 0
	s_add_i32 s73, s74, s36
	global_load_lds_dwordx4 v[162:163], off
	s_mov_b32 m0, s73
	v_lshl_add_u64 v[234:235], s[56:57], 0, v[134:135]
	global_load_lds_dwordx4 v136, s[6:7]
	s_add_i32 m0, s73, 0x2000
	s_nop 0
	global_load_lds_dwordx4 v132, s[6:7]
	v_lshl_add_u64 v[232:233], s[56:57], 0, v[138:139]
	s_mov_b32 m0, s37
	s_nop 0
	global_load_lds_dwordx4 v[232:233], off
	s_mov_b32 m0, s59
	s_nop 0
	global_load_lds_dwordx4 v[234:235], off
	s_waitcnt vmcnt(8)
	s_waitcnt lgkmcnt(0)
	s_barrier
	s_waitcnt lgkmcnt(0)
	v_mfma_f32_16x16x32_bf16 v[60:63], v[148:151], v[200:203], v[60:63]
	v_mfma_f32_16x16x32_bf16 v[52:55], v[172:175], v[200:203], v[52:55]
	v_mfma_f32_16x16x32_bf16 v[44:47], v[148:151], v[208:211], v[44:47]
	v_mfma_f32_16x16x32_bf16 v[36:39], v[172:175], v[208:211], v[36:39]
	v_mfma_f32_16x16x32_bf16 v[28:31], v[148:151], v[216:219], v[28:31]
	v_mfma_f32_16x16x32_bf16 v[20:23], v[172:175], v[216:219], v[20:23]
	v_mfma_f32_16x16x32_bf16 v[12:15], v[148:151], v[224:227], v[12:15]
	v_mfma_f32_16x16x32_bf16 v[4:7], v[172:175], v[224:227], v[4:7]
	v_mfma_f32_16x16x32_bf16 v[60:63], v[166:169], v[204:207], v[60:63]
	v_mfma_f32_16x16x32_bf16 v[52:55], v[176:179], v[204:207], v[52:55]
	v_mfma_f32_16x16x32_bf16 v[44:47], v[166:169], v[212:215], v[44:47]
	v_mfma_f32_16x16x32_bf16 v[36:39], v[176:179], v[212:215], v[36:39]
	v_mfma_f32_16x16x32_bf16 v[28:31], v[166:169], v[220:223], v[28:31]
	v_mfma_f32_16x16x32_bf16 v[20:23], v[176:179], v[220:223], v[20:23]
	v_mfma_f32_16x16x32_bf16 v[12:15], v[166:169], v[228:231], v[12:15]
	v_mfma_f32_16x16x32_bf16 v[4:7], v[176:179], v[228:231], v[4:7]
	v_mfma_f32_16x16x32_bf16 v[56:59], v[180:183], v[200:203], v[56:59]
	v_mfma_f32_16x16x32_bf16 v[48:51], v[188:191], v[200:203], v[48:51]
	v_mfma_f32_16x16x32_bf16 v[40:43], v[180:183], v[208:211], v[40:43]
	v_mfma_f32_16x16x32_bf16 v[32:35], v[188:191], v[208:211], v[32:35]
	v_mfma_f32_16x16x32_bf16 v[24:27], v[180:183], v[216:219], v[24:27]
	v_mfma_f32_16x16x32_bf16 v[16:19], v[188:191], v[216:219], v[16:19]
	v_mfma_f32_16x16x32_bf16 v[8:11], v[180:183], v[224:227], v[8:11]
	v_mfma_f32_16x16x32_bf16 v[0:3], v[188:191], v[224:227], v[0:3]
	v_mfma_f32_16x16x32_bf16 v[56:59], v[184:187], v[204:207], v[56:59]
	v_mfma_f32_16x16x32_bf16 v[48:51], v[196:199], v[204:207], v[48:51]
	v_mfma_f32_16x16x32_bf16 v[40:43], v[184:187], v[212:215], v[40:43]
	v_mfma_f32_16x16x32_bf16 v[32:35], v[196:199], v[212:215], v[32:35]
	v_mfma_f32_16x16x32_bf16 v[24:27], v[184:187], v[220:223], v[24:27]
	v_mfma_f32_16x16x32_bf16 v[16:19], v[196:199], v[220:223], v[16:19]
	v_mfma_f32_16x16x32_bf16 v[8:11], v[184:187], v[228:231], v[8:11]
	v_mfma_f32_16x16x32_bf16 v[0:3], v[196:199], v[228:231], v[0:3]
	s_barrier
; #define PG8_STAGE(bufoff, gbase, voff) do { _Pragma("unroll") for (int _i = 0; _i < 2; ++_i) \
;         __builtin_amdgcn_global_load_lds((const unsigned*)((const char*)(gbase) + (voff)[_i]), (PG8_LAS unsigned*)(lds + (bufoff) + ldsw + _i * 8192), 16, 0, 0); } while (0)
; #define PG8_LDA(dst, b, h) do { _Pragma("unroll") for (int m = 0; m < 4; ++m) _Pragma("unroll") for (int k = 0; k < 2; ++k) dst[m][k] = *(const PG8_LAS bf16x8*)(lds + PG8_SA(b, h) + aoff + m * 2048 + k * 1024); } while (0)
; #define PG8_LDB(dst, b, h) do { _Pragma("unroll") for (int n = 0; n < 2; ++n) _Pragma("unroll") for (int k = 0; k < 2; ++k) dst[n][k] = *(const PG8_LAS bf16x8*)(lds + PG8_SB(b, h) + boff + n * 2048 + k * 1024); } while (0)
; #define PG8_MMA(ai, bj, At, Bt) do { __builtin_amdgcn_s_setprio(1); _Pragma("unroll") for (int m = 0; m < 4; ++m) _Pragma("unroll") for (int n = 0; n < 2; ++n) _Pragma("unroll") for (int k = 0; k < 2; ++k) \
;         acc[ai][bj][m][n] = __builtin_amdgcn_mfma_f32_16x16x32_bf16(Bt[n][k], At[m][k], acc[ai][bj][m][n], 0, 0, 0); __builtin_amdgcn_s_setprio(0); } while (0)
; #define PG8_WAIT_V(n) asm volatile("s_waitcnt vmcnt(" #n ")" ::: "memory")
; #define PG8_WAIT_L(n) asm volatile("s_waitcnt lgkmcnt(" #n ")" ::: "memory")
; #define PG8_BAR __builtin_amdgcn_s_barrier()
; #define PG8_SCHED __builtin_amdgcn_sched_barrier(0)
; template <class Epi, class Sched, bool ALIGN_EPI = false, bool SP2 = false>
; __device__ __forceinline__ void gemm_phase(PG8_LAS unsigned char* lds, const Gemm g, const Sched& S, const Epi& E) {
;     ...
;             PG8_LDB(B0, 1, 0); PG8_LDB(B1, 1, 1); PG8_SCHED; PG8_LDA(At, 1, 0); PG8_STAGE(PG8_SA(0, 1), a2 + hstep, voffA);
;             PG8_WAIT_V(8); PG8_WAIT_L(0); PG8_BAR; PG8_MMA(0, 0, At, B0); PG8_MMA(0, 1, At, B1); PG8_BAR; PG8_SCHED;
;             PG8_LDA(At, 1, 1); PG8_STAGE(PG8_SB(1, 0), b3, voffB); PG8_STAGE(PG8_SB(1, 1), b3 + hstep, voffB); PG8_STAGE(PG8_SA(1, 0), a3, voffA);
;             PG8_WAIT_V(8); PG8_WAIT_L(0); PG8_BAR; PG8_MMA(1, 0, At, B0); PG8_MMA(1, 1, At, B1); PG8_BAR; PG8_SCHED;
	s_add_i32 s73, 0, 0x18000
	v_add_u32_e32 v161, s73, v154
	s_add_i32 s80, 0, 0x1c000
	ds_read_b128 v[148:151], v161
	ds_read_b128 v[166:169], v161 offset:1024
	ds_read_b128 v[172:175], v161 offset:2048
	ds_read_b128 v[176:179], v161 offset:3072
	v_add_u32_e32 v161, s80, v154
	ds_read_b128 v[180:183], v161
	ds_read_b128 v[184:187], v161 offset:1024
	ds_read_b128 v[188:191], v161 offset:2048
	ds_read_b128 v[196:199], v161 offset:3072
	s_add_u32 s6, s56, 0x40000
	s_addc_u32 s7, s57, 0
	s_mov_b32 m0, s60
	ds_read_b128 v[200:203], v159 offset:32768
	ds_read_b128 v[204:207], v159 offset:33792
	ds_read_b128 v[208:211], v159 offset:34816
	ds_read_b128 v[212:215], v159 offset:35840
	ds_read_b128 v[216:219], v159 offset:36864
	ds_read_b128 v[220:223], v159 offset:37888
	ds_read_b128 v[224:227], v159 offset:38912
	ds_read_b128 v[228:231], v159 offset:39936
	global_load_lds_dwordx4 v138, s[6:7]
	s_mov_b32 m0, s61
	s_nop 0
	global_load_lds_dwordx4 v134, s[6:7]
	s_waitcnt vmcnt(8)
	s_waitcnt lgkmcnt(0)
	s_barrier
	s_waitcnt lgkmcnt(0)
	v_mfma_f32_16x16x32_bf16 v[124:127], v[148:151], v[200:203], v[124:127]
	v_mfma_f32_16x16x32_bf16 v[116:119], v[172:175], v[200:203], v[116:119]
	v_mfma_f32_16x16x32_bf16 v[108:111], v[148:151], v[208:211], v[108:111]
	v_mfma_f32_16x16x32_bf16 v[100:103], v[172:175], v[208:211], v[100:103]
	v_mfma_f32_16x16x32_bf16 v[92:95], v[148:151], v[216:219], v[92:95]
	v_mfma_f32_16x16x32_bf16 v[84:87], v[172:175], v[216:219], v[84:87]
	v_mfma_f32_16x16x32_bf16 v[76:79], v[148:151], v[224:227], v[76:79]
	v_mfma_f32_16x16x32_bf16 v[68:71], v[172:175], v[224:227], v[68:71]
	v_mfma_f32_16x16x32_bf16 v[124:127], v[166:169], v[204:207], v[124:127]
	v_mfma_f32_16x16x32_bf16 v[116:119], v[176:179], v[204:207], v[116:119]
	v_mfma_f32_16x16x32_bf16 v[108:111], v[166:169], v[212:215], v[108:111]
	v_mfma_f32_16x16x32_bf16 v[100:103], v[176:179], v[212:215], v[100:103]
	v_mfma_f32_16x16x32_bf16 v[92:95], v[166:169], v[220:223], v[92:95]
	v_mfma_f32_16x16x32_bf16 v[84:87], v[176:179], v[220:223], v[84:87]
	v_mfma_f32_16x16x32_bf16 v[76:79], v[166:169], v[228:231], v[76:79]
	v_mfma_f32_16x16x32_bf16 v[68:71], v[176:179], v[228:231], v[68:71]
	v_mfma_f32_16x16x32_bf16 v[120:123], v[180:183], v[200:203], v[120:123]
	v_mfma_f32_16x16x32_bf16 v[112:115], v[188:191], v[200:203], v[112:115]
	v_mfma_f32_16x16x32_bf16 v[104:107], v[180:183], v[208:211], v[104:107]
	v_mfma_f32_16x16x32_bf16 v[96:99], v[188:191], v[208:211], v[96:99]
	v_mfma_f32_16x16x32_bf16 v[88:91], v[180:183], v[216:219], v[88:91]
	v_mfma_f32_16x16x32_bf16 v[80:83], v[188:191], v[216:219], v[80:83]
	v_mfma_f32_16x16x32_bf16 v[72:75], v[180:183], v[224:227], v[72:75]
	v_mfma_f32_16x16x32_bf16 v[64:67], v[188:191], v[224:227], v[64:67]
	v_mfma_f32_16x16x32_bf16 v[120:123], v[184:187], v[204:207], v[120:123]
	v_mfma_f32_16x16x32_bf16 v[112:115], v[196:199], v[204:207], v[112:115]
	v_mfma_f32_16x16x32_bf16 v[104:107], v[184:187], v[212:215], v[104:107]
	v_mfma_f32_16x16x32_bf16 v[96:99], v[196:199], v[212:215], v[96:99]
	v_mfma_f32_16x16x32_bf16 v[88:91], v[184:187], v[220:223], v[88:91]
	v_mfma_f32_16x16x32_bf16 v[80:83], v[196:199], v[220:223], v[80:83]
	v_mfma_f32_16x16x32_bf16 v[72:75], v[184:187], v[228:231], v[72:75]
	v_mfma_f32_16x16x32_bf16 v[64:67], v[196:199], v[228:231], v[64:67]
	s_barrier
	s_add_i32 s6, s73, s36
	v_lshl_add_u64 v[152:153], v[152:153], 0, s[30:31]
	s_mov_b32 m0, s6
	ds_read_b128 v[200:203], v159 offset:49152
	ds_read_b128 v[204:207], v159 offset:50176
	ds_read_b128 v[208:211], v159 offset:51200
	ds_read_b128 v[212:215], v159 offset:52224
	ds_read_b128 v[216:219], v159 offset:53248
	ds_read_b128 v[220:223], v159 offset:54272
	ds_read_b128 v[224:227], v159 offset:55296
	ds_read_b128 v[228:231], v159 offset:56320
	global_load_lds_dwordx4 v[152:153], off
	s_add_i32 m0, s6, 0x2000
	s_add_u32 s6, s54, 0x40080
	v_lshl_add_u64 v[152:153], v[162:163], 0, s[30:31]
	s_addc_u32 s7, s55, 0
	s_add_i32 s54, s80, s36
	global_load_lds_dwordx4 v[152:153], off
	s_mov_b32 m0, s54
	s_nop 0
	global_load_lds_dwordx4 v136, s[6:7]
	s_add_i32 m0, s54, 0x2000
	s_nop 0
	global_load_lds_dwordx4 v132, s[6:7]
	v_lshl_add_u64 v[152:153], v[232:233], 0, s[30:31]
	s_mov_b32 m0, s67
	s_nop 0
	global_load_lds_dwordx4 v[152:153], off
	v_lshl_add_u64 v[152:153], v[234:235], 0, s[30:31]
	s_mov_b32 m0, s68
	s_nop 0
	global_load_lds_dwordx4 v[152:153], off
	s_waitcnt vmcnt(8)
	s_waitcnt lgkmcnt(0)
	s_barrier
	s_waitcnt lgkmcnt(0)
	v_mfma_f32_16x16x32_bf16 v[60:63], v[148:151], v[200:203], v[60:63]
	v_mfma_f32_16x16x32_bf16 v[52:55], v[172:175], v[200:203], v[52:55]
	v_mfma_f32_16x16x32_bf16 v[44:47], v[148:151], v[208:211], v[44:47]
	v_mfma_f32_16x16x32_bf16 v[36:39], v[172:175], v[208:211], v[36:39]
	v_mfma_f32_16x16x32_bf16 v[28:31], v[148:151], v[216:219], v[28:31]
	v_mfma_f32_16x16x32_bf16 v[20:23], v[172:175], v[216:219], v[20:23]
	v_mfma_f32_16x16x32_bf16 v[12:15], v[148:151], v[224:227], v[12:15]
	v_mfma_f32_16x16x32_bf16 v[4:7], v[172:175], v[224:227], v[4:7]
	v_mfma_f32_16x16x32_bf16 v[60:63], v[166:169], v[204:207], v[60:63]
	v_mfma_f32_16x16x32_bf16 v[52:55], v[176:179], v[204:207], v[52:55]
	v_mfma_f32_16x16x32_bf16 v[44:47], v[166:169], v[212:215], v[44:47]
	v_mfma_f32_16x16x32_bf16 v[36:39], v[176:179], v[212:215], v[36:39]
	v_mfma_f32_16x16x32_bf16 v[28:31], v[166:169], v[220:223], v[28:31]
	v_mfma_f32_16x16x32_bf16 v[20:23], v[176:179], v[220:223], v[20:23]
	v_mfma_f32_16x16x32_bf16 v[12:15], v[166:169], v[228:231], v[12:15]
	v_mfma_f32_16x16x32_bf16 v[4:7], v[176:179], v[228:231], v[4:7]
	v_mfma_f32_16x16x32_bf16 v[56:59], v[180:183], v[200:203], v[56:59]
	v_mfma_f32_16x16x32_bf16 v[48:51], v[188:191], v[200:203], v[48:51]
	v_mfma_f32_16x16x32_bf16 v[40:43], v[180:183], v[208:211], v[40:43]
	v_mfma_f32_16x16x32_bf16 v[32:35], v[188:191], v[208:211], v[32:35]
	v_mfma_f32_16x16x32_bf16 v[24:27], v[180:183], v[216:219], v[24:27]
	v_mfma_f32_16x16x32_bf16 v[16:19], v[188:191], v[216:219], v[16:19]
	v_mfma_f32_16x16x32_bf16 v[8:11], v[180:183], v[224:227], v[8:11]
	v_mfma_f32_16x16x32_bf16 v[0:3], v[188:191], v[224:227], v[0:3]
	v_mfma_f32_16x16x32_bf16 v[56:59], v[184:187], v[204:207], v[56:59]
	v_mfma_f32_16x16x32_bf16 v[48:51], v[196:199], v[204:207], v[48:51]
	v_mfma_f32_16x16x32_bf16 v[40:43], v[184:187], v[212:215], v[40:43]
	v_mfma_f32_16x16x32_bf16 v[32:35], v[196:199], v[212:215], v[32:35]
	v_mfma_f32_16x16x32_bf16 v[24:27], v[184:187], v[220:223], v[24:27]
	v_mfma_f32_16x16x32_bf16 v[16:19], v[196:199], v[220:223], v[16:19]
	v_mfma_f32_16x16x32_bf16 v[8:11], v[184:187], v[228:231], v[8:11]
	v_mfma_f32_16x16x32_bf16 v[0:3], v[196:199], v[228:231], v[0:3]
	s_barrier
	s_add_i32 s72, s72, 2
	s_add_u32 s52, s52, 0x100
	s_addc_u32 s53, s53, 0
	s_add_u32 s79, s79, 0x100
	s_addc_u32 s33, s33, 0
	s_cmp_gt_u32 s72, 13
	s_cbranch_scc0 .LBB0_218
	s_and_b64 vcc, exec, s[34:35]
	s_cbranch_vccz .LBB0_221
	s_barrier

; #define PG8_STAGE(bufoff, gbase, voff) do { _Pragma("unroll") for (int _i = 0; _i < 2; ++_i) \
;         __builtin_amdgcn_global_load_lds((const unsigned*)((const char*)(gbase) + (voff)[_i]), (PG8_LAS unsigned*)(lds + (bufoff) + ldsw + _i * 8192), 16, 0, 0); } while (0)
; #define PG8_LDA(dst, b, h) do { _Pragma("unroll") for (int m = 0; m < 4; ++m) _Pragma("unroll") for (int k = 0; k < 2; ++k) dst[m][k] = *(const PG8_LAS bf16x8*)(lds + PG8_SA(b, h) + aoff + m * 2048 + k * 1024); } while (0)
; #define PG8_LDB(dst, b, h) do { _Pragma("unroll") for (int n = 0; n < 2; ++n) _Pragma("unroll") for (int k = 0; k < 2; ++k) dst[n][k] = *(const PG8_LAS bf16x8*)(lds + PG8_SB(b, h) + boff + n * 2048 + k * 1024); } while (0)
; #define PG8_MMA(ai, bj, At, Bt) do { __builtin_amdgcn_s_setprio(1); _Pragma("unroll") for (int m = 0; m < 4; ++m) _Pragma("unroll") for (int n = 0; n < 2; ++n) _Pragma("unroll") for (int k = 0; k < 2; ++k) \
;         acc[ai][bj][m][n] = __builtin_amdgcn_mfma_f32_16x16x32_bf16(Bt[n][k], At[m][k], acc[ai][bj][m][n], 0, 0, 0); __builtin_amdgcn_s_setprio(0); } while (0)
; #define PG8_WAIT_V(n) asm volatile("s_waitcnt vmcnt(" #n ")" ::: "memory")
; #define PG8_BAR __builtin_amdgcn_s_barrier()
; template <class Epi, class Sched, bool ALIGN_EPI = false, bool SP2 = false>
; __device__ __forceinline__ void gemm_phase(PG8_LAS unsigned char* lds, const Gemm g, const Sched& S, const Epi& E) {
;     ...
;         for (int t = 0; t < nt; t += 2) {
;             const bool last = (t == nt - 2);
;             const char* a1 = cA + (size_t)(t + 1) * kstep;
;             const char* a2 = last ? nA : cA + (size_t)(t + 2) * kstep; const char* b2 = last ? nB : cB + (size_t)(t + 2) * kstep;
;             const char* a3 = a2 + kstep; const char* b3 = b2 + kstep;
;             if (last && has_next) S.a_ready(nxt);
;             if constexpr (SP2) {
;             PG8_LDB(B0, 0, 0); PG8_LDB(B1, 0, 1); PG8_SCHED; PG8_LDA(At, 0, 0); PG8_STAGE(PG8_SA(1, 1), a1 + hstep, voffA);
;             PG8_WAIT_V(8); PG8_WAIT_L(0); PG8_BAR; PG8_MMA(0, 0, At, B0); PG8_MMA(0, 1, At, B1); PG8_BAR; PG8_SCHED;
;             PG8_LDA(At, 0, 1); PG8_STAGE(PG8_SB(0, 0), b2, voffB); PG8_STAGE(PG8_SB(0, 1), b2 + hstep, voffB); PG8_STAGE(PG8_SA(0, 0), a2, voffA);
;             PG8_WAIT_V(8); PG8_WAIT_L(0); PG8_BAR; PG8_MMA(1, 0, At, B0); PG8_MMA(1, 1, At, B1); PG8_BAR; PG8_SCHED;
.LBB0_323:
	ds_read_b128 v[148:151], v156
	ds_read_b128 v[166:169], v156 offset:1024
	ds_read_b128 v[172:175], v156 offset:2048
	ds_read_b128 v[176:179], v156 offset:3072
	ds_read_b128 v[180:183], v157
	ds_read_b128 v[184:187], v157 offset:1024
	ds_read_b128 v[188:191], v157 offset:2048
	ds_read_b128 v[196:199], v157 offset:3072
	s_add_u32 s56, s54, 0x100
	s_addc_u32 s57, s55, 0
	s_cmp_eq_u32 s69, 40
	s_cselect_b32 s61, s51, s57
	s_cselect_b32 s60, s50, s56
	s_cselect_b32 s59, s53, s33
	s_cselect_b32 s58, s52, s4
	s_add_i32 m0, s37, 0xc000
	ds_read_b128 v[200:203], v158
	ds_read_b128 v[204:207], v158 offset:1024
	ds_read_b128 v[208:211], v158 offset:2048
	ds_read_b128 v[212:215], v158 offset:3072
	ds_read_b128 v[216:219], v158 offset:4096
	ds_read_b128 v[220:223], v158 offset:5120
	ds_read_b128 v[224:227], v158 offset:6144
	ds_read_b128 v[228:231], v158 offset:7168
	global_load_lds_dwordx4 v140, s[54:55]
	s_add_i32 m0, s37, 0xe000
	s_nop 0
	global_load_lds_dwordx4 v142, s[54:55]
	s_waitcnt vmcnt(8)
	s_waitcnt lgkmcnt(0)
	s_barrier
	s_waitcnt lgkmcnt(0)
	v_mfma_f32_16x16x32_bf16 v[124:127], v[148:151], v[200:203], v[124:127]
	v_mfma_f32_16x16x32_bf16 v[120:123], v[172:175], v[200:203], v[120:123]
	v_mfma_f32_16x16x32_bf16 v[108:111], v[148:151], v[208:211], v[108:111]
	v_mfma_f32_16x16x32_bf16 v[104:107], v[172:175], v[208:211], v[104:107]
	v_mfma_f32_16x16x32_bf16 v[92:95], v[148:151], v[216:219], v[92:95]
	v_mfma_f32_16x16x32_bf16 v[88:91], v[172:175], v[216:219], v[88:91]
	v_mfma_f32_16x16x32_bf16 v[76:79], v[148:151], v[224:227], v[76:79]
	v_mfma_f32_16x16x32_bf16 v[72:75], v[172:175], v[224:227], v[72:75]
	v_mfma_f32_16x16x32_bf16 v[124:127], v[166:169], v[204:207], v[124:127]
	v_mfma_f32_16x16x32_bf16 v[120:123], v[176:179], v[204:207], v[120:123]
	v_mfma_f32_16x16x32_bf16 v[108:111], v[166:169], v[212:215], v[108:111]
	v_mfma_f32_16x16x32_bf16 v[104:107], v[176:179], v[212:215], v[104:107]
	v_mfma_f32_16x16x32_bf16 v[92:95], v[166:169], v[220:223], v[92:95]
	v_mfma_f32_16x16x32_bf16 v[88:91], v[176:179], v[220:223], v[88:91]
	v_mfma_f32_16x16x32_bf16 v[76:79], v[166:169], v[228:231], v[76:79]
	v_mfma_f32_16x16x32_bf16 v[72:75], v[176:179], v[228:231], v[72:75]
	v_mfma_f32_16x16x32_bf16 v[116:119], v[180:183], v[200:203], v[116:119]
	v_mfma_f32_16x16x32_bf16 v[112:115], v[188:191], v[200:203], v[112:115]
	v_mfma_f32_16x16x32_bf16 v[100:103], v[180:183], v[208:211], v[100:103]
	v_mfma_f32_16x16x32_bf16 v[96:99], v[188:191], v[208:211], v[96:99]
	v_mfma_f32_16x16x32_bf16 v[84:87], v[180:183], v[216:219], v[84:87]
	v_mfma_f32_16x16x32_bf16 v[80:83], v[188:191], v[216:219], v[80:83]
	v_mfma_f32_16x16x32_bf16 v[68:71], v[180:183], v[224:227], v[68:71]
	v_mfma_f32_16x16x32_bf16 v[64:67], v[188:191], v[224:227], v[64:67]
	v_mfma_f32_16x16x32_bf16 v[116:119], v[184:187], v[204:207], v[116:119]
	v_mfma_f32_16x16x32_bf16 v[112:115], v[196:199], v[204:207], v[112:115]
	v_mfma_f32_16x16x32_bf16 v[100:103], v[184:187], v[212:215], v[100:103]
	v_mfma_f32_16x16x32_bf16 v[96:99], v[196:199], v[212:215], v[96:99]
	v_mfma_f32_16x16x32_bf16 v[84:87], v[184:187], v[220:223], v[84:87]
	v_mfma_f32_16x16x32_bf16 v[80:83], v[196:199], v[220:223], v[80:83]
	v_mfma_f32_16x16x32_bf16 v[68:71], v[184:187], v[228:231], v[68:71]
	v_mfma_f32_16x16x32_bf16 v[64:67], v[196:199], v[228:231], v[64:67]
	s_barrier
	s_add_i32 s6, s74, s36
	v_lshl_add_u64 v[152:153], s[58:59], 0, v[134:135]
	s_mov_b32 m0, s6
	ds_read_b128 v[200:203], v158 offset:16384
	ds_read_b128 v[204:207], v158 offset:17408
	ds_read_b128 v[208:211], v158 offset:18432
	ds_read_b128 v[212:215], v158 offset:19456
	ds_read_b128 v[216:219], v158 offset:20480
	ds_read_b128 v[220:223], v158 offset:21504
	ds_read_b128 v[224:227], v158 offset:22528
	ds_read_b128 v[228:231], v158 offset:23552
	global_load_lds_dwordx4 v[152:153], off
	s_add_i32 m0, s6, 0x2000
	s_add_u32 s54, s58, 0xb0000
	v_lshl_add_u64 v[162:163], s[58:59], 0, v[138:139]
	s_addc_u32 s55, s59, 0
	s_add_i32 s6, s75, s36
	global_load_lds_dwordx4 v[162:163], off
	s_mov_b32 m0, s6
	v_lshl_add_u64 v[234:235], s[60:61], 0, v[136:137]
	global_load_lds_dwordx4 v134, s[54:55]
	s_add_i32 m0, s6, 0x2000
	s_nop 0
	global_load_lds_dwordx4 v138, s[54:55]
	v_lshl_add_u64 v[232:233], s[60:61], 0, v[132:133]
	s_mov_b32 m0, s37
	s_nop 0
	global_load_lds_dwordx4 v[232:233], off
	s_mov_b32 m0, s30
	s_nop 0
	global_load_lds_dwordx4 v[234:235], off
	s_waitcnt vmcnt(8)
	s_waitcnt lgkmcnt(0)
	s_barrier
	s_waitcnt lgkmcnt(0)
	v_mfma_f32_16x16x32_bf16 v[60:63], v[148:151], v[200:203], v[60:63]
	v_mfma_f32_16x16x32_bf16 v[56:59], v[172:175], v[200:203], v[56:59]
	v_mfma_f32_16x16x32_bf16 v[44:47], v[148:151], v[208:211], v[44:47]
	v_mfma_f32_16x16x32_bf16 v[40:43], v[172:175], v[208:211], v[40:43]
	v_mfma_f32_16x16x32_bf16 v[28:31], v[148:151], v[216:219], v[28:31]
	v_mfma_f32_16x16x32_bf16 v[24:27], v[172:175], v[216:219], v[24:27]
	v_mfma_f32_16x16x32_bf16 v[12:15], v[148:151], v[224:227], v[12:15]
	v_mfma_f32_16x16x32_bf16 v[8:11], v[172:175], v[224:227], v[8:11]
	v_mfma_f32_16x16x32_bf16 v[60:63], v[166:169], v[204:207], v[60:63]
	v_mfma_f32_16x16x32_bf16 v[56:59], v[176:179], v[204:207], v[56:59]
	v_mfma_f32_16x16x32_bf16 v[44:47], v[166:169], v[212:215], v[44:47]
	v_mfma_f32_16x16x32_bf16 v[40:43], v[176:179], v[212:215], v[40:43]
	v_mfma_f32_16x16x32_bf16 v[28:31], v[166:169], v[220:223], v[28:31]
	v_mfma_f32_16x16x32_bf16 v[24:27], v[176:179], v[220:223], v[24:27]
	v_mfma_f32_16x16x32_bf16 v[12:15], v[166:169], v[228:231], v[12:15]
	v_mfma_f32_16x16x32_bf16 v[8:11], v[176:179], v[228:231], v[8:11]
	v_mfma_f32_16x16x32_bf16 v[52:55], v[180:183], v[200:203], v[52:55]
	v_mfma_f32_16x16x32_bf16 v[48:51], v[188:191], v[200:203], v[48:51]
	v_mfma_f32_16x16x32_bf16 v[36:39], v[180:183], v[208:211], v[36:39]
	v_mfma_f32_16x16x32_bf16 v[32:35], v[188:191], v[208:211], v[32:35]
	v_mfma_f32_16x16x32_bf16 v[20:23], v[180:183], v[216:219], v[20:23]
	v_mfma_f32_16x16x32_bf16 v[16:19], v[188:191], v[216:219], v[16:19]
	v_mfma_f32_16x16x32_bf16 v[4:7], v[180:183], v[224:227], v[4:7]
	v_mfma_f32_16x16x32_bf16 v[0:3], v[188:191], v[224:227], v[0:3]
	v_mfma_f32_16x16x32_bf16 v[52:55], v[184:187], v[204:207], v[52:55]
	v_mfma_f32_16x16x32_bf16 v[48:51], v[196:199], v[204:207], v[48:51]
	v_mfma_f32_16x16x32_bf16 v[36:39], v[184:187], v[212:215], v[36:39]
	v_mfma_f32_16x16x32_bf16 v[32:35], v[196:199], v[212:215], v[32:35]
	v_mfma_f32_16x16x32_bf16 v[20:23], v[184:187], v[220:223], v[20:23]
	v_mfma_f32_16x16x32_bf16 v[16:19], v[196:199], v[220:223], v[16:19]
	v_mfma_f32_16x16x32_bf16 v[4:7], v[184:187], v[228:231], v[4:7]
	v_mfma_f32_16x16x32_bf16 v[0:3], v[196:199], v[228:231], v[0:3]
	s_barrier
; #define PG8_STAGE(bufoff, gbase, voff) do { _Pragma("unroll") for (int _i = 0; _i < 2; ++_i) \
;         __builtin_amdgcn_global_load_lds((const unsigned*)((const char*)(gbase) + (voff)[_i]), (PG8_LAS unsigned*)(lds + (bufoff) + ldsw + _i * 8192), 16, 0, 0); } while (0)
; #define PG8_LDA(dst, b, h) do { _Pragma("unroll") for (int m = 0; m < 4; ++m) _Pragma("unroll") for (int k = 0; k < 2; ++k) dst[m][k] = *(const PG8_LAS bf16x8*)(lds + PG8_SA(b, h) + aoff + m * 2048 + k * 1024); } while (0)
; #define PG8_LDB(dst, b, h) do { _Pragma("unroll") for (int n = 0; n < 2; ++n) _Pragma("unroll") for (int k = 0; k < 2; ++k) dst[n][k] = *(const PG8_LAS bf16x8*)(lds + PG8_SB(b, h) + boff + n * 2048 + k * 1024); } while (0)
; #define PG8_MMA(ai, bj, At, Bt) do { __builtin_amdgcn_s_setprio(1); _Pragma("unroll") for (int m = 0; m < 4; ++m) _Pragma("unroll") for (int n = 0; n < 2; ++n) _Pragma("unroll") for (int k = 0; k < 2; ++k) \
;         acc[ai][bj][m][n] = __builtin_amdgcn_mfma_f32_16x16x32_bf16(Bt[n][k], At[m][k], acc[ai][bj][m][n], 0, 0, 0); __builtin_amdgcn_s_setprio(0); } while (0)
; #define PG8_WAIT_V(n) asm volatile("s_waitcnt vmcnt(" #n ")" ::: "memory")
; #define PG8_WAIT_L(n) asm volatile("s_waitcnt lgkmcnt(" #n ")" ::: "memory")
; #define PG8_BAR __builtin_amdgcn_s_barrier()
; #define PG8_SCHED __builtin_amdgcn_sched_barrier(0)
; template <class Epi, class Sched, bool ALIGN_EPI = false, bool SP2 = false>
; __device__ __forceinline__ void gemm_phase(PG8_LAS unsigned char* lds, const Gemm g, const Sched& S, const Epi& E) {
;     ...
;             PG8_LDB(B0, 1, 0); PG8_LDB(B1, 1, 1); PG8_SCHED; PG8_LDA(At, 1, 0); PG8_STAGE(PG8_SA(0, 1), a2 + hstep, voffA);
;             PG8_WAIT_V(8); PG8_WAIT_L(0); PG8_BAR; PG8_MMA(0, 0, At, B0); PG8_MMA(0, 1, At, B1); PG8_BAR; PG8_SCHED;
;             PG8_LDA(At, 1, 1); PG8_STAGE(PG8_SB(1, 0), b3, voffB); PG8_STAGE(PG8_SB(1, 1), b3 + hstep, voffB); PG8_STAGE(PG8_SA(1, 0), a3, voffA);
;             PG8_WAIT_V(8); PG8_WAIT_L(0); PG8_BAR; PG8_MMA(1, 0, At, B0); PG8_MMA(1, 1, At, B1); PG8_BAR; PG8_SCHED;
	s_add_i32 s6, 0, 0x18000
	v_add_u32_e32 v161, s6, v154
	s_add_i32 s7, 0, 0x1c000
	ds_read_b128 v[148:151], v161
	ds_read_b128 v[166:169], v161 offset:1024
	ds_read_b128 v[172:175], v161 offset:2048
	ds_read_b128 v[176:179], v161 offset:3072
	v_add_u32_e32 v161, s7, v154
	ds_read_b128 v[180:183], v161
	ds_read_b128 v[184:187], v161 offset:1024
	ds_read_b128 v[188:191], v161 offset:2048
	ds_read_b128 v[196:199], v161 offset:3072
	s_add_u32 s54, s60, 0xb0000
	s_addc_u32 s55, s61, 0
	s_mov_b32 m0, s31
	ds_read_b128 v[200:203], v158 offset:32768
	ds_read_b128 v[204:207], v158 offset:33792
	ds_read_b128 v[208:211], v158 offset:34816
	ds_read_b128 v[212:215], v158 offset:35840
	ds_read_b128 v[216:219], v158 offset:36864
	ds_read_b128 v[220:223], v158 offset:37888
	ds_read_b128 v[224:227], v158 offset:38912
	ds_read_b128 v[228:231], v158 offset:39936
	global_load_lds_dwordx4 v132, s[54:55]
	s_mov_b32 m0, s76
	s_nop 0
	global_load_lds_dwordx4 v136, s[54:55]
	s_waitcnt vmcnt(8)
	s_waitcnt lgkmcnt(0)
	s_barrier
	s_waitcnt lgkmcnt(0)
	v_mfma_f32_16x16x32_bf16 v[124:127], v[148:151], v[200:203], v[124:127]
	v_mfma_f32_16x16x32_bf16 v[120:123], v[172:175], v[200:203], v[120:123]
	v_mfma_f32_16x16x32_bf16 v[108:111], v[148:151], v[208:211], v[108:111]
	v_mfma_f32_16x16x32_bf16 v[104:107], v[172:175], v[208:211], v[104:107]
	v_mfma_f32_16x16x32_bf16 v[92:95], v[148:151], v[216:219], v[92:95]
	v_mfma_f32_16x16x32_bf16 v[88:91], v[172:175], v[216:219], v[88:91]
	v_mfma_f32_16x16x32_bf16 v[76:79], v[148:151], v[224:227], v[76:79]
	v_mfma_f32_16x16x32_bf16 v[72:75], v[172:175], v[224:227], v[72:75]
	v_mfma_f32_16x16x32_bf16 v[124:127], v[166:169], v[204:207], v[124:127]
	v_mfma_f32_16x16x32_bf16 v[120:123], v[176:179], v[204:207], v[120:123]
	v_mfma_f32_16x16x32_bf16 v[108:111], v[166:169], v[212:215], v[108:111]
	v_mfma_f32_16x16x32_bf16 v[104:107], v[176:179], v[212:215], v[104:107]
	v_mfma_f32_16x16x32_bf16 v[92:95], v[166:169], v[220:223], v[92:95]
	v_mfma_f32_16x16x32_bf16 v[88:91], v[176:179], v[220:223], v[88:91]
	v_mfma_f32_16x16x32_bf16 v[76:79], v[166:169], v[228:231], v[76:79]
	v_mfma_f32_16x16x32_bf16 v[72:75], v[176:179], v[228:231], v[72:75]
	v_mfma_f32_16x16x32_bf16 v[116:119], v[180:183], v[200:203], v[116:119]
	v_mfma_f32_16x16x32_bf16 v[112:115], v[188:191], v[200:203], v[112:115]
	v_mfma_f32_16x16x32_bf16 v[100:103], v[180:183], v[208:211], v[100:103]
	v_mfma_f32_16x16x32_bf16 v[96:99], v[188:191], v[208:211], v[96:99]
	v_mfma_f32_16x16x32_bf16 v[84:87], v[180:183], v[216:219], v[84:87]
	v_mfma_f32_16x16x32_bf16 v[80:83], v[188:191], v[216:219], v[80:83]
	v_mfma_f32_16x16x32_bf16 v[68:71], v[180:183], v[224:227], v[68:71]
	v_mfma_f32_16x16x32_bf16 v[64:67], v[188:191], v[224:227], v[64:67]
	v_mfma_f32_16x16x32_bf16 v[116:119], v[184:187], v[204:207], v[116:119]
	v_mfma_f32_16x16x32_bf16 v[112:115], v[196:199], v[204:207], v[112:115]
	v_mfma_f32_16x16x32_bf16 v[100:103], v[184:187], v[212:215], v[100:103]
	v_mfma_f32_16x16x32_bf16 v[96:99], v[196:199], v[212:215], v[96:99]
	v_mfma_f32_16x16x32_bf16 v[84:87], v[184:187], v[220:223], v[84:87]
	v_mfma_f32_16x16x32_bf16 v[80:83], v[196:199], v[220:223], v[80:83]
	v_mfma_f32_16x16x32_bf16 v[68:71], v[184:187], v[228:231], v[68:71]
	v_mfma_f32_16x16x32_bf16 v[64:67], v[196:199], v[228:231], v[64:67]
	s_barrier
	s_add_i32 s6, s6, s36
	v_lshl_add_u64 v[152:153], v[152:153], 0, s[38:39]
	s_mov_b32 m0, s6
	ds_read_b128 v[200:203], v158 offset:49152
	ds_read_b128 v[204:207], v158 offset:50176
	ds_read_b128 v[208:211], v158 offset:51200
	ds_read_b128 v[212:215], v158 offset:52224
	ds_read_b128 v[216:219], v158 offset:53248
	ds_read_b128 v[220:223], v158 offset:54272
	ds_read_b128 v[224:227], v158 offset:55296
	ds_read_b128 v[228:231], v158 offset:56320
	global_load_lds_dwordx4 v[152:153], off
	s_add_i32 m0, s6, 0x2000
	s_add_u32 s54, s58, 0xb0080
	v_lshl_add_u64 v[152:153], v[162:163], 0, s[38:39]
	s_addc_u32 s55, s59, 0
	s_add_i32 s6, s7, s36
	global_load_lds_dwordx4 v[152:153], off
	s_mov_b32 m0, s6
	s_nop 0
	global_load_lds_dwordx4 v134, s[54:55]
	s_add_i32 m0, s6, 0x2000
	s_nop 0
	global_load_lds_dwordx4 v138, s[54:55]
	v_lshl_add_u64 v[152:153], v[232:233], 0, s[38:39]
	s_mov_b32 m0, s78
	s_nop 0
	global_load_lds_dwordx4 v[152:153], off
	v_lshl_add_u64 v[152:153], v[234:235], 0, s[38:39]
	s_mov_b32 m0, s79
	s_nop 0
	global_load_lds_dwordx4 v[152:153], off
	s_waitcnt vmcnt(8)
	s_waitcnt lgkmcnt(0)
	s_barrier
	s_waitcnt lgkmcnt(0)
	v_mfma_f32_16x16x32_bf16 v[60:63], v[148:151], v[200:203], v[60:63]
	v_mfma_f32_16x16x32_bf16 v[56:59], v[172:175], v[200:203], v[56:59]
	v_mfma_f32_16x16x32_bf16 v[44:47], v[148:151], v[208:211], v[44:47]
	v_mfma_f32_16x16x32_bf16 v[40:43], v[172:175], v[208:211], v[40:43]
	v_mfma_f32_16x16x32_bf16 v[28:31], v[148:151], v[216:219], v[28:31]
	v_mfma_f32_16x16x32_bf16 v[24:27], v[172:175], v[216:219], v[24:27]
	v_mfma_f32_16x16x32_bf16 v[12:15], v[148:151], v[224:227], v[12:15]
	v_mfma_f32_16x16x32_bf16 v[8:11], v[172:175], v[224:227], v[8:11]
	v_mfma_f32_16x16x32_bf16 v[60:63], v[166:169], v[204:207], v[60:63]
	v_mfma_f32_16x16x32_bf16 v[56:59], v[176:179], v[204:207], v[56:59]
	v_mfma_f32_16x16x32_bf16 v[44:47], v[166:169], v[212:215], v[44:47]
	v_mfma_f32_16x16x32_bf16 v[40:43], v[176:179], v[212:215], v[40:43]
	v_mfma_f32_16x16x32_bf16 v[28:31], v[166:169], v[220:223], v[28:31]
	v_mfma_f32_16x16x32_bf16 v[24:27], v[176:179], v[220:223], v[24:27]
	v_mfma_f32_16x16x32_bf16 v[12:15], v[166:169], v[228:231], v[12:15]
	v_mfma_f32_16x16x32_bf16 v[8:11], v[176:179], v[228:231], v[8:11]
	v_mfma_f32_16x16x32_bf16 v[52:55], v[180:183], v[200:203], v[52:55]
	v_mfma_f32_16x16x32_bf16 v[48:51], v[188:191], v[200:203], v[48:51]
	v_mfma_f32_16x16x32_bf16 v[36:39], v[180:183], v[208:211], v[36:39]
	v_mfma_f32_16x16x32_bf16 v[32:35], v[188:191], v[208:211], v[32:35]
	v_mfma_f32_16x16x32_bf16 v[20:23], v[180:183], v[216:219], v[20:23]
	v_mfma_f32_16x16x32_bf16 v[16:19], v[188:191], v[216:219], v[16:19]
	v_mfma_f32_16x16x32_bf16 v[4:7], v[180:183], v[224:227], v[4:7]
	v_mfma_f32_16x16x32_bf16 v[0:3], v[188:191], v[224:227], v[0:3]
	v_mfma_f32_16x16x32_bf16 v[52:55], v[184:187], v[204:207], v[52:55]
	v_mfma_f32_16x16x32_bf16 v[48:51], v[196:199], v[204:207], v[48:51]
	v_mfma_f32_16x16x32_bf16 v[36:39], v[184:187], v[212:215], v[36:39]
	v_mfma_f32_16x16x32_bf16 v[32:35], v[196:199], v[212:215], v[32:35]
	v_mfma_f32_16x16x32_bf16 v[20:23], v[184:187], v[220:223], v[20:23]
	v_mfma_f32_16x16x32_bf16 v[16:19], v[196:199], v[220:223], v[16:19]
	v_mfma_f32_16x16x32_bf16 v[4:7], v[184:187], v[228:231], v[4:7]
	v_mfma_f32_16x16x32_bf16 v[0:3], v[196:199], v[228:231], v[0:3]
	s_barrier
	s_add_i32 s69, s69, 2
	s_add_u32 s4, s4, 0x100
	s_addc_u32 s33, s33, 0
	s_cmp_gt_u32 s69, 41
	s_mov_b64 s[54:55], s[56:57]
	s_cbranch_scc0 .LBB0_323
	s_and_b64 vcc, exec, s[40:41]
	s_cbranch_vccz .LBB0_326
	s_barrier

; #define PG8_STAGE(bufoff, gbase, voff) do { _Pragma("unroll") for (int _i = 0; _i < 2; ++_i) \
;         __builtin_amdgcn_global_load_lds((const unsigned*)((const char*)(gbase) + (voff)[_i]), (PG8_LAS unsigned*)(lds + (bufoff) + ldsw + _i * 8192), 16, 0, 0); } while (0)
; #define PG8_LDA(dst, b, h) do { _Pragma("unroll") for (int m = 0; m < 4; ++m) _Pragma("unroll") for (int k = 0; k < 2; ++k) dst[m][k] = *(const PG8_LAS bf16x8*)(lds + PG8_SA(b, h) + aoff + m * 2048 + k * 1024); } while (0)
; #define PG8_LDB(dst, b, h) do { _Pragma("unroll") for (int n = 0; n < 2; ++n) _Pragma("unroll") for (int k = 0; k < 2; ++k) dst[n][k] = *(const PG8_LAS bf16x8*)(lds + PG8_SB(b, h) + boff + n * 2048 + k * 1024); } while (0)
; #define PG8_MMA(ai, bj, At, Bt) do { __builtin_amdgcn_s_setprio(1); _Pragma("unroll") for (int m = 0; m < 4; ++m) _Pragma("unroll") for (int n = 0; n < 2; ++n) _Pragma("unroll") for (int k = 0; k < 2; ++k) \
;         acc[ai][bj][m][n] = __builtin_amdgcn_mfma_f32_16x16x32_bf16(Bt[n][k], At[m][k], acc[ai][bj][m][n], 0, 0, 0); __builtin_amdgcn_s_setprio(0); } while (0)
; #define PG8_WAIT_V(n) asm volatile("s_waitcnt vmcnt(" #n ")" ::: "memory")
; #define PG8_BAR __builtin_amdgcn_s_barrier()
; template <class Epi, class Sched, bool ALIGN_EPI = false, bool SP2 = false>
; __device__ __forceinline__ void gemm_phase(PG8_LAS unsigned char* lds, const Gemm g, const Sched& S, const Epi& E) {
;     ...
;         for (int t = 0; t < nt; t += 2) {
;             const bool last = (t == nt - 2);
;             const char* a1 = cA + (size_t)(t + 1) * kstep;
;             const char* a2 = last ? nA : cA + (size_t)(t + 2) * kstep; const char* b2 = last ? nB : cB + (size_t)(t + 2) * kstep;
;             const char* a3 = a2 + kstep; const char* b3 = b2 + kstep;
;             if (last && has_next) S.a_ready(nxt);
;             if constexpr (SP2) {
;             PG8_LDB(B0, 0, 0); PG8_LDB(B1, 0, 1); PG8_SCHED; PG8_LDA(At, 0, 0); PG8_STAGE(PG8_SA(1, 1), a1 + hstep, voffA);
;             PG8_WAIT_V(8); PG8_WAIT_L(0); PG8_BAR; PG8_MMA(0, 0, At, B0); PG8_MMA(0, 1, At, B1); PG8_BAR; PG8_SCHED;
;             PG8_LDA(At, 0, 1); PG8_STAGE(PG8_SB(0, 0), b2, voffB); PG8_STAGE(PG8_SB(0, 1), b2 + hstep, voffB); PG8_STAGE(PG8_SA(0, 0), a2, voffA);
;             PG8_WAIT_V(8); PG8_WAIT_L(0); PG8_BAR; PG8_MMA(1, 0, At, B0); PG8_MMA(1, 1, At, B1); PG8_BAR; PG8_SCHED;
.LBB0_463:
	ds_read_b128 v[152:155], v172
	ds_read_b128 v[156:159], v172 offset:1024
	ds_read_b128 v[166:169], v172 offset:2048
	ds_read_b128 v[176:179], v172 offset:3072
	ds_read_b128 v[180:183], v173
	ds_read_b128 v[184:187], v173 offset:1024
	ds_read_b128 v[188:191], v173 offset:2048
	ds_read_b128 v[196:199], v173 offset:3072
	s_add_u32 s6, s60, 0xfffc0080
	s_addc_u32 s7, s61, -1
	s_cmp_eq_u32 s72, 12
	s_cselect_b32 s81, s49, s7
	s_cselect_b32 s80, s55, s6
	s_cselect_b32 s79, s53, s33
	s_cselect_b32 s78, vcc_lo, vcc_hi
	s_add_i32 m0, s31, 0xc000
	ds_read_b128 v[200:203], v174
	ds_read_b128 v[204:207], v174 offset:1024
	ds_read_b128 v[208:211], v174 offset:2048
	ds_read_b128 v[212:215], v174 offset:3072
	ds_read_b128 v[216:219], v174 offset:4096
	ds_read_b128 v[220:223], v174 offset:5120
	ds_read_b128 v[224:227], v174 offset:6144
	ds_read_b128 v[228:231], v174 offset:7168
	global_load_lds_dwordx4 v144, s[60:61]
	s_add_i32 m0, s31, 0xe000
	s_nop 0
	global_load_lds_dwordx4 v146, s[60:61]
	s_waitcnt vmcnt(8)
	s_waitcnt lgkmcnt(0)
	s_barrier
	s_waitcnt lgkmcnt(0)
	v_mfma_f32_16x16x32_bf16 v[124:127], v[152:155], v[200:203], v[124:127]
	v_mfma_f32_16x16x32_bf16 v[120:123], v[166:169], v[200:203], v[120:123]
	v_mfma_f32_16x16x32_bf16 v[108:111], v[152:155], v[208:211], v[108:111]
	v_mfma_f32_16x16x32_bf16 v[104:107], v[166:169], v[208:211], v[104:107]
	v_mfma_f32_16x16x32_bf16 v[92:95], v[152:155], v[216:219], v[92:95]
	v_mfma_f32_16x16x32_bf16 v[88:91], v[166:169], v[216:219], v[88:91]
	v_mfma_f32_16x16x32_bf16 v[76:79], v[152:155], v[224:227], v[76:79]
	v_mfma_f32_16x16x32_bf16 v[72:75], v[166:169], v[224:227], v[72:75]
	v_mfma_f32_16x16x32_bf16 v[124:127], v[156:159], v[204:207], v[124:127]
	v_mfma_f32_16x16x32_bf16 v[120:123], v[176:179], v[204:207], v[120:123]
	v_mfma_f32_16x16x32_bf16 v[108:111], v[156:159], v[212:215], v[108:111]
	v_mfma_f32_16x16x32_bf16 v[104:107], v[176:179], v[212:215], v[104:107]
	v_mfma_f32_16x16x32_bf16 v[92:95], v[156:159], v[220:223], v[92:95]
	v_mfma_f32_16x16x32_bf16 v[88:91], v[176:179], v[220:223], v[88:91]
	v_mfma_f32_16x16x32_bf16 v[76:79], v[156:159], v[228:231], v[76:79]
	v_mfma_f32_16x16x32_bf16 v[72:75], v[176:179], v[228:231], v[72:75]
	v_mfma_f32_16x16x32_bf16 v[116:119], v[180:183], v[200:203], v[116:119]
	v_mfma_f32_16x16x32_bf16 v[112:115], v[188:191], v[200:203], v[112:115]
	v_mfma_f32_16x16x32_bf16 v[100:103], v[180:183], v[208:211], v[100:103]
	v_mfma_f32_16x16x32_bf16 v[96:99], v[188:191], v[208:211], v[96:99]
	v_mfma_f32_16x16x32_bf16 v[84:87], v[180:183], v[216:219], v[84:87]
	v_mfma_f32_16x16x32_bf16 v[80:83], v[188:191], v[216:219], v[80:83]
	v_mfma_f32_16x16x32_bf16 v[68:71], v[180:183], v[224:227], v[68:71]
	v_mfma_f32_16x16x32_bf16 v[64:67], v[188:191], v[224:227], v[64:67]
	v_mfma_f32_16x16x32_bf16 v[116:119], v[184:187], v[204:207], v[116:119]
	v_mfma_f32_16x16x32_bf16 v[112:115], v[196:199], v[204:207], v[112:115]
	v_mfma_f32_16x16x32_bf16 v[100:103], v[184:187], v[212:215], v[100:103]
	v_mfma_f32_16x16x32_bf16 v[96:99], v[196:199], v[212:215], v[96:99]
	v_mfma_f32_16x16x32_bf16 v[84:87], v[184:187], v[220:223], v[84:87]
	v_mfma_f32_16x16x32_bf16 v[80:83], v[196:199], v[220:223], v[80:83]
	v_mfma_f32_16x16x32_bf16 v[68:71], v[184:187], v[228:231], v[68:71]
	v_mfma_f32_16x16x32_bf16 v[64:67], v[196:199], v[228:231], v[64:67]
	s_barrier
	s_add_i32 s6, s69, s30
	v_lshl_add_u64 v[232:233], s[78:79], 0, v[134:135]
	s_mov_b32 m0, s6
	ds_read_b128 v[200:203], v174 offset:16384
	ds_read_b128 v[204:207], v174 offset:17408
	ds_read_b128 v[208:211], v174 offset:18432
	ds_read_b128 v[212:215], v174 offset:19456
	ds_read_b128 v[216:219], v174 offset:20480
	ds_read_b128 v[220:223], v174 offset:21504
	ds_read_b128 v[224:227], v174 offset:22528
	ds_read_b128 v[228:231], v174 offset:23552
	global_load_lds_dwordx4 v[232:233], off
	s_add_i32 m0, s6, 0x2000
	s_add_u32 s6, s78, 0x40000
	v_lshl_add_u64 v[234:235], s[78:79], 0, v[138:139]
	s_addc_u32 s7, s79, 0
	s_add_i32 s73, s74, s30
	global_load_lds_dwordx4 v[234:235], off
	s_mov_b32 m0, s73
	v_lshl_add_u64 v[238:239], s[80:81], 0, v[136:137]
	global_load_lds_dwordx4 v134, s[6:7]
	s_add_i32 m0, s73, 0x2000
	s_nop 0
	global_load_lds_dwordx4 v138, s[6:7]
	v_lshl_add_u64 v[236:237], s[80:81], 0, v[132:133]
	s_mov_b32 m0, s31
	s_nop 0
	global_load_lds_dwordx4 v[236:237], off
	s_mov_b32 m0, s36
	s_nop 0
	global_load_lds_dwordx4 v[238:239], off
	s_waitcnt vmcnt(8)
	s_waitcnt lgkmcnt(0)
	s_barrier
	s_waitcnt lgkmcnt(0)
	v_mfma_f32_16x16x32_bf16 v[60:63], v[152:155], v[200:203], v[60:63]
	v_mfma_f32_16x16x32_bf16 v[56:59], v[166:169], v[200:203], v[56:59]
	v_mfma_f32_16x16x32_bf16 v[44:47], v[152:155], v[208:211], v[44:47]
	v_mfma_f32_16x16x32_bf16 v[40:43], v[166:169], v[208:211], v[40:43]
	v_mfma_f32_16x16x32_bf16 v[28:31], v[152:155], v[216:219], v[28:31]
	v_mfma_f32_16x16x32_bf16 v[24:27], v[166:169], v[216:219], v[24:27]
	v_mfma_f32_16x16x32_bf16 v[12:15], v[152:155], v[224:227], v[12:15]
	v_mfma_f32_16x16x32_bf16 v[8:11], v[166:169], v[224:227], v[8:11]
	v_mfma_f32_16x16x32_bf16 v[60:63], v[156:159], v[204:207], v[60:63]
	v_mfma_f32_16x16x32_bf16 v[56:59], v[176:179], v[204:207], v[56:59]
	v_mfma_f32_16x16x32_bf16 v[44:47], v[156:159], v[212:215], v[44:47]
	v_mfma_f32_16x16x32_bf16 v[40:43], v[176:179], v[212:215], v[40:43]
	v_mfma_f32_16x16x32_bf16 v[28:31], v[156:159], v[220:223], v[28:31]
	v_mfma_f32_16x16x32_bf16 v[24:27], v[176:179], v[220:223], v[24:27]
	v_mfma_f32_16x16x32_bf16 v[12:15], v[156:159], v[228:231], v[12:15]
	v_mfma_f32_16x16x32_bf16 v[8:11], v[176:179], v[228:231], v[8:11]
	v_mfma_f32_16x16x32_bf16 v[52:55], v[180:183], v[200:203], v[52:55]
	v_mfma_f32_16x16x32_bf16 v[48:51], v[188:191], v[200:203], v[48:51]
	v_mfma_f32_16x16x32_bf16 v[36:39], v[180:183], v[208:211], v[36:39]
	v_mfma_f32_16x16x32_bf16 v[32:35], v[188:191], v[208:211], v[32:35]
	v_mfma_f32_16x16x32_bf16 v[20:23], v[180:183], v[216:219], v[20:23]
	v_mfma_f32_16x16x32_bf16 v[16:19], v[188:191], v[216:219], v[16:19]
	v_mfma_f32_16x16x32_bf16 v[4:7], v[180:183], v[224:227], v[4:7]
	v_mfma_f32_16x16x32_bf16 v[0:3], v[188:191], v[224:227], v[0:3]
	v_mfma_f32_16x16x32_bf16 v[52:55], v[184:187], v[204:207], v[52:55]
	v_mfma_f32_16x16x32_bf16 v[48:51], v[196:199], v[204:207], v[48:51]
	v_mfma_f32_16x16x32_bf16 v[36:39], v[184:187], v[212:215], v[36:39]
	v_mfma_f32_16x16x32_bf16 v[32:35], v[196:199], v[212:215], v[32:35]
	v_mfma_f32_16x16x32_bf16 v[20:23], v[184:187], v[220:223], v[20:23]
	v_mfma_f32_16x16x32_bf16 v[16:19], v[196:199], v[220:223], v[16:19]
	v_mfma_f32_16x16x32_bf16 v[4:7], v[184:187], v[228:231], v[4:7]
	v_mfma_f32_16x16x32_bf16 v[0:3], v[196:199], v[228:231], v[0:3]
	s_barrier
; #define PG8_STAGE(bufoff, gbase, voff) do { _Pragma("unroll") for (int _i = 0; _i < 2; ++_i) \
;         __builtin_amdgcn_global_load_lds((const unsigned*)((const char*)(gbase) + (voff)[_i]), (PG8_LAS unsigned*)(lds + (bufoff) + ldsw + _i * 8192), 16, 0, 0); } while (0)
; #define PG8_LDA(dst, b, h) do { _Pragma("unroll") for (int m = 0; m < 4; ++m) _Pragma("unroll") for (int k = 0; k < 2; ++k) dst[m][k] = *(const PG8_LAS bf16x8*)(lds + PG8_SA(b, h) + aoff + m * 2048 + k * 1024); } while (0)
; #define PG8_LDB(dst, b, h) do { _Pragma("unroll") for (int n = 0; n < 2; ++n) _Pragma("unroll") for (int k = 0; k < 2; ++k) dst[n][k] = *(const PG8_LAS bf16x8*)(lds + PG8_SB(b, h) + boff + n * 2048 + k * 1024); } while (0)
; #define PG8_MMA(ai, bj, At, Bt) do { __builtin_amdgcn_s_setprio(1); _Pragma("unroll") for (int m = 0; m < 4; ++m) _Pragma("unroll") for (int n = 0; n < 2; ++n) _Pragma("unroll") for (int k = 0; k < 2; ++k) \
;         acc[ai][bj][m][n] = __builtin_amdgcn_mfma_f32_16x16x32_bf16(Bt[n][k], At[m][k], acc[ai][bj][m][n], 0, 0, 0); __builtin_amdgcn_s_setprio(0); } while (0)
; #define PG8_WAIT_V(n) asm volatile("s_waitcnt vmcnt(" #n ")" ::: "memory")
; #define PG8_WAIT_L(n) asm volatile("s_waitcnt lgkmcnt(" #n ")" ::: "memory")
; #define PG8_BAR __builtin_amdgcn_s_barrier()
; #define PG8_SCHED __builtin_amdgcn_sched_barrier(0)
; template <class Epi, class Sched, bool ALIGN_EPI = false, bool SP2 = false>
; __device__ __forceinline__ void gemm_phase(PG8_LAS unsigned char* lds, const Gemm g, const Sched& S, const Epi& E) {
;     ...
;             PG8_LDB(B0, 1, 0); PG8_LDB(B1, 1, 1); PG8_SCHED; PG8_LDA(At, 1, 0); PG8_STAGE(PG8_SA(0, 1), a2 + hstep, voffA);
;             PG8_WAIT_V(8); PG8_WAIT_L(0); PG8_BAR; PG8_MMA(0, 0, At, B0); PG8_MMA(0, 1, At, B1); PG8_BAR; PG8_SCHED;
;             PG8_LDA(At, 1, 1); PG8_STAGE(PG8_SB(1, 0), b3, voffB); PG8_STAGE(PG8_SB(1, 1), b3 + hstep, voffB); PG8_STAGE(PG8_SA(1, 0), a3, voffA);
;             PG8_WAIT_V(8); PG8_WAIT_L(0); PG8_BAR; PG8_MMA(1, 0, At, B0); PG8_MMA(1, 1, At, B1); PG8_BAR; PG8_SCHED;
	s_add_i32 s73, 0, 0x18000
	v_add_u32_e32 v175, s73, v143
	s_add_i32 s82, 0, 0x1c000
	ds_read_b128 v[152:155], v175
	ds_read_b128 v[156:159], v175 offset:1024
	ds_read_b128 v[166:169], v175 offset:2048
	ds_read_b128 v[176:179], v175 offset:3072
	v_add_u32_e32 v175, s82, v143
	ds_read_b128 v[180:183], v175
	ds_read_b128 v[184:187], v175 offset:1024
	ds_read_b128 v[188:191], v175 offset:2048
	ds_read_b128 v[196:199], v175 offset:3072
	s_add_u32 s6, s80, 0x40000
	s_addc_u32 s7, s81, 0
	s_mov_b32 m0, s37
	ds_read_b128 v[200:203], v174 offset:32768
	ds_read_b128 v[204:207], v174 offset:33792
	ds_read_b128 v[208:211], v174 offset:34816
	ds_read_b128 v[212:215], v174 offset:35840
	ds_read_b128 v[216:219], v174 offset:36864
	ds_read_b128 v[220:223], v174 offset:37888
	ds_read_b128 v[224:227], v174 offset:38912
	ds_read_b128 v[228:231], v174 offset:39936
	global_load_lds_dwordx4 v132, s[6:7]
	s_mov_b32 m0, s42
	s_nop 0
	global_load_lds_dwordx4 v136, s[6:7]
	s_waitcnt vmcnt(8)
	s_waitcnt lgkmcnt(0)
	s_barrier
	s_waitcnt lgkmcnt(0)
	v_mfma_f32_16x16x32_bf16 v[124:127], v[152:155], v[200:203], v[124:127]
	v_mfma_f32_16x16x32_bf16 v[120:123], v[166:169], v[200:203], v[120:123]
	v_mfma_f32_16x16x32_bf16 v[108:111], v[152:155], v[208:211], v[108:111]
	v_mfma_f32_16x16x32_bf16 v[104:107], v[166:169], v[208:211], v[104:107]
	v_mfma_f32_16x16x32_bf16 v[92:95], v[152:155], v[216:219], v[92:95]
	v_mfma_f32_16x16x32_bf16 v[88:91], v[166:169], v[216:219], v[88:91]
	v_mfma_f32_16x16x32_bf16 v[76:79], v[152:155], v[224:227], v[76:79]
	v_mfma_f32_16x16x32_bf16 v[72:75], v[166:169], v[224:227], v[72:75]
	v_mfma_f32_16x16x32_bf16 v[124:127], v[156:159], v[204:207], v[124:127]
	v_mfma_f32_16x16x32_bf16 v[120:123], v[176:179], v[204:207], v[120:123]
	v_mfma_f32_16x16x32_bf16 v[108:111], v[156:159], v[212:215], v[108:111]
	v_mfma_f32_16x16x32_bf16 v[104:107], v[176:179], v[212:215], v[104:107]
	v_mfma_f32_16x16x32_bf16 v[92:95], v[156:159], v[220:223], v[92:95]
	v_mfma_f32_16x16x32_bf16 v[88:91], v[176:179], v[220:223], v[88:91]
	v_mfma_f32_16x16x32_bf16 v[76:79], v[156:159], v[228:231], v[76:79]
	v_mfma_f32_16x16x32_bf16 v[72:75], v[176:179], v[228:231], v[72:75]
	v_mfma_f32_16x16x32_bf16 v[116:119], v[180:183], v[200:203], v[116:119]
	v_mfma_f32_16x16x32_bf16 v[112:115], v[188:191], v[200:203], v[112:115]
	v_mfma_f32_16x16x32_bf16 v[100:103], v[180:183], v[208:211], v[100:103]
	v_mfma_f32_16x16x32_bf16 v[96:99], v[188:191], v[208:211], v[96:99]
	v_mfma_f32_16x16x32_bf16 v[84:87], v[180:183], v[216:219], v[84:87]
	v_mfma_f32_16x16x32_bf16 v[80:83], v[188:191], v[216:219], v[80:83]
	v_mfma_f32_16x16x32_bf16 v[68:71], v[180:183], v[224:227], v[68:71]
	v_mfma_f32_16x16x32_bf16 v[64:67], v[188:191], v[224:227], v[64:67]
	v_mfma_f32_16x16x32_bf16 v[116:119], v[184:187], v[204:207], v[116:119]
	v_mfma_f32_16x16x32_bf16 v[112:115], v[196:199], v[204:207], v[112:115]
	v_mfma_f32_16x16x32_bf16 v[100:103], v[184:187], v[212:215], v[100:103]
	v_mfma_f32_16x16x32_bf16 v[96:99], v[196:199], v[212:215], v[96:99]
	v_mfma_f32_16x16x32_bf16 v[84:87], v[184:187], v[220:223], v[84:87]
	v_mfma_f32_16x16x32_bf16 v[80:83], v[196:199], v[220:223], v[80:83]
	v_mfma_f32_16x16x32_bf16 v[68:71], v[184:187], v[228:231], v[68:71]
	v_mfma_f32_16x16x32_bf16 v[64:67], v[196:199], v[228:231], v[64:67]
	s_barrier
	s_add_i32 s6, s73, s30
	v_lshl_add_u64 v[232:233], v[232:233], 0, s[40:41]
	s_mov_b32 m0, s6
	ds_read_b128 v[200:203], v174 offset:49152
	ds_read_b128 v[204:207], v174 offset:50176
	ds_read_b128 v[208:211], v174 offset:51200
	ds_read_b128 v[212:215], v174 offset:52224
	ds_read_b128 v[216:219], v174 offset:53248
	ds_read_b128 v[220:223], v174 offset:54272
	ds_read_b128 v[224:227], v174 offset:55296
	ds_read_b128 v[228:231], v174 offset:56320
	global_load_lds_dwordx4 v[232:233], off
	s_add_i32 m0, s6, 0x2000
	s_add_u32 s6, s78, 0x40080
	v_lshl_add_u64 v[232:233], v[234:235], 0, s[40:41]
	s_addc_u32 s7, s79, 0
	s_add_i32 s73, s82, s30
	global_load_lds_dwordx4 v[232:233], off
	s_mov_b32 m0, s73
	s_nop 0
	global_load_lds_dwordx4 v134, s[6:7]
	s_add_i32 m0, s73, 0x2000
	s_nop 0
	global_load_lds_dwordx4 v138, s[6:7]
	v_lshl_add_u64 v[232:233], v[236:237], 0, s[40:41]
	s_mov_b32 m0, s67
	s_nop 0
	global_load_lds_dwordx4 v[232:233], off
	v_lshl_add_u64 v[232:233], v[238:239], 0, s[40:41]
	s_mov_b32 m0, s68
	s_nop 0
	global_load_lds_dwordx4 v[232:233], off
	s_waitcnt vmcnt(8)
	s_waitcnt lgkmcnt(0)
	s_barrier
	s_waitcnt lgkmcnt(0)
	v_mfma_f32_16x16x32_bf16 v[60:63], v[152:155], v[200:203], v[60:63]
	v_mfma_f32_16x16x32_bf16 v[56:59], v[166:169], v[200:203], v[56:59]
	v_mfma_f32_16x16x32_bf16 v[44:47], v[152:155], v[208:211], v[44:47]
	v_mfma_f32_16x16x32_bf16 v[40:43], v[166:169], v[208:211], v[40:43]
	v_mfma_f32_16x16x32_bf16 v[28:31], v[152:155], v[216:219], v[28:31]
	v_mfma_f32_16x16x32_bf16 v[24:27], v[166:169], v[216:219], v[24:27]
	v_mfma_f32_16x16x32_bf16 v[12:15], v[152:155], v[224:227], v[12:15]
	v_mfma_f32_16x16x32_bf16 v[8:11], v[166:169], v[224:227], v[8:11]
	v_mfma_f32_16x16x32_bf16 v[60:63], v[156:159], v[204:207], v[60:63]
	v_mfma_f32_16x16x32_bf16 v[56:59], v[176:179], v[204:207], v[56:59]
	v_mfma_f32_16x16x32_bf16 v[44:47], v[156:159], v[212:215], v[44:47]
	v_mfma_f32_16x16x32_bf16 v[40:43], v[176:179], v[212:215], v[40:43]
	v_mfma_f32_16x16x32_bf16 v[28:31], v[156:159], v[220:223], v[28:31]
	v_mfma_f32_16x16x32_bf16 v[24:27], v[176:179], v[220:223], v[24:27]
	v_mfma_f32_16x16x32_bf16 v[12:15], v[156:159], v[228:231], v[12:15]
	v_mfma_f32_16x16x32_bf16 v[8:11], v[176:179], v[228:231], v[8:11]
	v_mfma_f32_16x16x32_bf16 v[52:55], v[180:183], v[200:203], v[52:55]
	v_mfma_f32_16x16x32_bf16 v[48:51], v[188:191], v[200:203], v[48:51]
	v_mfma_f32_16x16x32_bf16 v[36:39], v[180:183], v[208:211], v[36:39]
	v_mfma_f32_16x16x32_bf16 v[32:35], v[188:191], v[208:211], v[32:35]
	v_mfma_f32_16x16x32_bf16 v[20:23], v[180:183], v[216:219], v[20:23]
	v_mfma_f32_16x16x32_bf16 v[16:19], v[188:191], v[216:219], v[16:19]
	v_mfma_f32_16x16x32_bf16 v[4:7], v[180:183], v[224:227], v[4:7]
	v_mfma_f32_16x16x32_bf16 v[0:3], v[188:191], v[224:227], v[0:3]
	v_mfma_f32_16x16x32_bf16 v[52:55], v[184:187], v[204:207], v[52:55]
	v_mfma_f32_16x16x32_bf16 v[48:51], v[196:199], v[204:207], v[48:51]
	v_mfma_f32_16x16x32_bf16 v[36:39], v[184:187], v[212:215], v[36:39]
	v_mfma_f32_16x16x32_bf16 v[32:35], v[196:199], v[212:215], v[32:35]
	v_mfma_f32_16x16x32_bf16 v[20:23], v[184:187], v[220:223], v[20:23]
	v_mfma_f32_16x16x32_bf16 v[16:19], v[196:199], v[220:223], v[16:19]
	v_mfma_f32_16x16x32_bf16 v[4:7], v[184:187], v[228:231], v[4:7]
	v_mfma_f32_16x16x32_bf16 v[0:3], v[196:199], v[228:231], v[0:3]
	s_barrier
	s_add_i32 s72, s72, 2
	s_add_u32 s60, s60, 0x100
	s_addc_u32 s61, s61, 0
	s_add_u32 vcc_hi, vcc_hi, 0x100
	s_addc_u32 s33, s33, 0
	s_cmp_gt_u32 s72, 13
	s_cbranch_scc0 .LBB0_463
	s_and_b64 vcc, exec, s[50:51]
	s_cbranch_vccz .LBB0_466
	s_barrier

; #define PG8_STAGE(bufoff, gbase, voff) do { _Pragma("unroll") for (int _i = 0; _i < 2; ++_i) \
;         __builtin_amdgcn_global_load_lds((const unsigned*)((const char*)(gbase) + (voff)[_i]), (PG8_LAS unsigned*)(lds + (bufoff) + ldsw + _i * 8192), 16, 0, 0); } while (0)
; #define PG8_LDA(dst, b, h) do { _Pragma("unroll") for (int m = 0; m < 4; ++m) _Pragma("unroll") for (int k = 0; k < 2; ++k) dst[m][k] = *(const PG8_LAS bf16x8*)(lds + PG8_SA(b, h) + aoff + m * 2048 + k * 1024); } while (0)
; #define PG8_LDB(dst, b, h) do { _Pragma("unroll") for (int n = 0; n < 2; ++n) _Pragma("unroll") for (int k = 0; k < 2; ++k) dst[n][k] = *(const PG8_LAS bf16x8*)(lds + PG8_SB(b, h) + boff + n * 2048 + k * 1024); } while (0)
; #define PG8_MMA(ai, bj, At, Bt) do { __builtin_amdgcn_s_setprio(1); _Pragma("unroll") for (int m = 0; m < 4; ++m) _Pragma("unroll") for (int n = 0; n < 2; ++n) _Pragma("unroll") for (int k = 0; k < 2; ++k) \
;         acc[ai][bj][m][n] = __builtin_amdgcn_mfma_f32_16x16x32_bf16(Bt[n][k], At[m][k], acc[ai][bj][m][n], 0, 0, 0); __builtin_amdgcn_s_setprio(0); } while (0)
; #define PG8_WAIT_V(n) asm volatile("s_waitcnt vmcnt(" #n ")" ::: "memory")
; #define PG8_BAR __builtin_amdgcn_s_barrier()
; template <class Epi, class Sched, bool ALIGN_EPI = false, bool SP2 = false>
; __device__ __forceinline__ void gemm_phase(PG8_LAS unsigned char* lds, const Gemm g, const Sched& S, const Epi& E) {
;     ...
;         for (int t = 0; t < nt; t += 2) {
;             const bool last = (t == nt - 2);
;             const char* a1 = cA + (size_t)(t + 1) * kstep;
;             const char* a2 = last ? nA : cA + (size_t)(t + 2) * kstep; const char* b2 = last ? nB : cB + (size_t)(t + 2) * kstep;
;             const char* a3 = a2 + kstep; const char* b3 = b2 + kstep;
;             if (last && has_next) S.a_ready(nxt);
;             if constexpr (SP2) {
;             PG8_LDB(B0, 0, 0); PG8_LDB(B1, 0, 1); PG8_SCHED; PG8_LDA(At, 0, 0); PG8_STAGE(PG8_SA(1, 1), a1 + hstep, voffA);
;             PG8_WAIT_V(8); PG8_WAIT_L(0); PG8_BAR; PG8_MMA(0, 0, At, B0); PG8_MMA(0, 1, At, B1); PG8_BAR; PG8_SCHED;
;             PG8_LDA(At, 0, 1); PG8_STAGE(PG8_SB(0, 0), b2, voffB); PG8_STAGE(PG8_SB(0, 1), b2 + hstep, voffB); PG8_STAGE(PG8_SA(0, 0), a2, voffA);
;             PG8_WAIT_V(8); PG8_WAIT_L(0); PG8_BAR; PG8_MMA(1, 0, At, B0); PG8_MMA(1, 1, At, B1); PG8_BAR; PG8_SCHED;
.LBB0_777:
	ds_read_b128 v[144:147], v158
	ds_read_b128 v[168:171], v158 offset:1024
	ds_read_b128 v[172:175], v158 offset:2048
	ds_read_b128 v[176:179], v158 offset:3072
	ds_read_b128 v[180:183], v159
	ds_read_b128 v[184:187], v159 offset:1024
	ds_read_b128 v[188:191], v159 offset:2048
	ds_read_b128 v[196:199], v159 offset:3072
	s_add_u32 s60, s58, 0x100
	s_addc_u32 s61, s59, 0
	s_cmp_eq_u32 s72, 8
	s_cselect_b32 s81, s49, s61
	s_cselect_b32 s80, s48, s60
	s_cselect_b32 s79, s57, vcc_lo
	s_cselect_b32 s78, s56, s33
	s_add_i32 m0, s76, 0xc000
	ds_read_b128 v[200:203], v163
	ds_read_b128 v[204:207], v163 offset:1024
	ds_read_b128 v[208:211], v163 offset:2048
	ds_read_b128 v[212:215], v163 offset:3072
	ds_read_b128 v[216:219], v163 offset:4096
	ds_read_b128 v[220:223], v163 offset:5120
	ds_read_b128 v[224:227], v163 offset:6144
	ds_read_b128 v[228:231], v163 offset:7168
	global_load_lds_dwordx4 v136, s[58:59]
	s_add_i32 m0, s76, 0xe000
	s_nop 0
	global_load_lds_dwordx4 v138, s[58:59]
	s_waitcnt vmcnt(8)
	s_waitcnt lgkmcnt(0)
	s_barrier
	s_waitcnt lgkmcnt(0)
	v_mfma_f32_16x16x32_bf16 v[124:127], v[144:147], v[200:203], v[124:127]
	v_mfma_f32_16x16x32_bf16 v[120:123], v[172:175], v[200:203], v[120:123]
	v_mfma_f32_16x16x32_bf16 v[108:111], v[144:147], v[208:211], v[108:111]
	v_mfma_f32_16x16x32_bf16 v[104:107], v[172:175], v[208:211], v[104:107]
	v_mfma_f32_16x16x32_bf16 v[92:95], v[144:147], v[216:219], v[92:95]
	v_mfma_f32_16x16x32_bf16 v[88:91], v[172:175], v[216:219], v[88:91]
	v_mfma_f32_16x16x32_bf16 v[76:79], v[144:147], v[224:227], v[76:79]
	v_mfma_f32_16x16x32_bf16 v[72:75], v[172:175], v[224:227], v[72:75]
	v_mfma_f32_16x16x32_bf16 v[124:127], v[168:171], v[204:207], v[124:127]
	v_mfma_f32_16x16x32_bf16 v[120:123], v[176:179], v[204:207], v[120:123]
	v_mfma_f32_16x16x32_bf16 v[108:111], v[168:171], v[212:215], v[108:111]
	v_mfma_f32_16x16x32_bf16 v[104:107], v[176:179], v[212:215], v[104:107]
	v_mfma_f32_16x16x32_bf16 v[92:95], v[168:171], v[220:223], v[92:95]
	v_mfma_f32_16x16x32_bf16 v[88:91], v[176:179], v[220:223], v[88:91]
	v_mfma_f32_16x16x32_bf16 v[76:79], v[168:171], v[228:231], v[76:79]
	v_mfma_f32_16x16x32_bf16 v[72:75], v[176:179], v[228:231], v[72:75]
	v_mfma_f32_16x16x32_bf16 v[116:119], v[180:183], v[200:203], v[116:119]
	v_mfma_f32_16x16x32_bf16 v[112:115], v[188:191], v[200:203], v[112:115]
	v_mfma_f32_16x16x32_bf16 v[100:103], v[180:183], v[208:211], v[100:103]
	v_mfma_f32_16x16x32_bf16 v[96:99], v[188:191], v[208:211], v[96:99]
	v_mfma_f32_16x16x32_bf16 v[84:87], v[180:183], v[216:219], v[84:87]
	v_mfma_f32_16x16x32_bf16 v[80:83], v[188:191], v[216:219], v[80:83]
	v_mfma_f32_16x16x32_bf16 v[68:71], v[180:183], v[224:227], v[68:71]
	v_mfma_f32_16x16x32_bf16 v[64:67], v[188:191], v[224:227], v[64:67]
	v_mfma_f32_16x16x32_bf16 v[116:119], v[184:187], v[204:207], v[116:119]
	v_mfma_f32_16x16x32_bf16 v[112:115], v[196:199], v[204:207], v[112:115]
	v_mfma_f32_16x16x32_bf16 v[100:103], v[184:187], v[212:215], v[100:103]
	v_mfma_f32_16x16x32_bf16 v[96:99], v[196:199], v[212:215], v[96:99]
	v_mfma_f32_16x16x32_bf16 v[84:87], v[184:187], v[220:223], v[84:87]
	v_mfma_f32_16x16x32_bf16 v[80:83], v[196:199], v[220:223], v[80:83]
	v_mfma_f32_16x16x32_bf16 v[68:71], v[184:187], v[228:231], v[68:71]
	v_mfma_f32_16x16x32_bf16 v[64:67], v[196:199], v[228:231], v[64:67]
	s_barrier
	s_add_i32 s6, s26, s67
	v_lshl_add_u64 v[148:149], s[78:79], 0, v[130:131]
	s_mov_b32 m0, s6
	ds_read_b128 v[200:203], v163 offset:16384
	ds_read_b128 v[204:207], v163 offset:17408
	ds_read_b128 v[208:211], v163 offset:18432
	ds_read_b128 v[212:215], v163 offset:19456
	ds_read_b128 v[216:219], v163 offset:20480
	ds_read_b128 v[220:223], v163 offset:21504
	ds_read_b128 v[224:227], v163 offset:22528
	ds_read_b128 v[228:231], v163 offset:23552
	global_load_lds_dwordx4 v[148:149], off
	s_add_i32 m0, s6, 0x2000
	s_add_u32 s6, s78, 0x30000
	v_lshl_add_u64 v[232:233], s[78:79], 0, v[134:135]
	s_addc_u32 s7, s79, 0
	s_add_i32 s58, s74, s67
	global_load_lds_dwordx4 v[232:233], off
	s_mov_b32 m0, s58
	v_lshl_add_u64 v[236:237], s[80:81], 0, v[132:133]
	global_load_lds_dwordx4 v130, s[6:7]
	s_add_i32 m0, s58, 0x2000
	s_nop 0
	global_load_lds_dwordx4 v134, s[6:7]
	v_lshl_add_u64 v[234:235], s[80:81], 0, v[128:129]
	s_mov_b32 m0, s76
	s_nop 0
	global_load_lds_dwordx4 v[234:235], off
	s_mov_b32 m0, s77
	s_nop 0
	global_load_lds_dwordx4 v[236:237], off
	s_waitcnt vmcnt(8)
	s_waitcnt lgkmcnt(0)
	s_barrier
	s_waitcnt lgkmcnt(0)
	v_mfma_f32_16x16x32_bf16 v[60:63], v[144:147], v[200:203], v[60:63]
	v_mfma_f32_16x16x32_bf16 v[56:59], v[172:175], v[200:203], v[56:59]
	v_mfma_f32_16x16x32_bf16 v[44:47], v[144:147], v[208:211], v[44:47]
	v_mfma_f32_16x16x32_bf16 v[40:43], v[172:175], v[208:211], v[40:43]
	v_mfma_f32_16x16x32_bf16 v[28:31], v[144:147], v[216:219], v[28:31]
	v_mfma_f32_16x16x32_bf16 v[24:27], v[172:175], v[216:219], v[24:27]
	v_mfma_f32_16x16x32_bf16 v[12:15], v[144:147], v[224:227], v[12:15]
	v_mfma_f32_16x16x32_bf16 v[8:11], v[172:175], v[224:227], v[8:11]
	v_mfma_f32_16x16x32_bf16 v[60:63], v[168:171], v[204:207], v[60:63]
	v_mfma_f32_16x16x32_bf16 v[56:59], v[176:179], v[204:207], v[56:59]
	v_mfma_f32_16x16x32_bf16 v[44:47], v[168:171], v[212:215], v[44:47]
	v_mfma_f32_16x16x32_bf16 v[40:43], v[176:179], v[212:215], v[40:43]
	v_mfma_f32_16x16x32_bf16 v[28:31], v[168:171], v[220:223], v[28:31]
	v_mfma_f32_16x16x32_bf16 v[24:27], v[176:179], v[220:223], v[24:27]
	v_mfma_f32_16x16x32_bf16 v[12:15], v[168:171], v[228:231], v[12:15]
	v_mfma_f32_16x16x32_bf16 v[8:11], v[176:179], v[228:231], v[8:11]
	v_mfma_f32_16x16x32_bf16 v[52:55], v[180:183], v[200:203], v[52:55]
	v_mfma_f32_16x16x32_bf16 v[48:51], v[188:191], v[200:203], v[48:51]
	v_mfma_f32_16x16x32_bf16 v[36:39], v[180:183], v[208:211], v[36:39]
	v_mfma_f32_16x16x32_bf16 v[32:35], v[188:191], v[208:211], v[32:35]
	v_mfma_f32_16x16x32_bf16 v[20:23], v[180:183], v[216:219], v[20:23]
	v_mfma_f32_16x16x32_bf16 v[16:19], v[188:191], v[216:219], v[16:19]
	v_mfma_f32_16x16x32_bf16 v[4:7], v[180:183], v[224:227], v[4:7]
	v_mfma_f32_16x16x32_bf16 v[0:3], v[188:191], v[224:227], v[0:3]
	v_mfma_f32_16x16x32_bf16 v[52:55], v[184:187], v[204:207], v[52:55]
	v_mfma_f32_16x16x32_bf16 v[48:51], v[196:199], v[204:207], v[48:51]
	v_mfma_f32_16x16x32_bf16 v[36:39], v[184:187], v[212:215], v[36:39]
	v_mfma_f32_16x16x32_bf16 v[32:35], v[196:199], v[212:215], v[32:35]
	v_mfma_f32_16x16x32_bf16 v[20:23], v[184:187], v[220:223], v[20:23]
	v_mfma_f32_16x16x32_bf16 v[16:19], v[196:199], v[220:223], v[16:19]
	v_mfma_f32_16x16x32_bf16 v[4:7], v[184:187], v[228:231], v[4:7]
	v_mfma_f32_16x16x32_bf16 v[0:3], v[196:199], v[228:231], v[0:3]
	s_barrier
; #define PG8_STAGE(bufoff, gbase, voff) do { _Pragma("unroll") for (int _i = 0; _i < 2; ++_i) \
;         __builtin_amdgcn_global_load_lds((const unsigned*)((const char*)(gbase) + (voff)[_i]), (PG8_LAS unsigned*)(lds + (bufoff) + ldsw + _i * 8192), 16, 0, 0); } while (0)
; #define PG8_LDA(dst, b, h) do { _Pragma("unroll") for (int m = 0; m < 4; ++m) _Pragma("unroll") for (int k = 0; k < 2; ++k) dst[m][k] = *(const PG8_LAS bf16x8*)(lds + PG8_SA(b, h) + aoff + m * 2048 + k * 1024); } while (0)
; #define PG8_LDB(dst, b, h) do { _Pragma("unroll") for (int n = 0; n < 2; ++n) _Pragma("unroll") for (int k = 0; k < 2; ++k) dst[n][k] = *(const PG8_LAS bf16x8*)(lds + PG8_SB(b, h) + boff + n * 2048 + k * 1024); } while (0)
; #define PG8_MMA(ai, bj, At, Bt) do { __builtin_amdgcn_s_setprio(1); _Pragma("unroll") for (int m = 0; m < 4; ++m) _Pragma("unroll") for (int n = 0; n < 2; ++n) _Pragma("unroll") for (int k = 0; k < 2; ++k) \
;         acc[ai][bj][m][n] = __builtin_amdgcn_mfma_f32_16x16x32_bf16(Bt[n][k], At[m][k], acc[ai][bj][m][n], 0, 0, 0); __builtin_amdgcn_s_setprio(0); } while (0)
; #define PG8_WAIT_V(n) asm volatile("s_waitcnt vmcnt(" #n ")" ::: "memory")
; #define PG8_WAIT_L(n) asm volatile("s_waitcnt lgkmcnt(" #n ")" ::: "memory")
; #define PG8_BAR __builtin_amdgcn_s_barrier()
; #define PG8_SCHED __builtin_amdgcn_sched_barrier(0)
; template <class Epi, class Sched, bool ALIGN_EPI = false, bool SP2 = false>
; __device__ __forceinline__ void gemm_phase(PG8_LAS unsigned char* lds, const Gemm g, const Sched& S, const Epi& E) {
;     ...
;             PG8_LDB(B0, 1, 0); PG8_LDB(B1, 1, 1); PG8_SCHED; PG8_LDA(At, 1, 0); PG8_STAGE(PG8_SA(0, 1), a2 + hstep, voffA);
;             PG8_WAIT_V(8); PG8_WAIT_L(0); PG8_BAR; PG8_MMA(0, 0, At, B0); PG8_MMA(0, 1, At, B1); PG8_BAR; PG8_SCHED;
;             PG8_LDA(At, 1, 1); PG8_STAGE(PG8_SB(1, 0), b3, voffB); PG8_STAGE(PG8_SB(1, 1), b3 + hstep, voffB); PG8_STAGE(PG8_SA(1, 0), a3, voffA);
;             PG8_WAIT_V(8); PG8_WAIT_L(0); PG8_BAR; PG8_MMA(1, 0, At, B0); PG8_MMA(1, 1, At, B1); PG8_BAR; PG8_SCHED;
	s_add_i32 s58, 0, 0x18000
	v_add_u32_e32 v167, s58, v156
	s_add_i32 s59, 0, 0x1c000
	ds_read_b128 v[144:147], v167
	ds_read_b128 v[168:171], v167 offset:1024
	ds_read_b128 v[172:175], v167 offset:2048
	ds_read_b128 v[176:179], v167 offset:3072
	v_add_u32_e32 v167, s59, v156
	ds_read_b128 v[180:183], v167
	ds_read_b128 v[184:187], v167 offset:1024
	ds_read_b128 v[188:191], v167 offset:2048
	ds_read_b128 v[196:199], v167 offset:3072
	s_add_u32 s6, s80, 0x30000
	s_addc_u32 s7, s81, 0
	s_mov_b32 m0, s36
	ds_read_b128 v[200:203], v163 offset:32768
	ds_read_b128 v[204:207], v163 offset:33792
	ds_read_b128 v[208:211], v163 offset:34816
	ds_read_b128 v[212:215], v163 offset:35840
	ds_read_b128 v[216:219], v163 offset:36864
	ds_read_b128 v[220:223], v163 offset:37888
	ds_read_b128 v[224:227], v163 offset:38912
	ds_read_b128 v[228:231], v163 offset:39936
	global_load_lds_dwordx4 v128, s[6:7]
	s_mov_b32 m0, s37
	s_nop 0
	global_load_lds_dwordx4 v132, s[6:7]
	s_waitcnt vmcnt(8)
	s_waitcnt lgkmcnt(0)
	s_barrier
	s_waitcnt lgkmcnt(0)
	v_mfma_f32_16x16x32_bf16 v[124:127], v[144:147], v[200:203], v[124:127]
	v_mfma_f32_16x16x32_bf16 v[120:123], v[172:175], v[200:203], v[120:123]
	v_mfma_f32_16x16x32_bf16 v[108:111], v[144:147], v[208:211], v[108:111]
	v_mfma_f32_16x16x32_bf16 v[104:107], v[172:175], v[208:211], v[104:107]
	v_mfma_f32_16x16x32_bf16 v[92:95], v[144:147], v[216:219], v[92:95]
	v_mfma_f32_16x16x32_bf16 v[88:91], v[172:175], v[216:219], v[88:91]
	v_mfma_f32_16x16x32_bf16 v[76:79], v[144:147], v[224:227], v[76:79]
	v_mfma_f32_16x16x32_bf16 v[72:75], v[172:175], v[224:227], v[72:75]
	v_mfma_f32_16x16x32_bf16 v[124:127], v[168:171], v[204:207], v[124:127]
	v_mfma_f32_16x16x32_bf16 v[120:123], v[176:179], v[204:207], v[120:123]
	v_mfma_f32_16x16x32_bf16 v[108:111], v[168:171], v[212:215], v[108:111]
	v_mfma_f32_16x16x32_bf16 v[104:107], v[176:179], v[212:215], v[104:107]
	v_mfma_f32_16x16x32_bf16 v[92:95], v[168:171], v[220:223], v[92:95]
	v_mfma_f32_16x16x32_bf16 v[88:91], v[176:179], v[220:223], v[88:91]
	v_mfma_f32_16x16x32_bf16 v[76:79], v[168:171], v[228:231], v[76:79]
	v_mfma_f32_16x16x32_bf16 v[72:75], v[176:179], v[228:231], v[72:75]
	v_mfma_f32_16x16x32_bf16 v[116:119], v[180:183], v[200:203], v[116:119]
	v_mfma_f32_16x16x32_bf16 v[112:115], v[188:191], v[200:203], v[112:115]
	v_mfma_f32_16x16x32_bf16 v[100:103], v[180:183], v[208:211], v[100:103]
	v_mfma_f32_16x16x32_bf16 v[96:99], v[188:191], v[208:211], v[96:99]
	v_mfma_f32_16x16x32_bf16 v[84:87], v[180:183], v[216:219], v[84:87]
	v_mfma_f32_16x16x32_bf16 v[80:83], v[188:191], v[216:219], v[80:83]
	v_mfma_f32_16x16x32_bf16 v[68:71], v[180:183], v[224:227], v[68:71]
	v_mfma_f32_16x16x32_bf16 v[64:67], v[188:191], v[224:227], v[64:67]
	v_mfma_f32_16x16x32_bf16 v[116:119], v[184:187], v[204:207], v[116:119]
	v_mfma_f32_16x16x32_bf16 v[112:115], v[196:199], v[204:207], v[112:115]
	v_mfma_f32_16x16x32_bf16 v[100:103], v[184:187], v[212:215], v[100:103]
	v_mfma_f32_16x16x32_bf16 v[96:99], v[196:199], v[212:215], v[96:99]
	v_mfma_f32_16x16x32_bf16 v[84:87], v[184:187], v[220:223], v[84:87]
	v_mfma_f32_16x16x32_bf16 v[80:83], v[196:199], v[220:223], v[80:83]
	v_mfma_f32_16x16x32_bf16 v[68:71], v[184:187], v[228:231], v[68:71]
	v_mfma_f32_16x16x32_bf16 v[64:67], v[196:199], v[228:231], v[64:67]
	s_barrier
	s_add_i32 s6, s58, s67
	v_lshl_add_u64 v[148:149], v[148:149], 0, s[52:53]
	s_mov_b32 m0, s6
	ds_read_b128 v[200:203], v163 offset:49152
	ds_read_b128 v[204:207], v163 offset:50176
	ds_read_b128 v[208:211], v163 offset:51200
	ds_read_b128 v[212:215], v163 offset:52224
	ds_read_b128 v[216:219], v163 offset:53248
	ds_read_b128 v[220:223], v163 offset:54272
	ds_read_b128 v[224:227], v163 offset:55296
	ds_read_b128 v[228:231], v163 offset:56320
	global_load_lds_dwordx4 v[148:149], off
	s_add_i32 m0, s6, 0x2000
	s_add_u32 s6, s78, 0x30080
	v_lshl_add_u64 v[148:149], v[232:233], 0, s[52:53]
	s_addc_u32 s7, s79, 0
	s_add_i32 s58, s59, s67
	global_load_lds_dwordx4 v[148:149], off
	s_mov_b32 m0, s58
	s_nop 0
	global_load_lds_dwordx4 v130, s[6:7]
	s_add_i32 m0, s58, 0x2000
	s_nop 0
	global_load_lds_dwordx4 v134, s[6:7]
	v_lshl_add_u64 v[148:149], v[234:235], 0, s[52:53]
	s_mov_b32 m0, s31
	s_nop 0
	global_load_lds_dwordx4 v[148:149], off
	v_lshl_add_u64 v[148:149], v[236:237], 0, s[52:53]
	s_mov_b32 m0, s4
	s_nop 0
	global_load_lds_dwordx4 v[148:149], off
	s_waitcnt vmcnt(8)
	s_waitcnt lgkmcnt(0)
	s_barrier
	s_waitcnt lgkmcnt(0)
	v_mfma_f32_16x16x32_bf16 v[60:63], v[144:147], v[200:203], v[60:63]
	v_mfma_f32_16x16x32_bf16 v[56:59], v[172:175], v[200:203], v[56:59]
	v_mfma_f32_16x16x32_bf16 v[44:47], v[144:147], v[208:211], v[44:47]
	v_mfma_f32_16x16x32_bf16 v[40:43], v[172:175], v[208:211], v[40:43]
	v_mfma_f32_16x16x32_bf16 v[28:31], v[144:147], v[216:219], v[28:31]
	v_mfma_f32_16x16x32_bf16 v[24:27], v[172:175], v[216:219], v[24:27]
	v_mfma_f32_16x16x32_bf16 v[12:15], v[144:147], v[224:227], v[12:15]
	v_mfma_f32_16x16x32_bf16 v[8:11], v[172:175], v[224:227], v[8:11]
	v_mfma_f32_16x16x32_bf16 v[60:63], v[168:171], v[204:207], v[60:63]
	v_mfma_f32_16x16x32_bf16 v[56:59], v[176:179], v[204:207], v[56:59]
	v_mfma_f32_16x16x32_bf16 v[44:47], v[168:171], v[212:215], v[44:47]
	v_mfma_f32_16x16x32_bf16 v[40:43], v[176:179], v[212:215], v[40:43]
	v_mfma_f32_16x16x32_bf16 v[28:31], v[168:171], v[220:223], v[28:31]
	v_mfma_f32_16x16x32_bf16 v[24:27], v[176:179], v[220:223], v[24:27]
	v_mfma_f32_16x16x32_bf16 v[12:15], v[168:171], v[228:231], v[12:15]
	v_mfma_f32_16x16x32_bf16 v[8:11], v[176:179], v[228:231], v[8:11]
	v_mfma_f32_16x16x32_bf16 v[52:55], v[180:183], v[200:203], v[52:55]
	v_mfma_f32_16x16x32_bf16 v[48:51], v[188:191], v[200:203], v[48:51]
	v_mfma_f32_16x16x32_bf16 v[36:39], v[180:183], v[208:211], v[36:39]
	v_mfma_f32_16x16x32_bf16 v[32:35], v[188:191], v[208:211], v[32:35]
	v_mfma_f32_16x16x32_bf16 v[20:23], v[180:183], v[216:219], v[20:23]
	v_mfma_f32_16x16x32_bf16 v[16:19], v[188:191], v[216:219], v[16:19]
	v_mfma_f32_16x16x32_bf16 v[4:7], v[180:183], v[224:227], v[4:7]
	v_mfma_f32_16x16x32_bf16 v[0:3], v[188:191], v[224:227], v[0:3]
	v_mfma_f32_16x16x32_bf16 v[52:55], v[184:187], v[204:207], v[52:55]
	v_mfma_f32_16x16x32_bf16 v[48:51], v[196:199], v[204:207], v[48:51]
	v_mfma_f32_16x16x32_bf16 v[36:39], v[184:187], v[212:215], v[36:39]
	v_mfma_f32_16x16x32_bf16 v[32:35], v[196:199], v[212:215], v[32:35]
	v_mfma_f32_16x16x32_bf16 v[20:23], v[184:187], v[220:223], v[20:23]
	v_mfma_f32_16x16x32_bf16 v[16:19], v[196:199], v[220:223], v[16:19]
	v_mfma_f32_16x16x32_bf16 v[4:7], v[184:187], v[228:231], v[4:7]
	v_mfma_f32_16x16x32_bf16 v[0:3], v[196:199], v[228:231], v[0:3]
	s_barrier
	s_add_i32 s72, s72, 2
	s_add_u32 s33, s33, 0x100
	s_addc_u32 vcc_lo, vcc_lo, 0
	s_cmp_gt_u32 s72, 9
	s_mov_b64 s[58:59], s[60:61]
	s_cbranch_scc0 .LBB0_777
	s_and_b64 vcc, exec, s[54:55]
	s_cbranch_vccz .LBB0_780
	s_barrier

; #define PG8_STAGE(bufoff, gbase, voff) do { _Pragma("unroll") for (int _i = 0; _i < 2; ++_i) \
;         __builtin_amdgcn_global_load_lds((const unsigned*)((const char*)(gbase) + (voff)[_i]), (PG8_LAS unsigned*)(lds + (bufoff) + ldsw + _i * 8192), 16, 0, 0); } while (0)
; #define PG8_LDA(dst, b, h) do { _Pragma("unroll") for (int m = 0; m < 4; ++m) _Pragma("unroll") for (int k = 0; k < 2; ++k) dst[m][k] = *(const PG8_LAS bf16x8*)(lds + PG8_SA(b, h) + aoff + m * 2048 + k * 1024); } while (0)
; #define PG8_LDB(dst, b, h) do { _Pragma("unroll") for (int n = 0; n < 2; ++n) _Pragma("unroll") for (int k = 0; k < 2; ++k) dst[n][k] = *(const PG8_LAS bf16x8*)(lds + PG8_SB(b, h) + boff + n * 2048 + k * 1024); } while (0)
; #define PG8_MMA(ai, bj, At, Bt) do { __builtin_amdgcn_s_setprio(1); _Pragma("unroll") for (int m = 0; m < 4; ++m) _Pragma("unroll") for (int n = 0; n < 2; ++n) _Pragma("unroll") for (int k = 0; k < 2; ++k) \
;         acc[ai][bj][m][n] = __builtin_amdgcn_mfma_f32_16x16x32_bf16(Bt[n][k], At[m][k], acc[ai][bj][m][n], 0, 0, 0); __builtin_amdgcn_s_setprio(0); } while (0)
; #define PG8_WAIT_V(n) asm volatile("s_waitcnt vmcnt(" #n ")" ::: "memory")
; #define PG8_BAR __builtin_amdgcn_s_barrier()
; template <class Epi, class Sched, bool ALIGN_EPI = false, bool SP2 = false>
; __device__ __forceinline__ void gemm_phase(PG8_LAS unsigned char* lds, const Gemm g, const Sched& S, const Epi& E) {
;     ...
;         for (int t = 0; t < nt; t += 2) {
;             const bool last = (t == nt - 2);
;             const char* a1 = cA + (size_t)(t + 1) * kstep;
;             const char* a2 = last ? nA : cA + (size_t)(t + 2) * kstep; const char* b2 = last ? nB : cB + (size_t)(t + 2) * kstep;
;             const char* a3 = a2 + kstep; const char* b3 = b2 + kstep;
;             if (last && has_next) S.a_ready(nxt);
;             if constexpr (SP2) {
;             PG8_LDB(B0, 0, 0); PG8_LDB(B1, 0, 1); PG8_SCHED; PG8_LDA(At, 0, 0); PG8_STAGE(PG8_SA(1, 1), a1 + hstep, voffA);
;             PG8_WAIT_V(8); PG8_WAIT_L(0); PG8_BAR; PG8_MMA(0, 0, At, B0); PG8_MMA(0, 1, At, B1); PG8_BAR; PG8_SCHED;
;             PG8_LDA(At, 0, 1); PG8_STAGE(PG8_SB(0, 0), b2, voffB); PG8_STAGE(PG8_SB(0, 1), b2 + hstep, voffB); PG8_STAGE(PG8_SA(0, 0), a2, voffA);
;             PG8_WAIT_V(8); PG8_WAIT_L(0); PG8_BAR; PG8_MMA(1, 0, At, B0); PG8_MMA(1, 1, At, B1); PG8_BAR; PG8_SCHED;
.LBB0_901:
	ds_read_b128 v[144:147], v159
	ds_read_b128 v[168:171], v159 offset:1024
	ds_read_b128 v[172:175], v159 offset:2048
	ds_read_b128 v[176:179], v159 offset:3072
	ds_read_b128 v[180:183], v163
	ds_read_b128 v[184:187], v163 offset:1024
	ds_read_b128 v[188:191], v163 offset:2048
	ds_read_b128 v[196:199], v163 offset:3072
	s_add_u32 s6, s56, 0xfffc0080
	s_addc_u32 s7, s57, -1
	s_cmp_eq_u32 s72, 12
	s_cselect_b32 s61, s49, s7
	s_cselect_b32 s60, s76, s6
	s_cselect_b32 s59, s41, s33
	s_cselect_b32 s58, s77, s78
	s_add_i32 m0, s30, 0xc000
	ds_read_b128 v[200:203], v166
	ds_read_b128 v[204:207], v166 offset:1024
	ds_read_b128 v[208:211], v166 offset:2048
	ds_read_b128 v[212:215], v166 offset:3072
	ds_read_b128 v[216:219], v166 offset:4096
	ds_read_b128 v[220:223], v166 offset:5120
	ds_read_b128 v[224:227], v166 offset:6144
	ds_read_b128 v[228:231], v166 offset:7168
	global_load_lds_dwordx4 v136, s[56:57]
	s_add_i32 m0, s30, 0xe000
	s_nop 0
	global_load_lds_dwordx4 v138, s[56:57]
	s_waitcnt vmcnt(8)
	s_waitcnt lgkmcnt(0)
	s_barrier
	s_waitcnt lgkmcnt(0)
	v_mfma_f32_16x16x32_bf16 v[124:127], v[144:147], v[200:203], v[124:127]
	v_mfma_f32_16x16x32_bf16 v[116:119], v[172:175], v[200:203], v[116:119]
	v_mfma_f32_16x16x32_bf16 v[108:111], v[144:147], v[208:211], v[108:111]
	v_mfma_f32_16x16x32_bf16 v[100:103], v[172:175], v[208:211], v[100:103]
	v_mfma_f32_16x16x32_bf16 v[92:95], v[144:147], v[216:219], v[92:95]
	v_mfma_f32_16x16x32_bf16 v[84:87], v[172:175], v[216:219], v[84:87]
	v_mfma_f32_16x16x32_bf16 v[76:79], v[144:147], v[224:227], v[76:79]
	v_mfma_f32_16x16x32_bf16 v[68:71], v[172:175], v[224:227], v[68:71]
	v_mfma_f32_16x16x32_bf16 v[124:127], v[168:171], v[204:207], v[124:127]
	v_mfma_f32_16x16x32_bf16 v[116:119], v[176:179], v[204:207], v[116:119]
	v_mfma_f32_16x16x32_bf16 v[108:111], v[168:171], v[212:215], v[108:111]
	v_mfma_f32_16x16x32_bf16 v[100:103], v[176:179], v[212:215], v[100:103]
	v_mfma_f32_16x16x32_bf16 v[92:95], v[168:171], v[220:223], v[92:95]
	v_mfma_f32_16x16x32_bf16 v[84:87], v[176:179], v[220:223], v[84:87]
	v_mfma_f32_16x16x32_bf16 v[76:79], v[168:171], v[228:231], v[76:79]
	v_mfma_f32_16x16x32_bf16 v[68:71], v[176:179], v[228:231], v[68:71]
	v_mfma_f32_16x16x32_bf16 v[120:123], v[180:183], v[200:203], v[120:123]
	v_mfma_f32_16x16x32_bf16 v[112:115], v[188:191], v[200:203], v[112:115]
	v_mfma_f32_16x16x32_bf16 v[104:107], v[180:183], v[208:211], v[104:107]
	v_mfma_f32_16x16x32_bf16 v[96:99], v[188:191], v[208:211], v[96:99]
	v_mfma_f32_16x16x32_bf16 v[88:91], v[180:183], v[216:219], v[88:91]
	v_mfma_f32_16x16x32_bf16 v[80:83], v[188:191], v[216:219], v[80:83]
	v_mfma_f32_16x16x32_bf16 v[72:75], v[180:183], v[224:227], v[72:75]
	v_mfma_f32_16x16x32_bf16 v[64:67], v[188:191], v[224:227], v[64:67]
	v_mfma_f32_16x16x32_bf16 v[120:123], v[184:187], v[204:207], v[120:123]
	v_mfma_f32_16x16x32_bf16 v[112:115], v[196:199], v[204:207], v[112:115]
	v_mfma_f32_16x16x32_bf16 v[104:107], v[184:187], v[212:215], v[104:107]
	v_mfma_f32_16x16x32_bf16 v[96:99], v[196:199], v[212:215], v[96:99]
	v_mfma_f32_16x16x32_bf16 v[88:91], v[184:187], v[220:223], v[88:91]
	v_mfma_f32_16x16x32_bf16 v[80:83], v[196:199], v[220:223], v[80:83]
	v_mfma_f32_16x16x32_bf16 v[72:75], v[184:187], v[228:231], v[72:75]
	v_mfma_f32_16x16x32_bf16 v[64:67], v[196:199], v[228:231], v[64:67]
	s_barrier
	s_add_i32 s6, s67, s27
	v_lshl_add_u64 v[148:149], s[58:59], 0, v[132:133]
	s_mov_b32 m0, s6
	ds_read_b128 v[200:203], v166 offset:16384
	ds_read_b128 v[204:207], v166 offset:17408
	ds_read_b128 v[208:211], v166 offset:18432
	ds_read_b128 v[212:215], v166 offset:19456
	ds_read_b128 v[216:219], v166 offset:20480
	ds_read_b128 v[220:223], v166 offset:21504
	ds_read_b128 v[224:227], v166 offset:22528
	ds_read_b128 v[228:231], v166 offset:23552
	global_load_lds_dwordx4 v[148:149], off
	s_add_i32 m0, s6, 0x2000
	s_add_u32 s6, s58, 0x40000
	v_lshl_add_u64 v[232:233], s[58:59], 0, v[128:129]
	s_addc_u32 s7, s59, 0
	s_add_i32 s73, s68, s27
	global_load_lds_dwordx4 v[232:233], off
	s_mov_b32 m0, s73
	v_lshl_add_u64 v[236:237], s[60:61], 0, v[130:131]
	global_load_lds_dwordx4 v132, s[6:7]
	s_add_i32 m0, s73, 0x2000
	s_nop 0
	global_load_lds_dwordx4 v128, s[6:7]
	v_lshl_add_u64 v[234:235], s[60:61], 0, v[134:135]
	s_mov_b32 m0, s30
	s_nop 0
	global_load_lds_dwordx4 v[234:235], off
	s_mov_b32 m0, s31
	s_nop 0
	global_load_lds_dwordx4 v[236:237], off
	s_waitcnt vmcnt(8)
	s_waitcnt lgkmcnt(0)
	s_barrier
	s_waitcnt lgkmcnt(0)
	v_mfma_f32_16x16x32_bf16 v[60:63], v[144:147], v[200:203], v[60:63]
	v_mfma_f32_16x16x32_bf16 v[52:55], v[172:175], v[200:203], v[52:55]
	v_mfma_f32_16x16x32_bf16 v[44:47], v[144:147], v[208:211], v[44:47]
	v_mfma_f32_16x16x32_bf16 v[36:39], v[172:175], v[208:211], v[36:39]
	v_mfma_f32_16x16x32_bf16 v[28:31], v[144:147], v[216:219], v[28:31]
	v_mfma_f32_16x16x32_bf16 v[20:23], v[172:175], v[216:219], v[20:23]
	v_mfma_f32_16x16x32_bf16 v[12:15], v[144:147], v[224:227], v[12:15]
	v_mfma_f32_16x16x32_bf16 v[4:7], v[172:175], v[224:227], v[4:7]
	v_mfma_f32_16x16x32_bf16 v[60:63], v[168:171], v[204:207], v[60:63]
	v_mfma_f32_16x16x32_bf16 v[52:55], v[176:179], v[204:207], v[52:55]
	v_mfma_f32_16x16x32_bf16 v[44:47], v[168:171], v[212:215], v[44:47]
	v_mfma_f32_16x16x32_bf16 v[36:39], v[176:179], v[212:215], v[36:39]
	v_mfma_f32_16x16x32_bf16 v[28:31], v[168:171], v[220:223], v[28:31]
	v_mfma_f32_16x16x32_bf16 v[20:23], v[176:179], v[220:223], v[20:23]
	v_mfma_f32_16x16x32_bf16 v[12:15], v[168:171], v[228:231], v[12:15]
	v_mfma_f32_16x16x32_bf16 v[4:7], v[176:179], v[228:231], v[4:7]
	v_mfma_f32_16x16x32_bf16 v[56:59], v[180:183], v[200:203], v[56:59]
	v_mfma_f32_16x16x32_bf16 v[48:51], v[188:191], v[200:203], v[48:51]
	v_mfma_f32_16x16x32_bf16 v[40:43], v[180:183], v[208:211], v[40:43]
	v_mfma_f32_16x16x32_bf16 v[32:35], v[188:191], v[208:211], v[32:35]
	v_mfma_f32_16x16x32_bf16 v[24:27], v[180:183], v[216:219], v[24:27]
	v_mfma_f32_16x16x32_bf16 v[16:19], v[188:191], v[216:219], v[16:19]
	v_mfma_f32_16x16x32_bf16 v[8:11], v[180:183], v[224:227], v[8:11]
	v_mfma_f32_16x16x32_bf16 v[0:3], v[188:191], v[224:227], v[0:3]
	v_mfma_f32_16x16x32_bf16 v[56:59], v[184:187], v[204:207], v[56:59]
	v_mfma_f32_16x16x32_bf16 v[48:51], v[196:199], v[204:207], v[48:51]
	v_mfma_f32_16x16x32_bf16 v[40:43], v[184:187], v[212:215], v[40:43]
	v_mfma_f32_16x16x32_bf16 v[32:35], v[196:199], v[212:215], v[32:35]
	v_mfma_f32_16x16x32_bf16 v[24:27], v[184:187], v[220:223], v[24:27]
	v_mfma_f32_16x16x32_bf16 v[16:19], v[196:199], v[220:223], v[16:19]
	v_mfma_f32_16x16x32_bf16 v[8:11], v[184:187], v[228:231], v[8:11]
	v_mfma_f32_16x16x32_bf16 v[0:3], v[196:199], v[228:231], v[0:3]
	s_barrier
; #define PG8_STAGE(bufoff, gbase, voff) do { _Pragma("unroll") for (int _i = 0; _i < 2; ++_i) \
;         __builtin_amdgcn_global_load_lds((const unsigned*)((const char*)(gbase) + (voff)[_i]), (PG8_LAS unsigned*)(lds + (bufoff) + ldsw + _i * 8192), 16, 0, 0); } while (0)
; #define PG8_LDA(dst, b, h) do { _Pragma("unroll") for (int m = 0; m < 4; ++m) _Pragma("unroll") for (int k = 0; k < 2; ++k) dst[m][k] = *(const PG8_LAS bf16x8*)(lds + PG8_SA(b, h) + aoff + m * 2048 + k * 1024); } while (0)
; #define PG8_LDB(dst, b, h) do { _Pragma("unroll") for (int n = 0; n < 2; ++n) _Pragma("unroll") for (int k = 0; k < 2; ++k) dst[n][k] = *(const PG8_LAS bf16x8*)(lds + PG8_SB(b, h) + boff + n * 2048 + k * 1024); } while (0)
; #define PG8_MMA(ai, bj, At, Bt) do { __builtin_amdgcn_s_setprio(1); _Pragma("unroll") for (int m = 0; m < 4; ++m) _Pragma("unroll") for (int n = 0; n < 2; ++n) _Pragma("unroll") for (int k = 0; k < 2; ++k) \
;         acc[ai][bj][m][n] = __builtin_amdgcn_mfma_f32_16x16x32_bf16(Bt[n][k], At[m][k], acc[ai][bj][m][n], 0, 0, 0); __builtin_amdgcn_s_setprio(0); } while (0)
; #define PG8_WAIT_V(n) asm volatile("s_waitcnt vmcnt(" #n ")" ::: "memory")
; #define PG8_WAIT_L(n) asm volatile("s_waitcnt lgkmcnt(" #n ")" ::: "memory")
; #define PG8_BAR __builtin_amdgcn_s_barrier()
; #define PG8_SCHED __builtin_amdgcn_sched_barrier(0)
; template <class Epi, class Sched, bool ALIGN_EPI = false, bool SP2 = false>
; __device__ __forceinline__ void gemm_phase(PG8_LAS unsigned char* lds, const Gemm g, const Sched& S, const Epi& E) {
;     ...
;             PG8_LDB(B0, 1, 0); PG8_LDB(B1, 1, 1); PG8_SCHED; PG8_LDA(At, 1, 0); PG8_STAGE(PG8_SA(0, 1), a2 + hstep, voffA);
;             PG8_WAIT_V(8); PG8_WAIT_L(0); PG8_BAR; PG8_MMA(0, 0, At, B0); PG8_MMA(0, 1, At, B1); PG8_BAR; PG8_SCHED;
;             PG8_LDA(At, 1, 1); PG8_STAGE(PG8_SB(1, 0), b3, voffB); PG8_STAGE(PG8_SB(1, 1), b3 + hstep, voffB); PG8_STAGE(PG8_SA(1, 0), a3, voffA);
;             PG8_WAIT_V(8); PG8_WAIT_L(0); PG8_BAR; PG8_MMA(1, 0, At, B0); PG8_MMA(1, 1, At, B1); PG8_BAR; PG8_SCHED;
	s_add_i32 s73, 0, 0x18000
	v_add_u32_e32 v167, s73, v156
	s_add_i32 s79, 0, 0x1c000
	ds_read_b128 v[144:147], v167
	ds_read_b128 v[168:171], v167 offset:1024
	ds_read_b128 v[172:175], v167 offset:2048
	ds_read_b128 v[176:179], v167 offset:3072
	v_add_u32_e32 v167, s79, v156
	ds_read_b128 v[180:183], v167
	ds_read_b128 v[184:187], v167 offset:1024
	ds_read_b128 v[188:191], v167 offset:2048
	ds_read_b128 v[196:199], v167 offset:3072
	s_add_u32 s6, s60, 0x40000
	s_addc_u32 s7, s61, 0
	s_mov_b32 m0, s42
	ds_read_b128 v[200:203], v166 offset:32768
	ds_read_b128 v[204:207], v166 offset:33792
	ds_read_b128 v[208:211], v166 offset:34816
	ds_read_b128 v[212:215], v166 offset:35840
	ds_read_b128 v[216:219], v166 offset:36864
	ds_read_b128 v[220:223], v166 offset:37888
	ds_read_b128 v[224:227], v166 offset:38912
	ds_read_b128 v[228:231], v166 offset:39936
	global_load_lds_dwordx4 v134, s[6:7]
	s_mov_b32 m0, s43
	s_nop 0
	global_load_lds_dwordx4 v130, s[6:7]
	s_waitcnt vmcnt(8)
	s_waitcnt lgkmcnt(0)
	s_barrier
	s_waitcnt lgkmcnt(0)
	v_mfma_f32_16x16x32_bf16 v[124:127], v[144:147], v[200:203], v[124:127]
	v_mfma_f32_16x16x32_bf16 v[116:119], v[172:175], v[200:203], v[116:119]
	v_mfma_f32_16x16x32_bf16 v[108:111], v[144:147], v[208:211], v[108:111]
	v_mfma_f32_16x16x32_bf16 v[100:103], v[172:175], v[208:211], v[100:103]
	v_mfma_f32_16x16x32_bf16 v[92:95], v[144:147], v[216:219], v[92:95]
	v_mfma_f32_16x16x32_bf16 v[84:87], v[172:175], v[216:219], v[84:87]
	v_mfma_f32_16x16x32_bf16 v[76:79], v[144:147], v[224:227], v[76:79]
	v_mfma_f32_16x16x32_bf16 v[68:71], v[172:175], v[224:227], v[68:71]
	v_mfma_f32_16x16x32_bf16 v[124:127], v[168:171], v[204:207], v[124:127]
	v_mfma_f32_16x16x32_bf16 v[116:119], v[176:179], v[204:207], v[116:119]
	v_mfma_f32_16x16x32_bf16 v[108:111], v[168:171], v[212:215], v[108:111]
	v_mfma_f32_16x16x32_bf16 v[100:103], v[176:179], v[212:215], v[100:103]
	v_mfma_f32_16x16x32_bf16 v[92:95], v[168:171], v[220:223], v[92:95]
	v_mfma_f32_16x16x32_bf16 v[84:87], v[176:179], v[220:223], v[84:87]
	v_mfma_f32_16x16x32_bf16 v[76:79], v[168:171], v[228:231], v[76:79]
	v_mfma_f32_16x16x32_bf16 v[68:71], v[176:179], v[228:231], v[68:71]
	v_mfma_f32_16x16x32_bf16 v[120:123], v[180:183], v[200:203], v[120:123]
	v_mfma_f32_16x16x32_bf16 v[112:115], v[188:191], v[200:203], v[112:115]
	v_mfma_f32_16x16x32_bf16 v[104:107], v[180:183], v[208:211], v[104:107]
	v_mfma_f32_16x16x32_bf16 v[96:99], v[188:191], v[208:211], v[96:99]
	v_mfma_f32_16x16x32_bf16 v[88:91], v[180:183], v[216:219], v[88:91]
	v_mfma_f32_16x16x32_bf16 v[80:83], v[188:191], v[216:219], v[80:83]
	v_mfma_f32_16x16x32_bf16 v[72:75], v[180:183], v[224:227], v[72:75]
	v_mfma_f32_16x16x32_bf16 v[64:67], v[188:191], v[224:227], v[64:67]
	v_mfma_f32_16x16x32_bf16 v[120:123], v[184:187], v[204:207], v[120:123]
	v_mfma_f32_16x16x32_bf16 v[112:115], v[196:199], v[204:207], v[112:115]
	v_mfma_f32_16x16x32_bf16 v[104:107], v[184:187], v[212:215], v[104:107]
	v_mfma_f32_16x16x32_bf16 v[96:99], v[196:199], v[212:215], v[96:99]
	v_mfma_f32_16x16x32_bf16 v[88:91], v[184:187], v[220:223], v[88:91]
	v_mfma_f32_16x16x32_bf16 v[80:83], v[196:199], v[220:223], v[80:83]
	v_mfma_f32_16x16x32_bf16 v[72:75], v[184:187], v[228:231], v[72:75]
	v_mfma_f32_16x16x32_bf16 v[64:67], v[196:199], v[228:231], v[64:67]
	s_barrier
	s_add_i32 s6, s73, s27
	v_lshl_add_u64 v[148:149], v[148:149], 0, s[36:37]
	s_mov_b32 m0, s6
	ds_read_b128 v[200:203], v166 offset:49152
	ds_read_b128 v[204:207], v166 offset:50176
	ds_read_b128 v[208:211], v166 offset:51200
	ds_read_b128 v[212:215], v166 offset:52224
	ds_read_b128 v[216:219], v166 offset:53248
	ds_read_b128 v[220:223], v166 offset:54272
	ds_read_b128 v[224:227], v166 offset:55296
	ds_read_b128 v[228:231], v166 offset:56320
	global_load_lds_dwordx4 v[148:149], off
	s_add_i32 m0, s6, 0x2000
	s_add_u32 s6, s58, 0x40080
	v_lshl_add_u64 v[148:149], v[232:233], 0, s[36:37]
	s_addc_u32 s7, s59, 0
	s_add_i32 s58, s79, s27
	global_load_lds_dwordx4 v[148:149], off
	s_mov_b32 m0, s58
	s_nop 0
	global_load_lds_dwordx4 v132, s[6:7]
	s_add_i32 m0, s58, 0x2000
	s_nop 0
	global_load_lds_dwordx4 v128, s[6:7]
	v_lshl_add_u64 v[148:149], v[234:235], 0, s[36:37]
	s_mov_b32 m0, s44
	s_nop 0
	global_load_lds_dwordx4 v[148:149], off
	v_lshl_add_u64 v[148:149], v[236:237], 0, s[36:37]
	s_mov_b32 m0, s45
	s_nop 0
	global_load_lds_dwordx4 v[148:149], off
	s_waitcnt vmcnt(8)
	s_waitcnt lgkmcnt(0)
	s_barrier
	s_waitcnt lgkmcnt(0)
	v_mfma_f32_16x16x32_bf16 v[60:63], v[144:147], v[200:203], v[60:63]
	v_mfma_f32_16x16x32_bf16 v[52:55], v[172:175], v[200:203], v[52:55]
	v_mfma_f32_16x16x32_bf16 v[44:47], v[144:147], v[208:211], v[44:47]
	v_mfma_f32_16x16x32_bf16 v[36:39], v[172:175], v[208:211], v[36:39]
	v_mfma_f32_16x16x32_bf16 v[28:31], v[144:147], v[216:219], v[28:31]
	v_mfma_f32_16x16x32_bf16 v[20:23], v[172:175], v[216:219], v[20:23]
	v_mfma_f32_16x16x32_bf16 v[12:15], v[144:147], v[224:227], v[12:15]
	v_mfma_f32_16x16x32_bf16 v[4:7], v[172:175], v[224:227], v[4:7]
	v_mfma_f32_16x16x32_bf16 v[60:63], v[168:171], v[204:207], v[60:63]
	v_mfma_f32_16x16x32_bf16 v[52:55], v[176:179], v[204:207], v[52:55]
	v_mfma_f32_16x16x32_bf16 v[44:47], v[168:171], v[212:215], v[44:47]
	v_mfma_f32_16x16x32_bf16 v[36:39], v[176:179], v[212:215], v[36:39]
	v_mfma_f32_16x16x32_bf16 v[28:31], v[168:171], v[220:223], v[28:31]
	v_mfma_f32_16x16x32_bf16 v[20:23], v[176:179], v[220:223], v[20:23]
	v_mfma_f32_16x16x32_bf16 v[12:15], v[168:171], v[228:231], v[12:15]
	v_mfma_f32_16x16x32_bf16 v[4:7], v[176:179], v[228:231], v[4:7]
	v_mfma_f32_16x16x32_bf16 v[56:59], v[180:183], v[200:203], v[56:59]
	v_mfma_f32_16x16x32_bf16 v[48:51], v[188:191], v[200:203], v[48:51]
	v_mfma_f32_16x16x32_bf16 v[40:43], v[180:183], v[208:211], v[40:43]
	v_mfma_f32_16x16x32_bf16 v[32:35], v[188:191], v[208:211], v[32:35]
	v_mfma_f32_16x16x32_bf16 v[24:27], v[180:183], v[216:219], v[24:27]
	v_mfma_f32_16x16x32_bf16 v[16:19], v[188:191], v[216:219], v[16:19]
	v_mfma_f32_16x16x32_bf16 v[8:11], v[180:183], v[224:227], v[8:11]
	v_mfma_f32_16x16x32_bf16 v[0:3], v[188:191], v[224:227], v[0:3]
	v_mfma_f32_16x16x32_bf16 v[56:59], v[184:187], v[204:207], v[56:59]
	v_mfma_f32_16x16x32_bf16 v[48:51], v[196:199], v[204:207], v[48:51]
	v_mfma_f32_16x16x32_bf16 v[40:43], v[184:187], v[212:215], v[40:43]
	v_mfma_f32_16x16x32_bf16 v[32:35], v[196:199], v[212:215], v[32:35]
	v_mfma_f32_16x16x32_bf16 v[24:27], v[184:187], v[220:223], v[24:27]
	v_mfma_f32_16x16x32_bf16 v[16:19], v[196:199], v[220:223], v[16:19]
	v_mfma_f32_16x16x32_bf16 v[8:11], v[184:187], v[228:231], v[8:11]
	v_mfma_f32_16x16x32_bf16 v[0:3], v[196:199], v[228:231], v[0:3]
	s_barrier
	s_add_i32 s72, s72, 2
	s_add_u32 s56, s56, 0x100
	s_addc_u32 s57, s57, 0
	s_add_u32 s78, s78, 0x100
	s_addc_u32 s33, s33, 0
	s_cmp_gt_u32 s72, 13
	s_cbranch_scc0 .LBB0_901
	s_and_b64 vcc, exec, s[38:39]
	s_cbranch_vccz .LBB0_904
	s_barrier

; #define PG8_STAGE(bufoff, gbase, voff) do { _Pragma("unroll") for (int _i = 0; _i < 2; ++_i) \
;         __builtin_amdgcn_global_load_lds((const unsigned*)((const char*)(gbase) + (voff)[_i]), (PG8_LAS unsigned*)(lds + (bufoff) + ldsw + _i * 8192), 16, 0, 0); } while (0)
; #define PG8_LDA(dst, b, h) do { _Pragma("unroll") for (int m = 0; m < 4; ++m) _Pragma("unroll") for (int k = 0; k < 2; ++k) dst[m][k] = *(const PG8_LAS bf16x8*)(lds + PG8_SA(b, h) + aoff + m * 2048 + k * 1024); } while (0)
; #define PG8_LDB(dst, b, h) do { _Pragma("unroll") for (int n = 0; n < 2; ++n) _Pragma("unroll") for (int k = 0; k < 2; ++k) dst[n][k] = *(const PG8_LAS bf16x8*)(lds + PG8_SB(b, h) + boff + n * 2048 + k * 1024); } while (0)
; #define PG8_MMA(ai, bj, At, Bt) do { __builtin_amdgcn_s_setprio(1); _Pragma("unroll") for (int m = 0; m < 4; ++m) _Pragma("unroll") for (int n = 0; n < 2; ++n) _Pragma("unroll") for (int k = 0; k < 2; ++k) \
;         acc[ai][bj][m][n] = __builtin_amdgcn_mfma_f32_16x16x32_bf16(Bt[n][k], At[m][k], acc[ai][bj][m][n], 0, 0, 0); __builtin_amdgcn_s_setprio(0); } while (0)
; #define PG8_WAIT_V(n) asm volatile("s_waitcnt vmcnt(" #n ")" ::: "memory")
; #define PG8_BAR __builtin_amdgcn_s_barrier()
; template <class Epi, class Sched, bool ALIGN_EPI = false, bool SP2 = false>
; __device__ __forceinline__ void gemm_phase(PG8_LAS unsigned char* lds, const Gemm g, const Sched& S, const Epi& E) {
;     ...
;         for (int t = 0; t < nt; t += 2) {
;             const bool last = (t == nt - 2);
;             const char* a1 = cA + (size_t)(t + 1) * kstep;
;             const char* a2 = last ? nA : cA + (size_t)(t + 2) * kstep; const char* b2 = last ? nB : cB + (size_t)(t + 2) * kstep;
;             const char* a3 = a2 + kstep; const char* b3 = b2 + kstep;
;             if (last && has_next) S.a_ready(nxt);
;             if constexpr (SP2) {
;             PG8_LDB(B0, 0, 0); PG8_LDB(B1, 0, 1); PG8_SCHED; PG8_LDA(At, 0, 0); PG8_STAGE(PG8_SA(1, 1), a1 + hstep, voffA);
;             PG8_WAIT_V(8); PG8_WAIT_L(0); PG8_BAR; PG8_MMA(0, 0, At, B0); PG8_MMA(0, 1, At, B1); PG8_BAR; PG8_SCHED;
;             PG8_LDA(At, 0, 1); PG8_STAGE(PG8_SB(0, 0), b2, voffB); PG8_STAGE(PG8_SB(0, 1), b2 + hstep, voffB); PG8_STAGE(PG8_SA(0, 0), a2, voffA);
;             PG8_WAIT_V(8); PG8_WAIT_L(0); PG8_BAR; PG8_MMA(1, 0, At, B0); PG8_MMA(1, 1, At, B1); PG8_BAR; PG8_SCHED;
.LBB0_1014:
	ds_read_b128 v[144:147], v158
	ds_read_b128 v[168:171], v158 offset:1024
	ds_read_b128 v[172:175], v158 offset:2048
	ds_read_b128 v[176:179], v158 offset:3072
	ds_read_b128 v[180:183], v159
	ds_read_b128 v[184:187], v159 offset:1024
	ds_read_b128 v[188:191], v159 offset:2048
	ds_read_b128 v[196:199], v159 offset:3072
	s_add_u32 s58, s56, 0x100
	s_addc_u32 s59, s57, 0
	s_cmp_eq_u32 s72, 40
	s_cselect_b32 s79, s51, s59
	s_cselect_b32 s78, s50, s58
	s_cselect_b32 s61, s55, s80
	s_cselect_b32 s60, s54, s33
	s_add_i32 m0, s45, 0xc000
	ds_read_b128 v[200:203], v163
	ds_read_b128 v[204:207], v163 offset:1024
	ds_read_b128 v[208:211], v163 offset:2048
	ds_read_b128 v[212:215], v163 offset:3072
	ds_read_b128 v[216:219], v163 offset:4096
	ds_read_b128 v[220:223], v163 offset:5120
	ds_read_b128 v[224:227], v163 offset:6144
	ds_read_b128 v[228:231], v163 offset:7168
	global_load_lds_dwordx4 v136, s[56:57]
	s_add_i32 m0, s45, 0xe000
	s_nop 0
	global_load_lds_dwordx4 v138, s[56:57]
	s_waitcnt vmcnt(8)
	s_waitcnt lgkmcnt(0)
	s_barrier
	s_waitcnt lgkmcnt(0)
	v_mfma_f32_16x16x32_bf16 v[124:127], v[144:147], v[200:203], v[124:127]
	v_mfma_f32_16x16x32_bf16 v[120:123], v[172:175], v[200:203], v[120:123]
	v_mfma_f32_16x16x32_bf16 v[108:111], v[144:147], v[208:211], v[108:111]
	v_mfma_f32_16x16x32_bf16 v[104:107], v[172:175], v[208:211], v[104:107]
	v_mfma_f32_16x16x32_bf16 v[92:95], v[144:147], v[216:219], v[92:95]
	v_mfma_f32_16x16x32_bf16 v[88:91], v[172:175], v[216:219], v[88:91]
	v_mfma_f32_16x16x32_bf16 v[76:79], v[144:147], v[224:227], v[76:79]
	v_mfma_f32_16x16x32_bf16 v[72:75], v[172:175], v[224:227], v[72:75]
	v_mfma_f32_16x16x32_bf16 v[124:127], v[168:171], v[204:207], v[124:127]
	v_mfma_f32_16x16x32_bf16 v[120:123], v[176:179], v[204:207], v[120:123]
	v_mfma_f32_16x16x32_bf16 v[108:111], v[168:171], v[212:215], v[108:111]
	v_mfma_f32_16x16x32_bf16 v[104:107], v[176:179], v[212:215], v[104:107]
	v_mfma_f32_16x16x32_bf16 v[92:95], v[168:171], v[220:223], v[92:95]
	v_mfma_f32_16x16x32_bf16 v[88:91], v[176:179], v[220:223], v[88:91]
	v_mfma_f32_16x16x32_bf16 v[76:79], v[168:171], v[228:231], v[76:79]
	v_mfma_f32_16x16x32_bf16 v[72:75], v[176:179], v[228:231], v[72:75]
	v_mfma_f32_16x16x32_bf16 v[116:119], v[180:183], v[200:203], v[116:119]
	v_mfma_f32_16x16x32_bf16 v[112:115], v[188:191], v[200:203], v[112:115]
	v_mfma_f32_16x16x32_bf16 v[100:103], v[180:183], v[208:211], v[100:103]
	v_mfma_f32_16x16x32_bf16 v[96:99], v[188:191], v[208:211], v[96:99]
	v_mfma_f32_16x16x32_bf16 v[84:87], v[180:183], v[216:219], v[84:87]
	v_mfma_f32_16x16x32_bf16 v[80:83], v[188:191], v[216:219], v[80:83]
	v_mfma_f32_16x16x32_bf16 v[68:71], v[180:183], v[224:227], v[68:71]
	v_mfma_f32_16x16x32_bf16 v[64:67], v[188:191], v[224:227], v[64:67]
	v_mfma_f32_16x16x32_bf16 v[116:119], v[184:187], v[204:207], v[116:119]
	v_mfma_f32_16x16x32_bf16 v[112:115], v[196:199], v[204:207], v[112:115]
	v_mfma_f32_16x16x32_bf16 v[100:103], v[184:187], v[212:215], v[100:103]
	v_mfma_f32_16x16x32_bf16 v[96:99], v[196:199], v[212:215], v[96:99]
	v_mfma_f32_16x16x32_bf16 v[84:87], v[184:187], v[220:223], v[84:87]
	v_mfma_f32_16x16x32_bf16 v[80:83], v[196:199], v[220:223], v[80:83]
	v_mfma_f32_16x16x32_bf16 v[68:71], v[184:187], v[228:231], v[68:71]
	v_mfma_f32_16x16x32_bf16 v[64:67], v[196:199], v[228:231], v[64:67]
	s_barrier
	s_add_i32 s6, s26, s44
	v_lshl_add_u64 v[148:149], s[60:61], 0, v[130:131]
	s_mov_b32 m0, s6
	ds_read_b128 v[200:203], v163 offset:16384
	ds_read_b128 v[204:207], v163 offset:17408
	ds_read_b128 v[208:211], v163 offset:18432
	ds_read_b128 v[212:215], v163 offset:19456
	ds_read_b128 v[216:219], v163 offset:20480
	ds_read_b128 v[220:223], v163 offset:21504
	ds_read_b128 v[224:227], v163 offset:22528
	ds_read_b128 v[228:231], v163 offset:23552
	global_load_lds_dwordx4 v[148:149], off
	s_add_i32 m0, s6, 0x2000
	s_add_u32 s6, s60, 0xb0000
	v_lshl_add_u64 v[232:233], s[60:61], 0, v[134:135]
	s_addc_u32 s7, s61, 0
	s_add_i32 s56, s74, s44
	global_load_lds_dwordx4 v[232:233], off
	s_mov_b32 m0, s56
	v_lshl_add_u64 v[236:237], s[78:79], 0, v[132:133]
	global_load_lds_dwordx4 v130, s[6:7]
	s_add_i32 m0, s56, 0x2000
	s_nop 0
	global_load_lds_dwordx4 v134, s[6:7]
	v_lshl_add_u64 v[234:235], s[78:79], 0, v[128:129]
	s_mov_b32 m0, s45
	s_nop 0
	global_load_lds_dwordx4 v[234:235], off
	s_mov_b32 m0, s67
	s_nop 0
	global_load_lds_dwordx4 v[236:237], off
	s_waitcnt vmcnt(8)
	s_waitcnt lgkmcnt(0)
	s_barrier
	s_waitcnt lgkmcnt(0)
	v_mfma_f32_16x16x32_bf16 v[60:63], v[144:147], v[200:203], v[60:63]
	v_mfma_f32_16x16x32_bf16 v[56:59], v[172:175], v[200:203], v[56:59]
	v_mfma_f32_16x16x32_bf16 v[44:47], v[144:147], v[208:211], v[44:47]
	v_mfma_f32_16x16x32_bf16 v[40:43], v[172:175], v[208:211], v[40:43]
	v_mfma_f32_16x16x32_bf16 v[28:31], v[144:147], v[216:219], v[28:31]
	v_mfma_f32_16x16x32_bf16 v[24:27], v[172:175], v[216:219], v[24:27]
	v_mfma_f32_16x16x32_bf16 v[12:15], v[144:147], v[224:227], v[12:15]
	v_mfma_f32_16x16x32_bf16 v[8:11], v[172:175], v[224:227], v[8:11]
	v_mfma_f32_16x16x32_bf16 v[60:63], v[168:171], v[204:207], v[60:63]
	v_mfma_f32_16x16x32_bf16 v[56:59], v[176:179], v[204:207], v[56:59]
	v_mfma_f32_16x16x32_bf16 v[44:47], v[168:171], v[212:215], v[44:47]
	v_mfma_f32_16x16x32_bf16 v[40:43], v[176:179], v[212:215], v[40:43]
	v_mfma_f32_16x16x32_bf16 v[28:31], v[168:171], v[220:223], v[28:31]
	v_mfma_f32_16x16x32_bf16 v[24:27], v[176:179], v[220:223], v[24:27]
	v_mfma_f32_16x16x32_bf16 v[12:15], v[168:171], v[228:231], v[12:15]
	v_mfma_f32_16x16x32_bf16 v[8:11], v[176:179], v[228:231], v[8:11]
	v_mfma_f32_16x16x32_bf16 v[52:55], v[180:183], v[200:203], v[52:55]
	v_mfma_f32_16x16x32_bf16 v[48:51], v[188:191], v[200:203], v[48:51]
	v_mfma_f32_16x16x32_bf16 v[36:39], v[180:183], v[208:211], v[36:39]
	v_mfma_f32_16x16x32_bf16 v[32:35], v[188:191], v[208:211], v[32:35]
	v_mfma_f32_16x16x32_bf16 v[20:23], v[180:183], v[216:219], v[20:23]
	v_mfma_f32_16x16x32_bf16 v[16:19], v[188:191], v[216:219], v[16:19]
	v_mfma_f32_16x16x32_bf16 v[4:7], v[180:183], v[224:227], v[4:7]
	v_mfma_f32_16x16x32_bf16 v[0:3], v[188:191], v[224:227], v[0:3]
	v_mfma_f32_16x16x32_bf16 v[52:55], v[184:187], v[204:207], v[52:55]
	v_mfma_f32_16x16x32_bf16 v[48:51], v[196:199], v[204:207], v[48:51]
	v_mfma_f32_16x16x32_bf16 v[36:39], v[184:187], v[212:215], v[36:39]
	v_mfma_f32_16x16x32_bf16 v[32:35], v[196:199], v[212:215], v[32:35]
	v_mfma_f32_16x16x32_bf16 v[20:23], v[184:187], v[220:223], v[20:23]
	v_mfma_f32_16x16x32_bf16 v[16:19], v[196:199], v[220:223], v[16:19]
	v_mfma_f32_16x16x32_bf16 v[4:7], v[184:187], v[228:231], v[4:7]
	v_mfma_f32_16x16x32_bf16 v[0:3], v[196:199], v[228:231], v[0:3]
	s_barrier
; #define PG8_STAGE(bufoff, gbase, voff) do { _Pragma("unroll") for (int _i = 0; _i < 2; ++_i) \
;         __builtin_amdgcn_global_load_lds((const unsigned*)((const char*)(gbase) + (voff)[_i]), (PG8_LAS unsigned*)(lds + (bufoff) + ldsw + _i * 8192), 16, 0, 0); } while (0)
; #define PG8_LDA(dst, b, h) do { _Pragma("unroll") for (int m = 0; m < 4; ++m) _Pragma("unroll") for (int k = 0; k < 2; ++k) dst[m][k] = *(const PG8_LAS bf16x8*)(lds + PG8_SA(b, h) + aoff + m * 2048 + k * 1024); } while (0)
; #define PG8_LDB(dst, b, h) do { _Pragma("unroll") for (int n = 0; n < 2; ++n) _Pragma("unroll") for (int k = 0; k < 2; ++k) dst[n][k] = *(const PG8_LAS bf16x8*)(lds + PG8_SB(b, h) + boff + n * 2048 + k * 1024); } while (0)
; #define PG8_MMA(ai, bj, At, Bt) do { __builtin_amdgcn_s_setprio(1); _Pragma("unroll") for (int m = 0; m < 4; ++m) _Pragma("unroll") for (int n = 0; n < 2; ++n) _Pragma("unroll") for (int k = 0; k < 2; ++k) \
;         acc[ai][bj][m][n] = __builtin_amdgcn_mfma_f32_16x16x32_bf16(Bt[n][k], At[m][k], acc[ai][bj][m][n], 0, 0, 0); __builtin_amdgcn_s_setprio(0); } while (0)
; #define PG8_WAIT_V(n) asm volatile("s_waitcnt vmcnt(" #n ")" ::: "memory")
; #define PG8_WAIT_L(n) asm volatile("s_waitcnt lgkmcnt(" #n ")" ::: "memory")
; #define PG8_BAR __builtin_amdgcn_s_barrier()
; #define PG8_SCHED __builtin_amdgcn_sched_barrier(0)
; template <class Epi, class Sched, bool ALIGN_EPI = false, bool SP2 = false>
; __device__ __forceinline__ void gemm_phase(PG8_LAS unsigned char* lds, const Gemm g, const Sched& S, const Epi& E) {
;     ...
;             PG8_LDB(B0, 1, 0); PG8_LDB(B1, 1, 1); PG8_SCHED; PG8_LDA(At, 1, 0); PG8_STAGE(PG8_SA(0, 1), a2 + hstep, voffA);
;             PG8_WAIT_V(8); PG8_WAIT_L(0); PG8_BAR; PG8_MMA(0, 0, At, B0); PG8_MMA(0, 1, At, B1); PG8_BAR; PG8_SCHED;
;             PG8_LDA(At, 1, 1); PG8_STAGE(PG8_SB(1, 0), b3, voffB); PG8_STAGE(PG8_SB(1, 1), b3 + hstep, voffB); PG8_STAGE(PG8_SA(1, 0), a3, voffA);
;             PG8_WAIT_V(8); PG8_WAIT_L(0); PG8_BAR; PG8_MMA(1, 0, At, B0); PG8_MMA(1, 1, At, B1); PG8_BAR; PG8_SCHED;
	s_add_i32 s56, 0, 0x18000
	v_add_u32_e32 v167, s56, v156
	s_add_i32 s57, 0, 0x1c000
	ds_read_b128 v[144:147], v167
	ds_read_b128 v[168:171], v167 offset:1024
	ds_read_b128 v[172:175], v167 offset:2048
	ds_read_b128 v[176:179], v167 offset:3072
	v_add_u32_e32 v167, s57, v156
	ds_read_b128 v[180:183], v167
	ds_read_b128 v[184:187], v167 offset:1024
	ds_read_b128 v[188:191], v167 offset:2048
	ds_read_b128 v[196:199], v167 offset:3072
	s_add_u32 s6, s78, 0xb0000
	s_addc_u32 s7, s79, 0
	s_mov_b32 m0, s76
	ds_read_b128 v[200:203], v163 offset:32768
	ds_read_b128 v[204:207], v163 offset:33792
	ds_read_b128 v[208:211], v163 offset:34816
	ds_read_b128 v[212:215], v163 offset:35840
	ds_read_b128 v[216:219], v163 offset:36864
	ds_read_b128 v[220:223], v163 offset:37888
	ds_read_b128 v[224:227], v163 offset:38912
	ds_read_b128 v[228:231], v163 offset:39936
	global_load_lds_dwordx4 v128, s[6:7]
	s_mov_b32 m0, s77
	s_nop 0
	global_load_lds_dwordx4 v132, s[6:7]
	s_waitcnt vmcnt(8)
	s_waitcnt lgkmcnt(0)
	s_barrier
	s_waitcnt lgkmcnt(0)
	v_mfma_f32_16x16x32_bf16 v[124:127], v[144:147], v[200:203], v[124:127]
	v_mfma_f32_16x16x32_bf16 v[120:123], v[172:175], v[200:203], v[120:123]
	v_mfma_f32_16x16x32_bf16 v[108:111], v[144:147], v[208:211], v[108:111]
	v_mfma_f32_16x16x32_bf16 v[104:107], v[172:175], v[208:211], v[104:107]
	v_mfma_f32_16x16x32_bf16 v[92:95], v[144:147], v[216:219], v[92:95]
	v_mfma_f32_16x16x32_bf16 v[88:91], v[172:175], v[216:219], v[88:91]
	v_mfma_f32_16x16x32_bf16 v[76:79], v[144:147], v[224:227], v[76:79]
	v_mfma_f32_16x16x32_bf16 v[72:75], v[172:175], v[224:227], v[72:75]
	v_mfma_f32_16x16x32_bf16 v[124:127], v[168:171], v[204:207], v[124:127]
	v_mfma_f32_16x16x32_bf16 v[120:123], v[176:179], v[204:207], v[120:123]
	v_mfma_f32_16x16x32_bf16 v[108:111], v[168:171], v[212:215], v[108:111]
	v_mfma_f32_16x16x32_bf16 v[104:107], v[176:179], v[212:215], v[104:107]
	v_mfma_f32_16x16x32_bf16 v[92:95], v[168:171], v[220:223], v[92:95]
	v_mfma_f32_16x16x32_bf16 v[88:91], v[176:179], v[220:223], v[88:91]
	v_mfma_f32_16x16x32_bf16 v[76:79], v[168:171], v[228:231], v[76:79]
	v_mfma_f32_16x16x32_bf16 v[72:75], v[176:179], v[228:231], v[72:75]
	v_mfma_f32_16x16x32_bf16 v[116:119], v[180:183], v[200:203], v[116:119]
	v_mfma_f32_16x16x32_bf16 v[112:115], v[188:191], v[200:203], v[112:115]
	v_mfma_f32_16x16x32_bf16 v[100:103], v[180:183], v[208:211], v[100:103]
	v_mfma_f32_16x16x32_bf16 v[96:99], v[188:191], v[208:211], v[96:99]
	v_mfma_f32_16x16x32_bf16 v[84:87], v[180:183], v[216:219], v[84:87]
	v_mfma_f32_16x16x32_bf16 v[80:83], v[188:191], v[216:219], v[80:83]
	v_mfma_f32_16x16x32_bf16 v[68:71], v[180:183], v[224:227], v[68:71]
	v_mfma_f32_16x16x32_bf16 v[64:67], v[188:191], v[224:227], v[64:67]
	v_mfma_f32_16x16x32_bf16 v[116:119], v[184:187], v[204:207], v[116:119]
	v_mfma_f32_16x16x32_bf16 v[112:115], v[196:199], v[204:207], v[112:115]
	v_mfma_f32_16x16x32_bf16 v[100:103], v[184:187], v[212:215], v[100:103]
	v_mfma_f32_16x16x32_bf16 v[96:99], v[196:199], v[212:215], v[96:99]
	v_mfma_f32_16x16x32_bf16 v[84:87], v[184:187], v[220:223], v[84:87]
	v_mfma_f32_16x16x32_bf16 v[80:83], v[196:199], v[220:223], v[80:83]
	v_mfma_f32_16x16x32_bf16 v[68:71], v[184:187], v[228:231], v[68:71]
	v_mfma_f32_16x16x32_bf16 v[64:67], v[196:199], v[228:231], v[64:67]
	s_barrier
	s_add_i32 s6, s56, s44
	v_lshl_add_u64 v[148:149], v[148:149], 0, s[40:41]
	s_mov_b32 m0, s6
	ds_read_b128 v[200:203], v163 offset:49152
	ds_read_b128 v[204:207], v163 offset:50176
	ds_read_b128 v[208:211], v163 offset:51200
	ds_read_b128 v[212:215], v163 offset:52224
	ds_read_b128 v[216:219], v163 offset:53248
	ds_read_b128 v[220:223], v163 offset:54272
	ds_read_b128 v[224:227], v163 offset:55296
	ds_read_b128 v[228:231], v163 offset:56320
	global_load_lds_dwordx4 v[148:149], off
	s_add_i32 m0, s6, 0x2000
	s_add_u32 s6, s60, 0xb0080
	v_lshl_add_u64 v[148:149], v[232:233], 0, s[40:41]
	s_addc_u32 s7, s61, 0
	s_add_i32 s56, s57, s44
	global_load_lds_dwordx4 v[148:149], off
	s_mov_b32 m0, s56
	s_nop 0
	global_load_lds_dwordx4 v130, s[6:7]
	s_add_i32 m0, s56, 0x2000
	s_nop 0
	global_load_lds_dwordx4 v134, s[6:7]
	v_lshl_add_u64 v[148:149], v[234:235], 0, s[40:41]
	s_mov_b32 m0, s31
	s_nop 0
	global_load_lds_dwordx4 v[148:149], off
	v_lshl_add_u64 v[148:149], v[236:237], 0, s[40:41]
	s_mov_b32 m0, s4
	s_nop 0
	global_load_lds_dwordx4 v[148:149], off
	s_waitcnt vmcnt(8)
	s_waitcnt lgkmcnt(0)
	s_barrier
	s_waitcnt lgkmcnt(0)
	v_mfma_f32_16x16x32_bf16 v[60:63], v[144:147], v[200:203], v[60:63]
	v_mfma_f32_16x16x32_bf16 v[56:59], v[172:175], v[200:203], v[56:59]
	v_mfma_f32_16x16x32_bf16 v[44:47], v[144:147], v[208:211], v[44:47]
	v_mfma_f32_16x16x32_bf16 v[40:43], v[172:175], v[208:211], v[40:43]
	v_mfma_f32_16x16x32_bf16 v[28:31], v[144:147], v[216:219], v[28:31]
	v_mfma_f32_16x16x32_bf16 v[24:27], v[172:175], v[216:219], v[24:27]
	v_mfma_f32_16x16x32_bf16 v[12:15], v[144:147], v[224:227], v[12:15]
	v_mfma_f32_16x16x32_bf16 v[8:11], v[172:175], v[224:227], v[8:11]
	v_mfma_f32_16x16x32_bf16 v[60:63], v[168:171], v[204:207], v[60:63]
	v_mfma_f32_16x16x32_bf16 v[56:59], v[176:179], v[204:207], v[56:59]
	v_mfma_f32_16x16x32_bf16 v[44:47], v[168:171], v[212:215], v[44:47]
	v_mfma_f32_16x16x32_bf16 v[40:43], v[176:179], v[212:215], v[40:43]
	v_mfma_f32_16x16x32_bf16 v[28:31], v[168:171], v[220:223], v[28:31]
	v_mfma_f32_16x16x32_bf16 v[24:27], v[176:179], v[220:223], v[24:27]
	v_mfma_f32_16x16x32_bf16 v[12:15], v[168:171], v[228:231], v[12:15]
	v_mfma_f32_16x16x32_bf16 v[8:11], v[176:179], v[228:231], v[8:11]
	v_mfma_f32_16x16x32_bf16 v[52:55], v[180:183], v[200:203], v[52:55]
	v_mfma_f32_16x16x32_bf16 v[48:51], v[188:191], v[200:203], v[48:51]
	v_mfma_f32_16x16x32_bf16 v[36:39], v[180:183], v[208:211], v[36:39]
	v_mfma_f32_16x16x32_bf16 v[32:35], v[188:191], v[208:211], v[32:35]
	v_mfma_f32_16x16x32_bf16 v[20:23], v[180:183], v[216:219], v[20:23]
	v_mfma_f32_16x16x32_bf16 v[16:19], v[188:191], v[216:219], v[16:19]
	v_mfma_f32_16x16x32_bf16 v[4:7], v[180:183], v[224:227], v[4:7]
	v_mfma_f32_16x16x32_bf16 v[0:3], v[188:191], v[224:227], v[0:3]
	v_mfma_f32_16x16x32_bf16 v[52:55], v[184:187], v[204:207], v[52:55]
	v_mfma_f32_16x16x32_bf16 v[48:51], v[196:199], v[204:207], v[48:51]
	v_mfma_f32_16x16x32_bf16 v[36:39], v[184:187], v[212:215], v[36:39]
	v_mfma_f32_16x16x32_bf16 v[32:35], v[196:199], v[212:215], v[32:35]
	v_mfma_f32_16x16x32_bf16 v[20:23], v[184:187], v[220:223], v[20:23]
	v_mfma_f32_16x16x32_bf16 v[16:19], v[196:199], v[220:223], v[16:19]
	v_mfma_f32_16x16x32_bf16 v[4:7], v[184:187], v[228:231], v[4:7]
	v_mfma_f32_16x16x32_bf16 v[0:3], v[196:199], v[228:231], v[0:3]
	s_barrier
	s_add_i32 s72, s72, 2
	s_add_u32 s33, s33, 0x100
	s_addc_u32 s80, s80, 0
	s_cmp_gt_u32 s72, 41
	s_mov_b64 s[56:57], s[58:59]
	s_cbranch_scc0 .LBB0_1014
	s_and_b64 vcc, exec, s[52:53]
	s_cbranch_vccz .LBB0_1017
	s_barrier

; #define PG8_STAGE(bufoff, gbase, voff) do { _Pragma("unroll") for (int _i = 0; _i < 2; ++_i) \
;         __builtin_amdgcn_global_load_lds((const unsigned*)((const char*)(gbase) + (voff)[_i]), (PG8_LAS unsigned*)(lds + (bufoff) + ldsw + _i * 8192), 16, 0, 0); } while (0)
; #define PG8_LDA(dst, b, h) do { _Pragma("unroll") for (int m = 0; m < 4; ++m) _Pragma("unroll") for (int k = 0; k < 2; ++k) dst[m][k] = *(const PG8_LAS bf16x8*)(lds + PG8_SA(b, h) + aoff + m * 2048 + k * 1024); } while (0)
; #define PG8_LDB(dst, b, h) do { _Pragma("unroll") for (int n = 0; n < 2; ++n) _Pragma("unroll") for (int k = 0; k < 2; ++k) dst[n][k] = *(const PG8_LAS bf16x8*)(lds + PG8_SB(b, h) + boff + n * 2048 + k * 1024); } while (0)
; #define PG8_MMA(ai, bj, At, Bt) do { __builtin_amdgcn_s_setprio(1); _Pragma("unroll") for (int m = 0; m < 4; ++m) _Pragma("unroll") for (int n = 0; n < 2; ++n) _Pragma("unroll") for (int k = 0; k < 2; ++k) \
;         acc[ai][bj][m][n] = __builtin_amdgcn_mfma_f32_16x16x32_bf16(Bt[n][k], At[m][k], acc[ai][bj][m][n], 0, 0, 0); __builtin_amdgcn_s_setprio(0); } while (0)
; #define PG8_WAIT_V(n) asm volatile("s_waitcnt vmcnt(" #n ")" ::: "memory")
; #define PG8_BAR __builtin_amdgcn_s_barrier()
; template <class Epi, class Sched, bool ALIGN_EPI = false, bool SP2 = false>
; __device__ __forceinline__ void gemm_phase(PG8_LAS unsigned char* lds, const Gemm g, const Sched& S, const Epi& E) {
;     ...
;         for (int t = 0; t < nt; t += 2) {
;             const bool last = (t == nt - 2);
;             const char* a1 = cA + (size_t)(t + 1) * kstep;
;             const char* a2 = last ? nA : cA + (size_t)(t + 2) * kstep; const char* b2 = last ? nB : cB + (size_t)(t + 2) * kstep;
;             const char* a3 = a2 + kstep; const char* b3 = b2 + kstep;
;             if (last && has_next) S.a_ready(nxt);
;             if constexpr (SP2) {
;             PG8_LDB(B0, 0, 0); PG8_LDB(B1, 0, 1); PG8_SCHED; PG8_LDA(At, 0, 0); PG8_STAGE(PG8_SA(1, 1), a1 + hstep, voffA);
;             PG8_WAIT_V(8); PG8_WAIT_L(0); PG8_BAR; PG8_MMA(0, 0, At, B0); PG8_MMA(0, 1, At, B1); PG8_BAR; PG8_SCHED;
;             PG8_LDA(At, 0, 1); PG8_STAGE(PG8_SB(0, 0), b2, voffB); PG8_STAGE(PG8_SB(0, 1), b2 + hstep, voffB); PG8_STAGE(PG8_SA(0, 0), a2, voffA);
;             PG8_WAIT_V(8); PG8_WAIT_L(0); PG8_BAR; PG8_MMA(1, 0, At, B0); PG8_MMA(1, 1, At, B1); PG8_BAR; PG8_SCHED;
.LBB0_1392:
	ds_read_b128 v[144:147], v157
	ds_read_b128 v[166:169], v157 offset:1024
	ds_read_b128 v[170:173], v157 offset:2048
	ds_read_b128 v[174:177], v157 offset:3072
	ds_read_b128 v[178:181], v158
	ds_read_b128 v[182:185], v158 offset:1024
	ds_read_b128 v[186:189], v158 offset:2048
	ds_read_b128 v[196:199], v158 offset:3072
	s_add_u32 s6, s58, 0xfffc0080
	s_addc_u32 s7, s59, -1
	s_cmp_eq_u32 s72, 12
	s_cselect_b32 s79, s51, s7
	s_cselect_b32 s78, s75, s6
	s_cselect_b32 s61, s49, s33
	s_cselect_b32 s60, s76, s77
	v_lshl_add_u64 v[190:191], s[58:59], 0, v[136:137]
	s_add_i32 m0, s30, 0xc000
	ds_read_b128 v[200:203], v159
	ds_read_b128 v[204:207], v159 offset:1024
	ds_read_b128 v[208:211], v159 offset:2048
	ds_read_b128 v[212:215], v159 offset:3072
	ds_read_b128 v[216:219], v159 offset:4096
	ds_read_b128 v[220:223], v159 offset:5120
	ds_read_b128 v[224:227], v159 offset:6144
	ds_read_b128 v[228:231], v159 offset:7168
	global_load_lds_dwordx4 v[190:191], off
	v_lshl_add_u64 v[190:191], s[58:59], 0, v[138:139]
	s_add_i32 m0, s30, 0xe000
	s_nop 0
	global_load_lds_dwordx4 v[190:191], off
	s_waitcnt vmcnt(8)
	s_waitcnt lgkmcnt(0)
	s_barrier
	s_waitcnt lgkmcnt(0)
	v_mfma_f32_16x16x32_bf16 v[124:127], v[144:147], v[200:203], v[124:127]
	v_mfma_f32_16x16x32_bf16 v[120:123], v[170:173], v[200:203], v[120:123]
	v_mfma_f32_16x16x32_bf16 v[112:115], v[144:147], v[208:211], v[112:115]
	v_mfma_f32_16x16x32_bf16 v[104:107], v[170:173], v[208:211], v[104:107]
	v_mfma_f32_16x16x32_bf16 v[96:99], v[144:147], v[216:219], v[96:99]
	v_mfma_f32_16x16x32_bf16 v[88:91], v[170:173], v[216:219], v[88:91]
	v_mfma_f32_16x16x32_bf16 v[80:83], v[144:147], v[224:227], v[80:83]
	v_mfma_f32_16x16x32_bf16 v[72:75], v[170:173], v[224:227], v[72:75]
	v_mfma_f32_16x16x32_bf16 v[124:127], v[166:169], v[204:207], v[124:127]
	v_mfma_f32_16x16x32_bf16 v[120:123], v[174:177], v[204:207], v[120:123]
	v_mfma_f32_16x16x32_bf16 v[112:115], v[166:169], v[212:215], v[112:115]
	v_mfma_f32_16x16x32_bf16 v[104:107], v[174:177], v[212:215], v[104:107]
	v_mfma_f32_16x16x32_bf16 v[96:99], v[166:169], v[220:223], v[96:99]
	v_mfma_f32_16x16x32_bf16 v[88:91], v[174:177], v[220:223], v[88:91]
	v_mfma_f32_16x16x32_bf16 v[80:83], v[166:169], v[228:231], v[80:83]
	v_mfma_f32_16x16x32_bf16 v[72:75], v[174:177], v[228:231], v[72:75]
	v_mfma_f32_16x16x32_bf16 v[116:119], v[178:181], v[200:203], v[116:119]
	v_mfma_f32_16x16x32_bf16 v[108:111], v[186:189], v[200:203], v[108:111]
	v_mfma_f32_16x16x32_bf16 v[100:103], v[178:181], v[208:211], v[100:103]
	v_mfma_f32_16x16x32_bf16 v[92:95], v[186:189], v[208:211], v[92:95]
	v_mfma_f32_16x16x32_bf16 v[84:87], v[178:181], v[216:219], v[84:87]
	v_mfma_f32_16x16x32_bf16 v[76:79], v[186:189], v[216:219], v[76:79]
	v_mfma_f32_16x16x32_bf16 v[68:71], v[178:181], v[224:227], v[68:71]
	v_mfma_f32_16x16x32_bf16 v[64:67], v[186:189], v[224:227], v[64:67]
	v_mfma_f32_16x16x32_bf16 v[116:119], v[182:185], v[204:207], v[116:119]
	v_mfma_f32_16x16x32_bf16 v[108:111], v[196:199], v[204:207], v[108:111]
	v_mfma_f32_16x16x32_bf16 v[100:103], v[182:185], v[212:215], v[100:103]
	v_mfma_f32_16x16x32_bf16 v[92:95], v[196:199], v[212:215], v[92:95]
	v_mfma_f32_16x16x32_bf16 v[84:87], v[182:185], v[220:223], v[84:87]
	v_mfma_f32_16x16x32_bf16 v[76:79], v[196:199], v[220:223], v[76:79]
	v_mfma_f32_16x16x32_bf16 v[68:71], v[182:185], v[228:231], v[68:71]
	v_mfma_f32_16x16x32_bf16 v[64:67], v[196:199], v[228:231], v[64:67]
	s_barrier
	s_add_i32 s6, s57, s27
	v_lshl_add_u64 v[190:191], s[60:61], 0, v[130:131]
	s_mov_b32 m0, s6
	ds_read_b128 v[200:203], v159 offset:16384
	ds_read_b128 v[204:207], v159 offset:17408
	ds_read_b128 v[208:211], v159 offset:18432
	ds_read_b128 v[212:215], v159 offset:19456
	ds_read_b128 v[216:219], v159 offset:20480
	ds_read_b128 v[220:223], v159 offset:21504
	ds_read_b128 v[224:227], v159 offset:22528
	ds_read_b128 v[228:231], v159 offset:23552
	global_load_lds_dwordx4 v[190:191], off
	s_add_i32 m0, s6, 0x2000
	s_add_u32 s6, s60, 0x40000
	v_lshl_add_u64 v[232:233], s[60:61], 0, v[134:135]
	s_addc_u32 s7, s61, 0
	s_add_i32 s73, s67, s27
	global_load_lds_dwordx4 v[232:233], off
	s_mov_b32 m0, s73
	v_lshl_add_u64 v[236:237], s[78:79], 0, v[132:133]
	global_load_lds_dwordx4 v130, s[6:7]
	s_add_i32 m0, s73, 0x2000
	s_nop 0
	global_load_lds_dwordx4 v134, s[6:7]
	v_lshl_add_u64 v[234:235], s[78:79], 0, v[128:129]
	s_mov_b32 m0, s30
	s_nop 0
	global_load_lds_dwordx4 v[234:235], off
	s_mov_b32 m0, s31
	s_nop 0
	global_load_lds_dwordx4 v[236:237], off
	s_waitcnt vmcnt(8)
	s_waitcnt lgkmcnt(0)
	s_barrier
; #define PG8_STAGE(bufoff, gbase, voff) do { _Pragma("unroll") for (int _i = 0; _i < 2; ++_i) \
;         __builtin_amdgcn_global_load_lds((const unsigned*)((const char*)(gbase) + (voff)[_i]), (PG8_LAS unsigned*)(lds + (bufoff) + ldsw + _i * 8192), 16, 0, 0); } while (0)
; #define PG8_LDA(dst, b, h) do { _Pragma("unroll") for (int m = 0; m < 4; ++m) _Pragma("unroll") for (int k = 0; k < 2; ++k) dst[m][k] = *(const PG8_LAS bf16x8*)(lds + PG8_SA(b, h) + aoff + m * 2048 + k * 1024); } while (0)
; #define PG8_LDB(dst, b, h) do { _Pragma("unroll") for (int n = 0; n < 2; ++n) _Pragma("unroll") for (int k = 0; k < 2; ++k) dst[n][k] = *(const PG8_LAS bf16x8*)(lds + PG8_SB(b, h) + boff + n * 2048 + k * 1024); } while (0)
; #define PG8_MMA(ai, bj, At, Bt) do { __builtin_amdgcn_s_setprio(1); _Pragma("unroll") for (int m = 0; m < 4; ++m) _Pragma("unroll") for (int n = 0; n < 2; ++n) _Pragma("unroll") for (int k = 0; k < 2; ++k) \
;         acc[ai][bj][m][n] = __builtin_amdgcn_mfma_f32_16x16x32_bf16(Bt[n][k], At[m][k], acc[ai][bj][m][n], 0, 0, 0); __builtin_amdgcn_s_setprio(0); } while (0)
; #define PG8_WAIT_V(n) asm volatile("s_waitcnt vmcnt(" #n ")" ::: "memory")
; #define PG8_WAIT_L(n) asm volatile("s_waitcnt lgkmcnt(" #n ")" ::: "memory")
; #define PG8_BAR __builtin_amdgcn_s_barrier()
; #define PG8_SCHED __builtin_amdgcn_sched_barrier(0)
; template <class Epi, class Sched, bool ALIGN_EPI = false, bool SP2 = false>
; __device__ __forceinline__ void gemm_phase(PG8_LAS unsigned char* lds, const Gemm g, const Sched& S, const Epi& E) {
;     ...
;             PG8_WAIT_V(8); PG8_WAIT_L(0); PG8_BAR; PG8_MMA(1, 0, At, B0); PG8_MMA(1, 1, At, B1); PG8_BAR; PG8_SCHED;
;             PG8_LDB(B0, 1, 0); PG8_LDB(B1, 1, 1); PG8_SCHED; PG8_LDA(At, 1, 0); PG8_STAGE(PG8_SA(0, 1), a2 + hstep, voffA);
;             PG8_WAIT_V(8); PG8_WAIT_L(0); PG8_BAR; PG8_MMA(0, 0, At, B0); PG8_MMA(0, 1, At, B1); PG8_BAR; PG8_SCHED;
	s_waitcnt lgkmcnt(0)
	v_mfma_f32_16x16x32_bf16 v[60:63], v[144:147], v[200:203], v[60:63]
	v_mfma_f32_16x16x32_bf16 v[56:59], v[170:173], v[200:203], v[56:59]
	v_mfma_f32_16x16x32_bf16 v[52:55], v[144:147], v[208:211], v[52:55]
	v_mfma_f32_16x16x32_bf16 v[40:43], v[170:173], v[208:211], v[40:43]
	v_mfma_f32_16x16x32_bf16 v[36:39], v[144:147], v[216:219], v[36:39]
	v_mfma_f32_16x16x32_bf16 v[24:27], v[170:173], v[216:219], v[24:27]
	v_mfma_f32_16x16x32_bf16 v[20:23], v[144:147], v[224:227], v[20:23]
	v_mfma_f32_16x16x32_bf16 v[8:11], v[170:173], v[224:227], v[8:11]
	v_mfma_f32_16x16x32_bf16 v[60:63], v[166:169], v[204:207], v[60:63]
	v_mfma_f32_16x16x32_bf16 v[56:59], v[174:177], v[204:207], v[56:59]
	v_mfma_f32_16x16x32_bf16 v[52:55], v[166:169], v[212:215], v[52:55]
	v_mfma_f32_16x16x32_bf16 v[40:43], v[174:177], v[212:215], v[40:43]
	v_mfma_f32_16x16x32_bf16 v[36:39], v[166:169], v[220:223], v[36:39]
	v_mfma_f32_16x16x32_bf16 v[24:27], v[174:177], v[220:223], v[24:27]
	v_mfma_f32_16x16x32_bf16 v[20:23], v[166:169], v[228:231], v[20:23]
	v_mfma_f32_16x16x32_bf16 v[8:11], v[174:177], v[228:231], v[8:11]
	v_mfma_f32_16x16x32_bf16 v[48:51], v[178:181], v[200:203], v[48:51]
	v_mfma_f32_16x16x32_bf16 v[44:47], v[186:189], v[200:203], v[44:47]
	v_mfma_f32_16x16x32_bf16 v[32:35], v[178:181], v[208:211], v[32:35]
	v_mfma_f32_16x16x32_bf16 v[28:31], v[186:189], v[208:211], v[28:31]
	v_mfma_f32_16x16x32_bf16 v[16:19], v[178:181], v[216:219], v[16:19]
	v_mfma_f32_16x16x32_bf16 v[12:15], v[186:189], v[216:219], v[12:15]
	v_mfma_f32_16x16x32_bf16 v[4:7], v[178:181], v[224:227], v[4:7]
	v_mfma_f32_16x16x32_bf16 v[0:3], v[186:189], v[224:227], v[0:3]
	v_mfma_f32_16x16x32_bf16 v[48:51], v[182:185], v[204:207], v[48:51]
	v_mfma_f32_16x16x32_bf16 v[44:47], v[196:199], v[204:207], v[44:47]
	v_mfma_f32_16x16x32_bf16 v[32:35], v[182:185], v[212:215], v[32:35]
	v_mfma_f32_16x16x32_bf16 v[28:31], v[196:199], v[212:215], v[28:31]
	v_mfma_f32_16x16x32_bf16 v[16:19], v[182:185], v[220:223], v[16:19]
	v_mfma_f32_16x16x32_bf16 v[12:15], v[196:199], v[220:223], v[12:15]
	v_mfma_f32_16x16x32_bf16 v[4:7], v[182:185], v[228:231], v[4:7]
	v_mfma_f32_16x16x32_bf16 v[0:3], v[196:199], v[228:231], v[0:3]
	s_barrier
	s_add_i32 s73, 0, 0x18000
	v_add_u32_e32 v163, s73, v149
	s_add_i32 s80, 0, 0x1c000
	ds_read_b128 v[144:147], v163
	ds_read_b128 v[166:169], v163 offset:1024
	ds_read_b128 v[170:173], v163 offset:2048
	ds_read_b128 v[174:177], v163 offset:3072
	v_add_u32_e32 v163, s80, v149
	ds_read_b128 v[178:181], v163
	ds_read_b128 v[182:185], v163 offset:1024
	ds_read_b128 v[186:189], v163 offset:2048
	ds_read_b128 v[196:199], v163 offset:3072
	s_add_u32 s6, s78, 0x40000
	s_addc_u32 s7, s79, 0
	s_mov_b32 m0, s42
	ds_read_b128 v[200:203], v159 offset:32768
	ds_read_b128 v[204:207], v159 offset:33792
	ds_read_b128 v[208:211], v159 offset:34816
	ds_read_b128 v[212:215], v159 offset:35840
	ds_read_b128 v[216:219], v159 offset:36864
	ds_read_b128 v[220:223], v159 offset:37888
	ds_read_b128 v[224:227], v159 offset:38912
	ds_read_b128 v[228:231], v159 offset:39936
	global_load_lds_dwordx4 v128, s[6:7]
	s_mov_b32 m0, s43
	s_nop 0
	global_load_lds_dwordx4 v132, s[6:7]
	s_waitcnt vmcnt(8)
	s_waitcnt lgkmcnt(0)
	s_barrier
	s_waitcnt lgkmcnt(0)
	v_mfma_f32_16x16x32_bf16 v[124:127], v[144:147], v[200:203], v[124:127]
	v_mfma_f32_16x16x32_bf16 v[120:123], v[170:173], v[200:203], v[120:123]
	v_mfma_f32_16x16x32_bf16 v[112:115], v[144:147], v[208:211], v[112:115]
	v_mfma_f32_16x16x32_bf16 v[104:107], v[170:173], v[208:211], v[104:107]
	v_mfma_f32_16x16x32_bf16 v[96:99], v[144:147], v[216:219], v[96:99]
	v_mfma_f32_16x16x32_bf16 v[88:91], v[170:173], v[216:219], v[88:91]
	v_mfma_f32_16x16x32_bf16 v[80:83], v[144:147], v[224:227], v[80:83]
	v_mfma_f32_16x16x32_bf16 v[72:75], v[170:173], v[224:227], v[72:75]
	v_mfma_f32_16x16x32_bf16 v[124:127], v[166:169], v[204:207], v[124:127]
	v_mfma_f32_16x16x32_bf16 v[120:123], v[174:177], v[204:207], v[120:123]
	v_mfma_f32_16x16x32_bf16 v[112:115], v[166:169], v[212:215], v[112:115]
	v_mfma_f32_16x16x32_bf16 v[104:107], v[174:177], v[212:215], v[104:107]
	v_mfma_f32_16x16x32_bf16 v[96:99], v[166:169], v[220:223], v[96:99]
	v_mfma_f32_16x16x32_bf16 v[88:91], v[174:177], v[220:223], v[88:91]
	v_mfma_f32_16x16x32_bf16 v[80:83], v[166:169], v[228:231], v[80:83]
	v_mfma_f32_16x16x32_bf16 v[72:75], v[174:177], v[228:231], v[72:75]
	v_mfma_f32_16x16x32_bf16 v[116:119], v[178:181], v[200:203], v[116:119]
	v_mfma_f32_16x16x32_bf16 v[108:111], v[186:189], v[200:203], v[108:111]
	v_mfma_f32_16x16x32_bf16 v[100:103], v[178:181], v[208:211], v[100:103]
	v_mfma_f32_16x16x32_bf16 v[92:95], v[186:189], v[208:211], v[92:95]
	v_mfma_f32_16x16x32_bf16 v[84:87], v[178:181], v[216:219], v[84:87]
	v_mfma_f32_16x16x32_bf16 v[76:79], v[186:189], v[216:219], v[76:79]
	v_mfma_f32_16x16x32_bf16 v[68:71], v[178:181], v[224:227], v[68:71]
	v_mfma_f32_16x16x32_bf16 v[64:67], v[186:189], v[224:227], v[64:67]
	v_mfma_f32_16x16x32_bf16 v[116:119], v[182:185], v[204:207], v[116:119]
	v_mfma_f32_16x16x32_bf16 v[108:111], v[196:199], v[204:207], v[108:111]
	v_mfma_f32_16x16x32_bf16 v[100:103], v[182:185], v[212:215], v[100:103]
	v_mfma_f32_16x16x32_bf16 v[92:95], v[196:199], v[212:215], v[92:95]
	v_mfma_f32_16x16x32_bf16 v[84:87], v[182:185], v[220:223], v[84:87]
	v_mfma_f32_16x16x32_bf16 v[76:79], v[196:199], v[220:223], v[76:79]
	v_mfma_f32_16x16x32_bf16 v[68:71], v[182:185], v[228:231], v[68:71]
	v_mfma_f32_16x16x32_bf16 v[64:67], v[196:199], v[228:231], v[64:67]
	s_barrier
; #define PG8_STAGE(bufoff, gbase, voff) do { _Pragma("unroll") for (int _i = 0; _i < 2; ++_i) \
;         __builtin_amdgcn_global_load_lds((const unsigned*)((const char*)(gbase) + (voff)[_i]), (PG8_LAS unsigned*)(lds + (bufoff) + ldsw + _i * 8192), 16, 0, 0); } while (0)
; #define PG8_LDA(dst, b, h) do { _Pragma("unroll") for (int m = 0; m < 4; ++m) _Pragma("unroll") for (int k = 0; k < 2; ++k) dst[m][k] = *(const PG8_LAS bf16x8*)(lds + PG8_SA(b, h) + aoff + m * 2048 + k * 1024); } while (0)
; #define PG8_MMA(ai, bj, At, Bt) do { __builtin_amdgcn_s_setprio(1); _Pragma("unroll") for (int m = 0; m < 4; ++m) _Pragma("unroll") for (int n = 0; n < 2; ++n) _Pragma("unroll") for (int k = 0; k < 2; ++k) \
;         acc[ai][bj][m][n] = __builtin_amdgcn_mfma_f32_16x16x32_bf16(Bt[n][k], At[m][k], acc[ai][bj][m][n], 0, 0, 0); __builtin_amdgcn_s_setprio(0); } while (0)
; #define PG8_WAIT_V(n) asm volatile("s_waitcnt vmcnt(" #n ")" ::: "memory")
; #define PG8_WAIT_L(n) asm volatile("s_waitcnt lgkmcnt(" #n ")" ::: "memory")
; #define PG8_BAR __builtin_amdgcn_s_barrier()
; #define PG8_SCHED __builtin_amdgcn_sched_barrier(0)
; template <class Epi, class Sched, bool ALIGN_EPI = false, bool SP2 = false>
; __device__ __forceinline__ void gemm_phase(PG8_LAS unsigned char* lds, const Gemm g, const Sched& S, const Epi& E) {
;     ...
;         for (int t = 0; t < nt; t += 2) {
;             const bool last = (t == nt - 2);
;             const char* a1 = cA + (size_t)(t + 1) * kstep;
;             const char* a2 = last ? nA : cA + (size_t)(t + 2) * kstep; const char* b2 = last ? nB : cB + (size_t)(t + 2) * kstep;
;     ...
;             PG8_LDA(At, 1, 1); PG8_STAGE(PG8_SB(1, 0), b3, voffB); PG8_STAGE(PG8_SB(1, 1), b3 + hstep, voffB); PG8_STAGE(PG8_SA(1, 0), a3, voffA);
;             PG8_WAIT_V(8); PG8_WAIT_L(0); PG8_BAR; PG8_MMA(1, 0, At, B0); PG8_MMA(1, 1, At, B1); PG8_BAR; PG8_SCHED;
	s_add_i32 s6, s73, s27
	v_lshl_add_u64 v[190:191], v[190:191], 0, s[38:39]
	s_mov_b32 m0, s6
	ds_read_b128 v[200:203], v159 offset:49152
	ds_read_b128 v[204:207], v159 offset:50176
	ds_read_b128 v[208:211], v159 offset:51200
	ds_read_b128 v[212:215], v159 offset:52224
	ds_read_b128 v[216:219], v159 offset:53248
	ds_read_b128 v[220:223], v159 offset:54272
	ds_read_b128 v[224:227], v159 offset:55296
	ds_read_b128 v[228:231], v159 offset:56320
	global_load_lds_dwordx4 v[190:191], off
	s_add_i32 m0, s6, 0x2000
	s_add_u32 s6, s60, 0x40080
	v_lshl_add_u64 v[190:191], v[232:233], 0, s[38:39]
	s_addc_u32 s7, s61, 0
	s_add_i32 s60, s80, s27
	global_load_lds_dwordx4 v[190:191], off
	v_lshl_add_u64 v[190:191], s[6:7], 0, v[130:131]
	s_mov_b32 m0, s60
	s_nop 0
	global_load_lds_dwordx4 v[190:191], off
	v_lshl_add_u64 v[190:191], s[6:7], 0, v[134:135]
	s_add_i32 m0, s60, 0x2000
	s_nop 0
	global_load_lds_dwordx4 v[190:191], off
	v_lshl_add_u64 v[190:191], v[234:235], 0, s[38:39]
	s_mov_b32 m0, s44
	s_nop 0
	global_load_lds_dwordx4 v[190:191], off
	v_lshl_add_u64 v[190:191], v[236:237], 0, s[38:39]
	s_mov_b32 m0, s45
	s_nop 0
	global_load_lds_dwordx4 v[190:191], off
	s_waitcnt vmcnt(8)
	s_waitcnt lgkmcnt(0)
	s_barrier
	s_waitcnt lgkmcnt(0)
	v_mfma_f32_16x16x32_bf16 v[60:63], v[144:147], v[200:203], v[60:63]
	v_mfma_f32_16x16x32_bf16 v[56:59], v[170:173], v[200:203], v[56:59]
	v_mfma_f32_16x16x32_bf16 v[52:55], v[144:147], v[208:211], v[52:55]
	v_mfma_f32_16x16x32_bf16 v[40:43], v[170:173], v[208:211], v[40:43]
	v_mfma_f32_16x16x32_bf16 v[36:39], v[144:147], v[216:219], v[36:39]
	v_mfma_f32_16x16x32_bf16 v[24:27], v[170:173], v[216:219], v[24:27]
	v_mfma_f32_16x16x32_bf16 v[20:23], v[144:147], v[224:227], v[20:23]
	v_mfma_f32_16x16x32_bf16 v[8:11], v[170:173], v[224:227], v[8:11]
	v_mfma_f32_16x16x32_bf16 v[60:63], v[166:169], v[204:207], v[60:63]
	v_mfma_f32_16x16x32_bf16 v[56:59], v[174:177], v[204:207], v[56:59]
	v_mfma_f32_16x16x32_bf16 v[52:55], v[166:169], v[212:215], v[52:55]
	v_mfma_f32_16x16x32_bf16 v[40:43], v[174:177], v[212:215], v[40:43]
	v_mfma_f32_16x16x32_bf16 v[36:39], v[166:169], v[220:223], v[36:39]
	v_mfma_f32_16x16x32_bf16 v[24:27], v[174:177], v[220:223], v[24:27]
	v_mfma_f32_16x16x32_bf16 v[20:23], v[166:169], v[228:231], v[20:23]
	v_mfma_f32_16x16x32_bf16 v[8:11], v[174:177], v[228:231], v[8:11]
	v_mfma_f32_16x16x32_bf16 v[48:51], v[178:181], v[200:203], v[48:51]
	v_mfma_f32_16x16x32_bf16 v[44:47], v[186:189], v[200:203], v[44:47]
	v_mfma_f32_16x16x32_bf16 v[32:35], v[178:181], v[208:211], v[32:35]
	v_mfma_f32_16x16x32_bf16 v[28:31], v[186:189], v[208:211], v[28:31]
	v_mfma_f32_16x16x32_bf16 v[16:19], v[178:181], v[216:219], v[16:19]
	v_mfma_f32_16x16x32_bf16 v[12:15], v[186:189], v[216:219], v[12:15]
	v_mfma_f32_16x16x32_bf16 v[4:7], v[178:181], v[224:227], v[4:7]
	v_mfma_f32_16x16x32_bf16 v[0:3], v[186:189], v[224:227], v[0:3]
	v_mfma_f32_16x16x32_bf16 v[48:51], v[182:185], v[204:207], v[48:51]
	v_mfma_f32_16x16x32_bf16 v[44:47], v[196:199], v[204:207], v[44:47]
	v_mfma_f32_16x16x32_bf16 v[32:35], v[182:185], v[212:215], v[32:35]
	v_mfma_f32_16x16x32_bf16 v[28:31], v[196:199], v[212:215], v[28:31]
	v_mfma_f32_16x16x32_bf16 v[16:19], v[182:185], v[220:223], v[16:19]
	v_mfma_f32_16x16x32_bf16 v[12:15], v[196:199], v[220:223], v[12:15]
	v_mfma_f32_16x16x32_bf16 v[4:7], v[182:185], v[228:231], v[4:7]
	v_mfma_f32_16x16x32_bf16 v[0:3], v[196:199], v[228:231], v[0:3]
	s_barrier
	s_add_i32 s72, s72, 2
	s_add_u32 s58, s58, 0x100
	s_addc_u32 s59, s59, 0
	s_add_u32 s77, s77, 0x100
	s_addc_u32 s33, s33, 0
	s_cmp_gt_u32 s72, 13
	s_cbranch_scc0 .LBB0_1392
	s_and_b64 vcc, exec, s[40:41]
	s_cbranch_vccz .LBB0_1395
	s_barrier

; #define PG8_STAGE(bufoff, gbase, voff) do { _Pragma("unroll") for (int _i = 0; _i < 2; ++_i) \
;         __builtin_amdgcn_global_load_lds((const unsigned*)((const char*)(gbase) + (voff)[_i]), (PG8_LAS unsigned*)(lds + (bufoff) + ldsw + _i * 8192), 16, 0, 0); } while (0)
; #define PG8_LDA(dst, b, h) do { _Pragma("unroll") for (int m = 0; m < 4; ++m) _Pragma("unroll") for (int k = 0; k < 2; ++k) dst[m][k] = *(const PG8_LAS bf16x8*)(lds + PG8_SA(b, h) + aoff + m * 2048 + k * 1024); } while (0)
; #define PG8_LDB(dst, b, h) do { _Pragma("unroll") for (int n = 0; n < 2; ++n) _Pragma("unroll") for (int k = 0; k < 2; ++k) dst[n][k] = *(const PG8_LAS bf16x8*)(lds + PG8_SB(b, h) + boff + n * 2048 + k * 1024); } while (0)
; #define PG8_MMA(ai, bj, At, Bt) do { __builtin_amdgcn_s_setprio(1); _Pragma("unroll") for (int m = 0; m < 4; ++m) _Pragma("unroll") for (int n = 0; n < 2; ++n) _Pragma("unroll") for (int k = 0; k < 2; ++k) \
;         acc[ai][bj][m][n] = __builtin_amdgcn_mfma_f32_16x16x32_bf16(Bt[n][k], At[m][k], acc[ai][bj][m][n], 0, 0, 0); __builtin_amdgcn_s_setprio(0); } while (0)
; #define PG8_WAIT_V(n) asm volatile("s_waitcnt vmcnt(" #n ")" ::: "memory")
; #define PG8_BAR __builtin_amdgcn_s_barrier()
; template <class Epi, class Sched, bool ALIGN_EPI = false, bool SP2 = false>
; __device__ __forceinline__ void gemm_phase(PG8_LAS unsigned char* lds, const Gemm g, const Sched& S, const Epi& E) {
;     ...
;         for (int t = 0; t < nt; t += 2) {
;             const bool last = (t == nt - 2);
;             const char* a1 = cA + (size_t)(t + 1) * kstep;
;             const char* a2 = last ? nA : cA + (size_t)(t + 2) * kstep; const char* b2 = last ? nB : cB + (size_t)(t + 2) * kstep;
;             const char* a3 = a2 + kstep; const char* b3 = b2 + kstep;
;             if (last && has_next) S.a_ready(nxt);
;             if constexpr (SP2) {
;             PG8_LDB(B0, 0, 0); PG8_LDB(B1, 0, 1); PG8_SCHED; PG8_LDA(At, 0, 0); PG8_STAGE(PG8_SA(1, 1), a1 + hstep, voffA);
;             PG8_WAIT_V(8); PG8_WAIT_L(0); PG8_BAR; PG8_MMA(0, 0, At, B0); PG8_MMA(0, 1, At, B1); PG8_BAR; PG8_SCHED;
;             PG8_LDA(At, 0, 1); PG8_STAGE(PG8_SB(0, 0), b2, voffB); PG8_STAGE(PG8_SB(0, 1), b2 + hstep, voffB); PG8_STAGE(PG8_SA(0, 0), a2, voffA);
;             PG8_WAIT_V(8); PG8_WAIT_L(0); PG8_BAR; PG8_MMA(1, 0, At, B0); PG8_MMA(1, 1, At, B1); PG8_BAR; PG8_SCHED;
.LBB0_1617:
	ds_read_b128 v[32:35], v191
	ds_read_b128 v[36:39], v191 offset:1024
	ds_read_b128 v[48:51], v191 offset:2048
	ds_read_b128 v[52:55], v191 offset:3072
	ds_read_b128 v[128:131], v195
	ds_read_b128 v[148:151], v195 offset:1024
	ds_read_b128 v[152:155], v195 offset:2048
	ds_read_b128 v[180:183], v195 offset:3072
	s_add_u32 s6, s56, 0xfffc0080
	s_addc_u32 s7, s57, -1
	s_cmp_eq_u32 s69, 12
	s_cselect_b32 s61, s26, s7
	s_cselect_b32 s60, s29, s6
	s_cselect_b32 s59, s49, s33
	s_cselect_b32 s58, s51, s68
	s_add_i32 m0, s78, 0xc000
	ds_read_b128 v[184:187], v198
	ds_read_b128 v[200:203], v198 offset:1024
	ds_read_b128 v[204:207], v198 offset:2048
	ds_read_b128 v[208:211], v198 offset:3072
	ds_read_b128 v[212:215], v198 offset:4096
	ds_read_b128 v[216:219], v198 offset:5120
	ds_read_b128 v[220:223], v198 offset:6144
	ds_read_b128 v[224:227], v198 offset:7168
	global_load_lds_dwordx4 v172, s[56:57]
	s_add_i32 m0, s78, 0xe000
	s_nop 0
	global_load_lds_dwordx4 v174, s[56:57]
	s_waitcnt vmcnt(8)
	s_waitcnt lgkmcnt(0)
	s_barrier
	s_waitcnt lgkmcnt(0)
	v_mfma_f32_16x16x32_bf16 v[144:147], v[32:35], v[184:187], v[144:147]
	v_mfma_f32_16x16x32_bf16 v[140:143], v[48:51], v[184:187], v[140:143]
	v_mfma_f32_16x16x32_bf16 v[124:127], v[32:35], v[204:207], v[124:127]
	v_mfma_f32_16x16x32_bf16 v[120:123], v[48:51], v[204:207], v[120:123]
	v_mfma_f32_16x16x32_bf16 v[108:111], v[32:35], v[212:215], v[108:111]
	v_mfma_f32_16x16x32_bf16 v[104:107], v[48:51], v[212:215], v[104:107]
	v_mfma_f32_16x16x32_bf16 v[92:95], v[32:35], v[220:223], v[92:95]
	v_mfma_f32_16x16x32_bf16 v[88:91], v[48:51], v[220:223], v[88:91]
	v_mfma_f32_16x16x32_bf16 v[144:147], v[36:39], v[200:203], v[144:147]
	v_mfma_f32_16x16x32_bf16 v[140:143], v[52:55], v[200:203], v[140:143]
	v_mfma_f32_16x16x32_bf16 v[124:127], v[36:39], v[208:211], v[124:127]
	v_mfma_f32_16x16x32_bf16 v[120:123], v[52:55], v[208:211], v[120:123]
	v_mfma_f32_16x16x32_bf16 v[108:111], v[36:39], v[216:219], v[108:111]
	v_mfma_f32_16x16x32_bf16 v[104:107], v[52:55], v[216:219], v[104:107]
	v_mfma_f32_16x16x32_bf16 v[92:95], v[36:39], v[224:227], v[92:95]
	v_mfma_f32_16x16x32_bf16 v[88:91], v[52:55], v[224:227], v[88:91]
	v_mfma_f32_16x16x32_bf16 v[136:139], v[128:131], v[184:187], v[136:139]
	v_mfma_f32_16x16x32_bf16 v[132:135], v[152:155], v[184:187], v[132:135]
	v_mfma_f32_16x16x32_bf16 v[116:119], v[128:131], v[204:207], v[116:119]
	v_mfma_f32_16x16x32_bf16 v[112:115], v[152:155], v[204:207], v[112:115]
	v_mfma_f32_16x16x32_bf16 v[100:103], v[128:131], v[212:215], v[100:103]
	v_mfma_f32_16x16x32_bf16 v[96:99], v[152:155], v[212:215], v[96:99]
	v_mfma_f32_16x16x32_bf16 v[84:87], v[128:131], v[220:223], v[84:87]
	v_mfma_f32_16x16x32_bf16 v[80:83], v[152:155], v[220:223], v[80:83]
	v_mfma_f32_16x16x32_bf16 v[136:139], v[148:151], v[200:203], v[136:139]
	v_mfma_f32_16x16x32_bf16 v[132:135], v[180:183], v[200:203], v[132:135]
	v_mfma_f32_16x16x32_bf16 v[116:119], v[148:151], v[208:211], v[116:119]
	v_mfma_f32_16x16x32_bf16 v[112:115], v[180:183], v[208:211], v[112:115]
	v_mfma_f32_16x16x32_bf16 v[100:103], v[148:151], v[216:219], v[100:103]
	v_mfma_f32_16x16x32_bf16 v[96:99], v[180:183], v[216:219], v[96:99]
	v_mfma_f32_16x16x32_bf16 v[84:87], v[148:151], v[224:227], v[84:87]
	v_mfma_f32_16x16x32_bf16 v[80:83], v[180:183], v[224:227], v[80:83]
	s_barrier
	s_add_i32 s6, s43, s67
	v_lshl_add_u64 v[188:189], s[58:59], 0, v[158:159]
	s_mov_b32 m0, s6
	ds_read_b128 v[184:187], v198 offset:16384
	ds_read_b128 v[200:203], v198 offset:17408
	ds_read_b128 v[204:207], v198 offset:18432
	ds_read_b128 v[208:211], v198 offset:19456
	ds_read_b128 v[212:215], v198 offset:20480
	ds_read_b128 v[216:219], v198 offset:21504
	ds_read_b128 v[220:223], v198 offset:22528
	ds_read_b128 v[224:227], v198 offset:23552
	global_load_lds_dwordx4 v[188:189], off
	s_add_i32 m0, s6, 0x2000
	s_add_u32 s6, s58, 0x40000
	v_lshl_add_u64 v[228:229], s[58:59], 0, v[170:171]
	s_addc_u32 s7, s59, 0
	s_add_i32 s72, s76, s67
	global_load_lds_dwordx4 v[228:229], off
	s_mov_b32 m0, s72
	v_lshl_add_u64 v[232:233], s[60:61], 0, v[164:165]
	global_load_lds_dwordx4 v158, s[6:7]
	s_add_i32 m0, s72, 0x2000
	s_nop 0
	global_load_lds_dwordx4 v170, s[6:7]
	v_lshl_add_u64 v[230:231], s[60:61], 0, v[156:157]
	s_mov_b32 m0, s78
	s_nop 0
	global_load_lds_dwordx4 v[230:231], off
	s_mov_b32 m0, s79
	s_nop 0
	global_load_lds_dwordx4 v[232:233], off
	s_waitcnt vmcnt(8)
	s_waitcnt lgkmcnt(0)
	s_barrier
	s_waitcnt lgkmcnt(0)
	v_mfma_f32_16x16x32_bf16 v[76:79], v[32:35], v[184:187], v[76:79]
	v_mfma_f32_16x16x32_bf16 v[72:75], v[48:51], v[184:187], v[72:75]
	v_mfma_f32_16x16x32_bf16 v[60:63], v[32:35], v[204:207], v[60:63]
	v_mfma_f32_16x16x32_bf16 v[56:59], v[48:51], v[204:207], v[56:59]
	v_mfma_f32_16x16x32_bf16 v[28:31], v[32:35], v[212:215], v[28:31]
	v_mfma_f32_16x16x32_bf16 v[24:27], v[48:51], v[212:215], v[24:27]
	v_mfma_f32_16x16x32_bf16 v[12:15], v[32:35], v[220:223], v[12:15]
	v_mfma_f32_16x16x32_bf16 v[8:11], v[48:51], v[220:223], v[8:11]
	v_mfma_f32_16x16x32_bf16 v[76:79], v[36:39], v[200:203], v[76:79]
	v_mfma_f32_16x16x32_bf16 v[72:75], v[52:55], v[200:203], v[72:75]
	v_mfma_f32_16x16x32_bf16 v[60:63], v[36:39], v[208:211], v[60:63]
	v_mfma_f32_16x16x32_bf16 v[56:59], v[52:55], v[208:211], v[56:59]
	v_mfma_f32_16x16x32_bf16 v[28:31], v[36:39], v[216:219], v[28:31]
	v_mfma_f32_16x16x32_bf16 v[24:27], v[52:55], v[216:219], v[24:27]
	v_mfma_f32_16x16x32_bf16 v[12:15], v[36:39], v[224:227], v[12:15]
	v_mfma_f32_16x16x32_bf16 v[8:11], v[52:55], v[224:227], v[8:11]
	v_mfma_f32_16x16x32_bf16 v[44:47], v[128:131], v[204:207], v[44:47]
	v_mfma_f32_16x16x32_bf16 v[40:43], v[152:155], v[204:207], v[40:43]
	v_mfma_f32_16x16x32_bf16 v[20:23], v[128:131], v[212:215], v[20:23]
	v_mfma_f32_16x16x32_bf16 v[16:19], v[152:155], v[212:215], v[16:19]
	v_mfma_f32_16x16x32_bf16 v[4:7], v[128:131], v[220:223], v[4:7]
	v_mfma_f32_16x16x32_bf16 v[0:3], v[152:155], v[220:223], v[0:3]
	v_mfma_f32_16x16x32_bf16 v[32:35], v[128:131], v[184:187], v[68:71]
	v_mfma_f32_16x16x32_bf16 v[36:39], v[152:155], v[184:187], v[64:67]
	v_mfma_f32_16x16x32_bf16 v[44:47], v[148:151], v[208:211], v[44:47]
	v_mfma_f32_16x16x32_bf16 v[40:43], v[180:183], v[208:211], v[40:43]
	v_mfma_f32_16x16x32_bf16 v[20:23], v[148:151], v[216:219], v[20:23]
	v_mfma_f32_16x16x32_bf16 v[16:19], v[180:183], v[216:219], v[16:19]
	v_mfma_f32_16x16x32_bf16 v[4:7], v[148:151], v[224:227], v[4:7]
	v_mfma_f32_16x16x32_bf16 v[0:3], v[180:183], v[224:227], v[0:3]
	v_mfma_f32_16x16x32_bf16 v[32:35], v[148:151], v[200:203], v[32:35]
	v_mfma_f32_16x16x32_bf16 v[36:39], v[180:183], v[200:203], v[36:39]
	s_barrier
; #define PG8_STAGE(bufoff, gbase, voff) do { _Pragma("unroll") for (int _i = 0; _i < 2; ++_i) \
;         __builtin_amdgcn_global_load_lds((const unsigned*)((const char*)(gbase) + (voff)[_i]), (PG8_LAS unsigned*)(lds + (bufoff) + ldsw + _i * 8192), 16, 0, 0); } while (0)
; #define PG8_LDA(dst, b, h) do { _Pragma("unroll") for (int m = 0; m < 4; ++m) _Pragma("unroll") for (int k = 0; k < 2; ++k) dst[m][k] = *(const PG8_LAS bf16x8*)(lds + PG8_SA(b, h) + aoff + m * 2048 + k * 1024); } while (0)
; #define PG8_LDB(dst, b, h) do { _Pragma("unroll") for (int n = 0; n < 2; ++n) _Pragma("unroll") for (int k = 0; k < 2; ++k) dst[n][k] = *(const PG8_LAS bf16x8*)(lds + PG8_SB(b, h) + boff + n * 2048 + k * 1024); } while (0)
; #define PG8_MMA(ai, bj, At, Bt) do { __builtin_amdgcn_s_setprio(1); _Pragma("unroll") for (int m = 0; m < 4; ++m) _Pragma("unroll") for (int n = 0; n < 2; ++n) _Pragma("unroll") for (int k = 0; k < 2; ++k) \
;         acc[ai][bj][m][n] = __builtin_amdgcn_mfma_f32_16x16x32_bf16(Bt[n][k], At[m][k], acc[ai][bj][m][n], 0, 0, 0); __builtin_amdgcn_s_setprio(0); } while (0)
; #define PG8_WAIT_V(n) asm volatile("s_waitcnt vmcnt(" #n ")" ::: "memory")
; #define PG8_WAIT_L(n) asm volatile("s_waitcnt lgkmcnt(" #n ")" ::: "memory")
; #define PG8_BAR __builtin_amdgcn_s_barrier()
; #define PG8_SCHED __builtin_amdgcn_sched_barrier(0)
; template <class Epi, class Sched, bool ALIGN_EPI = false, bool SP2 = false>
; __device__ __forceinline__ void gemm_phase(PG8_LAS unsigned char* lds, const Gemm g, const Sched& S, const Epi& E) {
;     ...
;         for (int t = 0; t < nt; t += 2) {
;             const bool last = (t == nt - 2);
;     ...
;             PG8_LDB(B0, 1, 0); PG8_LDB(B1, 1, 1); PG8_SCHED; PG8_LDA(At, 1, 0); PG8_STAGE(PG8_SA(0, 1), a2 + hstep, voffA);
;             PG8_WAIT_V(8); PG8_WAIT_L(0); PG8_BAR; PG8_MMA(0, 0, At, B0); PG8_MMA(0, 1, At, B1); PG8_BAR; PG8_SCHED;
;             PG8_LDA(At, 1, 1); PG8_STAGE(PG8_SB(1, 0), b3, voffB); PG8_STAGE(PG8_SB(1, 1), b3 + hstep, voffB); PG8_STAGE(PG8_SA(1, 0), a3, voffA);
;             PG8_WAIT_V(8); PG8_WAIT_L(0); PG8_BAR; PG8_MMA(1, 0, At, B0); PG8_MMA(1, 1, At, B1); PG8_BAR; PG8_SCHED;
	s_add_i32 s72, 0, 0x18000
	s_add_i32 s73, 0, 0x1c000
	v_add_u32_e32 v68, s72, v169
	v_add_u32_e32 v180, s73, v169
	ds_read_b128 v[48:51], v68
	ds_read_b128 v[52:55], v68 offset:1024
	ds_read_b128 v[64:67], v68 offset:2048
	ds_read_b128 v[68:71], v68 offset:3072
	ds_read_b128 v[128:131], v180
	ds_read_b128 v[148:151], v180 offset:1024
	ds_read_b128 v[152:155], v180 offset:2048
	ds_read_b128 v[180:183], v180 offset:3072
	s_add_u32 s6, s60, 0x40000
	s_addc_u32 s7, s61, 0
	s_mov_b32 m0, s80
	ds_read_b128 v[184:187], v198 offset:32768
	ds_read_b128 v[200:203], v198 offset:33792
	ds_read_b128 v[204:207], v198 offset:34816
	ds_read_b128 v[208:211], v198 offset:35840
	ds_read_b128 v[212:215], v198 offset:36864
	ds_read_b128 v[216:219], v198 offset:37888
	ds_read_b128 v[220:223], v198 offset:38912
	ds_read_b128 v[224:227], v198 offset:39936
	global_load_lds_dwordx4 v156, s[6:7]
	s_mov_b32 m0, s81
	s_nop 0
	global_load_lds_dwordx4 v164, s[6:7]
	s_waitcnt vmcnt(8)
	s_waitcnt lgkmcnt(0)
	s_barrier
	s_waitcnt lgkmcnt(0)
	v_mfma_f32_16x16x32_bf16 v[144:147], v[48:51], v[184:187], v[144:147]
	v_mfma_f32_16x16x32_bf16 v[140:143], v[64:67], v[184:187], v[140:143]
	v_mfma_f32_16x16x32_bf16 v[124:127], v[48:51], v[204:207], v[124:127]
	v_mfma_f32_16x16x32_bf16 v[120:123], v[64:67], v[204:207], v[120:123]
	v_mfma_f32_16x16x32_bf16 v[108:111], v[48:51], v[212:215], v[108:111]
	v_mfma_f32_16x16x32_bf16 v[104:107], v[64:67], v[212:215], v[104:107]
	v_mfma_f32_16x16x32_bf16 v[92:95], v[48:51], v[220:223], v[92:95]
	v_mfma_f32_16x16x32_bf16 v[88:91], v[64:67], v[220:223], v[88:91]
	v_mfma_f32_16x16x32_bf16 v[144:147], v[52:55], v[200:203], v[144:147]
	v_mfma_f32_16x16x32_bf16 v[140:143], v[68:71], v[200:203], v[140:143]
	v_mfma_f32_16x16x32_bf16 v[124:127], v[52:55], v[208:211], v[124:127]
	v_mfma_f32_16x16x32_bf16 v[120:123], v[68:71], v[208:211], v[120:123]
	v_mfma_f32_16x16x32_bf16 v[108:111], v[52:55], v[216:219], v[108:111]
	v_mfma_f32_16x16x32_bf16 v[104:107], v[68:71], v[216:219], v[104:107]
	v_mfma_f32_16x16x32_bf16 v[92:95], v[52:55], v[224:227], v[92:95]
	v_mfma_f32_16x16x32_bf16 v[88:91], v[68:71], v[224:227], v[88:91]
	v_mfma_f32_16x16x32_bf16 v[136:139], v[128:131], v[184:187], v[136:139]
	v_mfma_f32_16x16x32_bf16 v[132:135], v[152:155], v[184:187], v[132:135]
	v_mfma_f32_16x16x32_bf16 v[116:119], v[128:131], v[204:207], v[116:119]
	v_mfma_f32_16x16x32_bf16 v[112:115], v[152:155], v[204:207], v[112:115]
	v_mfma_f32_16x16x32_bf16 v[100:103], v[128:131], v[212:215], v[100:103]
	v_mfma_f32_16x16x32_bf16 v[96:99], v[152:155], v[212:215], v[96:99]
	v_mfma_f32_16x16x32_bf16 v[84:87], v[128:131], v[220:223], v[84:87]
	v_mfma_f32_16x16x32_bf16 v[80:83], v[152:155], v[220:223], v[80:83]
	v_mfma_f32_16x16x32_bf16 v[136:139], v[148:151], v[200:203], v[136:139]
	v_mfma_f32_16x16x32_bf16 v[132:135], v[180:183], v[200:203], v[132:135]
	v_mfma_f32_16x16x32_bf16 v[116:119], v[148:151], v[208:211], v[116:119]
	v_mfma_f32_16x16x32_bf16 v[112:115], v[180:183], v[208:211], v[112:115]
	v_mfma_f32_16x16x32_bf16 v[100:103], v[148:151], v[216:219], v[100:103]
	v_mfma_f32_16x16x32_bf16 v[96:99], v[180:183], v[216:219], v[96:99]
	v_mfma_f32_16x16x32_bf16 v[84:87], v[148:151], v[224:227], v[84:87]
	v_mfma_f32_16x16x32_bf16 v[80:83], v[180:183], v[224:227], v[80:83]
	s_barrier
	s_add_i32 s6, s72, s67
	v_lshl_add_u64 v[188:189], v[188:189], 0, s[38:39]
	s_mov_b32 m0, s6
	ds_read_b128 v[184:187], v198 offset:49152
	ds_read_b128 v[200:203], v198 offset:50176
	ds_read_b128 v[204:207], v198 offset:51200
	ds_read_b128 v[208:211], v198 offset:52224
	ds_read_b128 v[212:215], v198 offset:53248
	ds_read_b128 v[216:219], v198 offset:54272
	ds_read_b128 v[220:223], v198 offset:55296
	ds_read_b128 v[224:227], v198 offset:56320
	global_load_lds_dwordx4 v[188:189], off
	s_add_i32 m0, s6, 0x2000
	s_add_u32 s6, s58, 0x40080
	v_lshl_add_u64 v[188:189], v[228:229], 0, s[38:39]
	s_addc_u32 s7, s59, 0
	s_add_i32 s58, s73, s67
	global_load_lds_dwordx4 v[188:189], off
	s_mov_b32 m0, s58
	s_nop 0
	global_load_lds_dwordx4 v158, s[6:7]
	s_add_i32 m0, s58, 0x2000
	s_nop 0
	global_load_lds_dwordx4 v170, s[6:7]
	v_lshl_add_u64 v[188:189], v[230:231], 0, s[38:39]
	s_mov_b32 m0, s45
	s_nop 0
	global_load_lds_dwordx4 v[188:189], off
	v_lshl_add_u64 v[188:189], v[232:233], 0, s[38:39]
	s_mov_b32 m0, s42
	s_nop 0
	global_load_lds_dwordx4 v[188:189], off
	s_waitcnt vmcnt(8)
	s_waitcnt lgkmcnt(0)
	s_barrier
	s_waitcnt lgkmcnt(0)
	v_mfma_f32_16x16x32_bf16 v[76:79], v[48:51], v[184:187], v[76:79]
	v_mfma_f32_16x16x32_bf16 v[72:75], v[64:67], v[184:187], v[72:75]
	v_mfma_f32_16x16x32_bf16 v[60:63], v[48:51], v[204:207], v[60:63]
	v_mfma_f32_16x16x32_bf16 v[56:59], v[64:67], v[204:207], v[56:59]
	v_mfma_f32_16x16x32_bf16 v[28:31], v[48:51], v[212:215], v[28:31]
	v_mfma_f32_16x16x32_bf16 v[24:27], v[64:67], v[212:215], v[24:27]
	v_mfma_f32_16x16x32_bf16 v[12:15], v[48:51], v[220:223], v[12:15]
	v_mfma_f32_16x16x32_bf16 v[8:11], v[64:67], v[220:223], v[8:11]
	v_mfma_f32_16x16x32_bf16 v[76:79], v[52:55], v[200:203], v[76:79]
	v_mfma_f32_16x16x32_bf16 v[72:75], v[68:71], v[200:203], v[72:75]
	v_mfma_f32_16x16x32_bf16 v[60:63], v[52:55], v[208:211], v[60:63]
	v_mfma_f32_16x16x32_bf16 v[56:59], v[68:71], v[208:211], v[56:59]
	v_mfma_f32_16x16x32_bf16 v[28:31], v[52:55], v[216:219], v[28:31]
	v_mfma_f32_16x16x32_bf16 v[24:27], v[68:71], v[216:219], v[24:27]
	v_mfma_f32_16x16x32_bf16 v[12:15], v[52:55], v[224:227], v[12:15]
	v_mfma_f32_16x16x32_bf16 v[8:11], v[68:71], v[224:227], v[8:11]
	v_mfma_f32_16x16x32_bf16 v[32:35], v[128:131], v[184:187], v[32:35]
	v_mfma_f32_16x16x32_bf16 v[68:71], v[148:151], v[200:203], v[32:35]
	v_mfma_f32_16x16x32_bf16 v[32:35], v[152:155], v[184:187], v[36:39]
	v_mfma_f32_16x16x32_bf16 v[64:67], v[180:183], v[200:203], v[32:35]
	v_mfma_f32_16x16x32_bf16 v[32:35], v[128:131], v[204:207], v[44:47]
	v_mfma_f32_16x16x32_bf16 v[44:47], v[148:151], v[208:211], v[32:35]
	v_mfma_f32_16x16x32_bf16 v[32:35], v[152:155], v[204:207], v[40:43]
	v_mfma_f32_16x16x32_bf16 v[20:23], v[128:131], v[212:215], v[20:23]
	v_mfma_f32_16x16x32_bf16 v[16:19], v[152:155], v[212:215], v[16:19]
	v_mfma_f32_16x16x32_bf16 v[4:7], v[128:131], v[220:223], v[4:7]
	v_mfma_f32_16x16x32_bf16 v[0:3], v[152:155], v[220:223], v[0:3]
	v_mfma_f32_16x16x32_bf16 v[40:43], v[180:183], v[208:211], v[32:35]
	v_mfma_f32_16x16x32_bf16 v[20:23], v[148:151], v[216:219], v[20:23]
	v_mfma_f32_16x16x32_bf16 v[16:19], v[180:183], v[216:219], v[16:19]
	v_mfma_f32_16x16x32_bf16 v[4:7], v[148:151], v[224:227], v[4:7]
	v_mfma_f32_16x16x32_bf16 v[0:3], v[180:183], v[224:227], v[0:3]
	s_barrier
	s_add_i32 s69, s69, 2
	s_add_u32 s56, s56, 0x100
	s_addc_u32 s57, s57, 0
	s_add_u32 s68, s68, 0x100
	s_addc_u32 s33, s33, 0
	s_cmp_gt_u32 s69, 13
	s_cbranch_scc0 .LBB0_1617
	v_readlane_b32 s68, v243, 59
	s_and_b64 vcc, exec, s[40:41]
	v_readlane_b32 s69, v243, 60
	s_cbranch_vccz .LBB0_1620
	s_barrier

; #define PG8_STAGE(bufoff, gbase, voff) do { _Pragma("unroll") for (int _i = 0; _i < 2; ++_i) \
;         __builtin_amdgcn_global_load_lds((const unsigned*)((const char*)(gbase) + (voff)[_i]), (PG8_LAS unsigned*)(lds + (bufoff) + ldsw + _i * 8192), 16, 0, 0); } while (0)
; #define PG8_LDA(dst, b, h) do { _Pragma("unroll") for (int m = 0; m < 4; ++m) _Pragma("unroll") for (int k = 0; k < 2; ++k) dst[m][k] = *(const PG8_LAS bf16x8*)(lds + PG8_SA(b, h) + aoff + m * 2048 + k * 1024); } while (0)
; #define PG8_LDB(dst, b, h) do { _Pragma("unroll") for (int n = 0; n < 2; ++n) _Pragma("unroll") for (int k = 0; k < 2; ++k) dst[n][k] = *(const PG8_LAS bf16x8*)(lds + PG8_SB(b, h) + boff + n * 2048 + k * 1024); } while (0)
; #define PG8_MMA(ai, bj, At, Bt) do { __builtin_amdgcn_s_setprio(1); _Pragma("unroll") for (int m = 0; m < 4; ++m) _Pragma("unroll") for (int n = 0; n < 2; ++n) _Pragma("unroll") for (int k = 0; k < 2; ++k) \
;         acc[ai][bj][m][n] = __builtin_amdgcn_mfma_f32_16x16x32_bf16(Bt[n][k], At[m][k], acc[ai][bj][m][n], 0, 0, 0); __builtin_amdgcn_s_setprio(0); } while (0)
; #define PG8_WAIT_V(n) asm volatile("s_waitcnt vmcnt(" #n ")" ::: "memory")
; #define PG8_BAR __builtin_amdgcn_s_barrier()
; template <class Epi, class Sched, bool ALIGN_EPI = false, bool SP2 = false>
; __device__ __forceinline__ void gemm_phase(PG8_LAS unsigned char* lds, const Gemm g, const Sched& S, const Epi& E) {
;     ...
;         for (int t = 0; t < nt; t += 2) {
;             const bool last = (t == nt - 2);
;             const char* a1 = cA + (size_t)(t + 1) * kstep;
;             const char* a2 = last ? nA : cA + (size_t)(t + 2) * kstep; const char* b2 = last ? nB : cB + (size_t)(t + 2) * kstep;
;             const char* a3 = a2 + kstep; const char* b3 = b2 + kstep;
;             if (last && has_next) S.a_ready(nxt);
;             if constexpr (SP2) {
;             PG8_LDB(B0, 0, 0); PG8_LDB(B1, 0, 1); PG8_SCHED; PG8_LDA(At, 0, 0); PG8_STAGE(PG8_SA(1, 1), a1 + hstep, voffA);
;             PG8_WAIT_V(8); PG8_WAIT_L(0); PG8_BAR; PG8_MMA(0, 0, At, B0); PG8_MMA(0, 1, At, B1); PG8_BAR; PG8_SCHED;
;             PG8_LDA(At, 0, 1); PG8_STAGE(PG8_SB(0, 0), b2, voffB); PG8_STAGE(PG8_SB(0, 1), b2 + hstep, voffB); PG8_STAGE(PG8_SA(0, 0), a2, voffA);
;             PG8_WAIT_V(8); PG8_WAIT_L(0); PG8_BAR; PG8_MMA(1, 0, At, B0); PG8_MMA(1, 1, At, B1); PG8_BAR; PG8_SCHED;
.LBB0_1698:
	ds_read_b128 v[144:147], v153
	ds_read_b128 v[170:173], v153 offset:1024
	ds_read_b128 v[174:177], v153 offset:2048
	ds_read_b128 v[178:181], v153 offset:3072
	ds_read_b128 v[182:185], v154
	ds_read_b128 v[186:189], v154 offset:1024
	ds_read_b128 v[198:201], v154 offset:2048
	ds_read_b128 v[202:205], v154 offset:3072
	s_add_u32 s6, s60, 0xfffc0080
	s_addc_u32 s7, s61, -1
	s_cmp_eq_u32 s72, 12
	s_cselect_b32 s81, s29, s7
	s_cselect_b32 s80, s55, s6
	s_cselect_b32 s79, s53, s33
	s_cselect_b32 s78, s68, s69
	s_add_i32 m0, s43, 0xc000
	ds_read_b128 v[206:209], v155
	ds_read_b128 v[210:213], v155 offset:1024
	ds_read_b128 v[214:217], v155 offset:2048
	ds_read_b128 v[218:221], v155 offset:3072
	ds_read_b128 v[222:225], v155 offset:4096
	ds_read_b128 v[226:229], v155 offset:5120
	ds_read_b128 v[230:233], v155 offset:6144
	ds_read_b128 v[234:237], v155 offset:7168
	global_load_lds_dwordx4 v136, s[60:61]
	s_add_i32 m0, s43, 0xe000
	s_nop 0
	global_load_lds_dwordx4 v138, s[60:61]
	s_waitcnt vmcnt(8)
	s_waitcnt lgkmcnt(0)
	s_barrier
	s_waitcnt lgkmcnt(0)
	v_mfma_f32_16x16x32_bf16 v[124:127], v[144:147], v[206:209], v[124:127]
	v_mfma_f32_16x16x32_bf16 v[120:123], v[174:177], v[206:209], v[120:123]
	v_mfma_f32_16x16x32_bf16 v[108:111], v[144:147], v[214:217], v[108:111]
	v_mfma_f32_16x16x32_bf16 v[104:107], v[174:177], v[214:217], v[104:107]
	v_mfma_f32_16x16x32_bf16 v[92:95], v[144:147], v[222:225], v[92:95]
	v_mfma_f32_16x16x32_bf16 v[88:91], v[174:177], v[222:225], v[88:91]
	v_mfma_f32_16x16x32_bf16 v[76:79], v[144:147], v[230:233], v[76:79]
	v_mfma_f32_16x16x32_bf16 v[72:75], v[174:177], v[230:233], v[72:75]
	v_mfma_f32_16x16x32_bf16 v[124:127], v[170:173], v[210:213], v[124:127]
	v_mfma_f32_16x16x32_bf16 v[120:123], v[178:181], v[210:213], v[120:123]
	v_mfma_f32_16x16x32_bf16 v[108:111], v[170:173], v[218:221], v[108:111]
	v_mfma_f32_16x16x32_bf16 v[104:107], v[178:181], v[218:221], v[104:107]
	v_mfma_f32_16x16x32_bf16 v[92:95], v[170:173], v[226:229], v[92:95]
	v_mfma_f32_16x16x32_bf16 v[88:91], v[178:181], v[226:229], v[88:91]
	v_mfma_f32_16x16x32_bf16 v[76:79], v[170:173], v[234:237], v[76:79]
	v_mfma_f32_16x16x32_bf16 v[72:75], v[178:181], v[234:237], v[72:75]
	v_mfma_f32_16x16x32_bf16 v[116:119], v[182:185], v[206:209], v[116:119]
	v_mfma_f32_16x16x32_bf16 v[112:115], v[198:201], v[206:209], v[112:115]
	v_mfma_f32_16x16x32_bf16 v[100:103], v[182:185], v[214:217], v[100:103]
	v_mfma_f32_16x16x32_bf16 v[96:99], v[198:201], v[214:217], v[96:99]
	v_mfma_f32_16x16x32_bf16 v[84:87], v[182:185], v[222:225], v[84:87]
	v_mfma_f32_16x16x32_bf16 v[80:83], v[198:201], v[222:225], v[80:83]
	v_mfma_f32_16x16x32_bf16 v[68:71], v[182:185], v[230:233], v[68:71]
	v_mfma_f32_16x16x32_bf16 v[64:67], v[198:201], v[230:233], v[64:67]
	v_mfma_f32_16x16x32_bf16 v[116:119], v[186:189], v[210:213], v[116:119]
	v_mfma_f32_16x16x32_bf16 v[112:115], v[202:205], v[210:213], v[112:115]
	v_mfma_f32_16x16x32_bf16 v[100:103], v[186:189], v[218:221], v[100:103]
	v_mfma_f32_16x16x32_bf16 v[96:99], v[202:205], v[218:221], v[96:99]
	v_mfma_f32_16x16x32_bf16 v[84:87], v[186:189], v[226:229], v[84:87]
	v_mfma_f32_16x16x32_bf16 v[80:83], v[202:205], v[226:229], v[80:83]
	v_mfma_f32_16x16x32_bf16 v[68:71], v[186:189], v[234:237], v[68:71]
	v_mfma_f32_16x16x32_bf16 v[64:67], v[202:205], v[234:237], v[64:67]
	s_barrier
	s_add_i32 s6, s26, s42
	v_lshl_add_u64 v[148:149], s[78:79], 0, v[130:131]
	s_mov_b32 m0, s6
	ds_read_b128 v[206:209], v155 offset:16384
	ds_read_b128 v[210:213], v155 offset:17408
	ds_read_b128 v[214:217], v155 offset:18432
	ds_read_b128 v[218:221], v155 offset:19456
	ds_read_b128 v[222:225], v155 offset:20480
	ds_read_b128 v[226:229], v155 offset:21504
	ds_read_b128 v[230:233], v155 offset:22528
	ds_read_b128 v[234:237], v155 offset:23552
	global_load_lds_dwordx4 v[148:149], off
	s_add_i32 m0, s6, 0x2000
	s_add_u32 s6, s78, 0x40000
	v_lshl_add_u64 v[158:159], s[78:79], 0, v[134:135]
	s_addc_u32 s7, s79, 0
	s_add_i32 s73, s74, s42
	global_load_lds_dwordx4 v[158:159], off
	s_mov_b32 m0, s73
	v_lshl_add_u64 v[190:191], s[80:81], 0, v[132:133]
	global_load_lds_dwordx4 v130, s[6:7]
	s_add_i32 m0, s73, 0x2000
	s_nop 0
	global_load_lds_dwordx4 v134, s[6:7]
	v_lshl_add_u64 v[164:165], s[80:81], 0, v[128:129]
	s_mov_b32 m0, s43
	s_nop 0
	global_load_lds_dwordx4 v[164:165], off
	s_mov_b32 m0, s44
	s_nop 0
	global_load_lds_dwordx4 v[190:191], off
	s_waitcnt vmcnt(8)
	s_waitcnt lgkmcnt(0)
	s_barrier
	s_waitcnt lgkmcnt(0)
	v_mfma_f32_16x16x32_bf16 v[60:63], v[144:147], v[206:209], v[60:63]
	v_mfma_f32_16x16x32_bf16 v[56:59], v[174:177], v[206:209], v[56:59]
	v_mfma_f32_16x16x32_bf16 v[44:47], v[144:147], v[214:217], v[44:47]
	v_mfma_f32_16x16x32_bf16 v[40:43], v[174:177], v[214:217], v[40:43]
	v_mfma_f32_16x16x32_bf16 v[28:31], v[144:147], v[222:225], v[28:31]
	v_mfma_f32_16x16x32_bf16 v[24:27], v[174:177], v[222:225], v[24:27]
	v_mfma_f32_16x16x32_bf16 v[12:15], v[144:147], v[230:233], v[12:15]
	v_mfma_f32_16x16x32_bf16 v[8:11], v[174:177], v[230:233], v[8:11]
	v_mfma_f32_16x16x32_bf16 v[60:63], v[170:173], v[210:213], v[60:63]
	v_mfma_f32_16x16x32_bf16 v[56:59], v[178:181], v[210:213], v[56:59]
	v_mfma_f32_16x16x32_bf16 v[44:47], v[170:173], v[218:221], v[44:47]
	v_mfma_f32_16x16x32_bf16 v[40:43], v[178:181], v[218:221], v[40:43]
	v_mfma_f32_16x16x32_bf16 v[28:31], v[170:173], v[226:229], v[28:31]
	v_mfma_f32_16x16x32_bf16 v[24:27], v[178:181], v[226:229], v[24:27]
	v_mfma_f32_16x16x32_bf16 v[12:15], v[170:173], v[234:237], v[12:15]
	v_mfma_f32_16x16x32_bf16 v[8:11], v[178:181], v[234:237], v[8:11]
	v_mfma_f32_16x16x32_bf16 v[52:55], v[182:185], v[206:209], v[52:55]
	v_mfma_f32_16x16x32_bf16 v[48:51], v[198:201], v[206:209], v[48:51]
	v_mfma_f32_16x16x32_bf16 v[36:39], v[182:185], v[214:217], v[36:39]
	v_mfma_f32_16x16x32_bf16 v[32:35], v[198:201], v[214:217], v[32:35]
	v_mfma_f32_16x16x32_bf16 v[20:23], v[182:185], v[222:225], v[20:23]
	v_mfma_f32_16x16x32_bf16 v[16:19], v[198:201], v[222:225], v[16:19]
	v_mfma_f32_16x16x32_bf16 v[4:7], v[182:185], v[230:233], v[4:7]
	v_mfma_f32_16x16x32_bf16 v[0:3], v[198:201], v[230:233], v[0:3]
	v_mfma_f32_16x16x32_bf16 v[52:55], v[186:189], v[210:213], v[52:55]
	v_mfma_f32_16x16x32_bf16 v[48:51], v[202:205], v[210:213], v[48:51]
	v_mfma_f32_16x16x32_bf16 v[36:39], v[186:189], v[218:221], v[36:39]
	v_mfma_f32_16x16x32_bf16 v[32:35], v[202:205], v[218:221], v[32:35]
	v_mfma_f32_16x16x32_bf16 v[20:23], v[186:189], v[226:229], v[20:23]
	v_mfma_f32_16x16x32_bf16 v[16:19], v[202:205], v[226:229], v[16:19]
	v_mfma_f32_16x16x32_bf16 v[4:7], v[186:189], v[234:237], v[4:7]
	v_mfma_f32_16x16x32_bf16 v[0:3], v[202:205], v[234:237], v[0:3]
	s_barrier
; #define PG8_STAGE(bufoff, gbase, voff) do { _Pragma("unroll") for (int _i = 0; _i < 2; ++_i) \
;         __builtin_amdgcn_global_load_lds((const unsigned*)((const char*)(gbase) + (voff)[_i]), (PG8_LAS unsigned*)(lds + (bufoff) + ldsw + _i * 8192), 16, 0, 0); } while (0)
; #define PG8_LDA(dst, b, h) do { _Pragma("unroll") for (int m = 0; m < 4; ++m) _Pragma("unroll") for (int k = 0; k < 2; ++k) dst[m][k] = *(const PG8_LAS bf16x8*)(lds + PG8_SA(b, h) + aoff + m * 2048 + k * 1024); } while (0)
; #define PG8_LDB(dst, b, h) do { _Pragma("unroll") for (int n = 0; n < 2; ++n) _Pragma("unroll") for (int k = 0; k < 2; ++k) dst[n][k] = *(const PG8_LAS bf16x8*)(lds + PG8_SB(b, h) + boff + n * 2048 + k * 1024); } while (0)
; #define PG8_MMA(ai, bj, At, Bt) do { __builtin_amdgcn_s_setprio(1); _Pragma("unroll") for (int m = 0; m < 4; ++m) _Pragma("unroll") for (int n = 0; n < 2; ++n) _Pragma("unroll") for (int k = 0; k < 2; ++k) \
;         acc[ai][bj][m][n] = __builtin_amdgcn_mfma_f32_16x16x32_bf16(Bt[n][k], At[m][k], acc[ai][bj][m][n], 0, 0, 0); __builtin_amdgcn_s_setprio(0); } while (0)
; #define PG8_WAIT_V(n) asm volatile("s_waitcnt vmcnt(" #n ")" ::: "memory")
; #define PG8_WAIT_L(n) asm volatile("s_waitcnt lgkmcnt(" #n ")" ::: "memory")
; #define PG8_BAR __builtin_amdgcn_s_barrier()
; #define PG8_SCHED __builtin_amdgcn_sched_barrier(0)
; template <class Epi, class Sched, bool ALIGN_EPI = false, bool SP2 = false>
; __device__ __forceinline__ void gemm_phase(PG8_LAS unsigned char* lds, const Gemm g, const Sched& S, const Epi& E) {
;     ...
;         for (int t = 0; t < nt; t += 2) {
;             const bool last = (t == nt - 2);
;     ...
;             PG8_LDB(B0, 1, 0); PG8_LDB(B1, 1, 1); PG8_SCHED; PG8_LDA(At, 1, 0); PG8_STAGE(PG8_SA(0, 1), a2 + hstep, voffA);
;             PG8_WAIT_V(8); PG8_WAIT_L(0); PG8_BAR; PG8_MMA(0, 0, At, B0); PG8_MMA(0, 1, At, B1); PG8_BAR; PG8_SCHED;
;             PG8_LDA(At, 1, 1); PG8_STAGE(PG8_SB(1, 0), b3, voffB); PG8_STAGE(PG8_SB(1, 1), b3 + hstep, voffB); PG8_STAGE(PG8_SA(1, 0), a3, voffA);
;             PG8_WAIT_V(8); PG8_WAIT_L(0); PG8_BAR; PG8_MMA(1, 0, At, B0); PG8_MMA(1, 1, At, B1); PG8_BAR; PG8_SCHED;
	s_add_i32 s73, 0, 0x18000
	v_add_u32_e32 v157, s73, v151
	s_add_i32 s82, 0, 0x1c000
	ds_read_b128 v[144:147], v157
	ds_read_b128 v[170:173], v157 offset:1024
	ds_read_b128 v[174:177], v157 offset:2048
	ds_read_b128 v[178:181], v157 offset:3072
	v_add_u32_e32 v157, s82, v151
	ds_read_b128 v[182:185], v157
	ds_read_b128 v[186:189], v157 offset:1024
	ds_read_b128 v[198:201], v157 offset:2048
	ds_read_b128 v[202:205], v157 offset:3072
	s_add_u32 s6, s80, 0x40000
	s_addc_u32 s7, s81, 0
	s_mov_b32 m0, s45
	ds_read_b128 v[206:209], v155 offset:32768
	ds_read_b128 v[210:213], v155 offset:33792
	ds_read_b128 v[214:217], v155 offset:34816
	ds_read_b128 v[218:221], v155 offset:35840
	ds_read_b128 v[222:225], v155 offset:36864
	ds_read_b128 v[226:229], v155 offset:37888
	ds_read_b128 v[230:233], v155 offset:38912
	ds_read_b128 v[234:237], v155 offset:39936
	global_load_lds_dwordx4 v128, s[6:7]
	s_mov_b32 m0, s67
	s_nop 0
	global_load_lds_dwordx4 v132, s[6:7]
	s_waitcnt vmcnt(8)
	s_waitcnt lgkmcnt(0)
	s_barrier
	s_waitcnt lgkmcnt(0)
	v_mfma_f32_16x16x32_bf16 v[124:127], v[144:147], v[206:209], v[124:127]
	v_mfma_f32_16x16x32_bf16 v[120:123], v[174:177], v[206:209], v[120:123]
	v_mfma_f32_16x16x32_bf16 v[108:111], v[144:147], v[214:217], v[108:111]
	v_mfma_f32_16x16x32_bf16 v[104:107], v[174:177], v[214:217], v[104:107]
	v_mfma_f32_16x16x32_bf16 v[92:95], v[144:147], v[222:225], v[92:95]
	v_mfma_f32_16x16x32_bf16 v[88:91], v[174:177], v[222:225], v[88:91]
	v_mfma_f32_16x16x32_bf16 v[76:79], v[144:147], v[230:233], v[76:79]
	v_mfma_f32_16x16x32_bf16 v[72:75], v[174:177], v[230:233], v[72:75]
	v_mfma_f32_16x16x32_bf16 v[124:127], v[170:173], v[210:213], v[124:127]
	v_mfma_f32_16x16x32_bf16 v[120:123], v[178:181], v[210:213], v[120:123]
	v_mfma_f32_16x16x32_bf16 v[108:111], v[170:173], v[218:221], v[108:111]
	v_mfma_f32_16x16x32_bf16 v[104:107], v[178:181], v[218:221], v[104:107]
	v_mfma_f32_16x16x32_bf16 v[92:95], v[170:173], v[226:229], v[92:95]
	v_mfma_f32_16x16x32_bf16 v[88:91], v[178:181], v[226:229], v[88:91]
	v_mfma_f32_16x16x32_bf16 v[76:79], v[170:173], v[234:237], v[76:79]
	v_mfma_f32_16x16x32_bf16 v[72:75], v[178:181], v[234:237], v[72:75]
	v_mfma_f32_16x16x32_bf16 v[116:119], v[182:185], v[206:209], v[116:119]
	v_mfma_f32_16x16x32_bf16 v[112:115], v[198:201], v[206:209], v[112:115]
	v_mfma_f32_16x16x32_bf16 v[100:103], v[182:185], v[214:217], v[100:103]
	v_mfma_f32_16x16x32_bf16 v[96:99], v[198:201], v[214:217], v[96:99]
	v_mfma_f32_16x16x32_bf16 v[84:87], v[182:185], v[222:225], v[84:87]
	v_mfma_f32_16x16x32_bf16 v[80:83], v[198:201], v[222:225], v[80:83]
	v_mfma_f32_16x16x32_bf16 v[68:71], v[182:185], v[230:233], v[68:71]
	v_mfma_f32_16x16x32_bf16 v[64:67], v[198:201], v[230:233], v[64:67]
	v_mfma_f32_16x16x32_bf16 v[116:119], v[186:189], v[210:213], v[116:119]
	v_mfma_f32_16x16x32_bf16 v[112:115], v[202:205], v[210:213], v[112:115]
	v_mfma_f32_16x16x32_bf16 v[100:103], v[186:189], v[218:221], v[100:103]
	v_mfma_f32_16x16x32_bf16 v[96:99], v[202:205], v[218:221], v[96:99]
	v_mfma_f32_16x16x32_bf16 v[84:87], v[186:189], v[226:229], v[84:87]
	v_mfma_f32_16x16x32_bf16 v[80:83], v[202:205], v[226:229], v[80:83]
	v_mfma_f32_16x16x32_bf16 v[68:71], v[186:189], v[234:237], v[68:71]
	v_mfma_f32_16x16x32_bf16 v[64:67], v[202:205], v[234:237], v[64:67]
	s_barrier
	s_add_i32 s6, s73, s42
	v_lshl_add_u64 v[148:149], v[148:149], 0, s[40:41]
	s_mov_b32 m0, s6
	ds_read_b128 v[206:209], v155 offset:49152
	ds_read_b128 v[210:213], v155 offset:50176
	ds_read_b128 v[214:217], v155 offset:51200
	ds_read_b128 v[218:221], v155 offset:52224
	ds_read_b128 v[222:225], v155 offset:53248
	ds_read_b128 v[226:229], v155 offset:54272
	ds_read_b128 v[230:233], v155 offset:55296
	ds_read_b128 v[234:237], v155 offset:56320
	global_load_lds_dwordx4 v[148:149], off
	s_add_i32 m0, s6, 0x2000
	s_add_u32 s6, s78, 0x40080
	v_lshl_add_u64 v[148:149], v[158:159], 0, s[40:41]
	s_addc_u32 s7, s79, 0
	s_add_i32 s73, s82, s42
	global_load_lds_dwordx4 v[148:149], off
	s_mov_b32 m0, s73
	s_nop 0
	global_load_lds_dwordx4 v130, s[6:7]
	s_add_i32 m0, s73, 0x2000
	s_nop 0
	global_load_lds_dwordx4 v134, s[6:7]
	v_lshl_add_u64 v[148:149], v[164:165], 0, s[40:41]
	s_mov_b32 m0, s4
	s_nop 0
	global_load_lds_dwordx4 v[148:149], off
	v_lshl_add_u64 v[148:149], v[190:191], 0, s[40:41]
	s_mov_b32 m0, s77
	s_nop 0
	global_load_lds_dwordx4 v[148:149], off
	s_waitcnt vmcnt(8)
	s_waitcnt lgkmcnt(0)
	s_barrier
	s_waitcnt lgkmcnt(0)
	v_mfma_f32_16x16x32_bf16 v[60:63], v[144:147], v[206:209], v[60:63]
	v_mfma_f32_16x16x32_bf16 v[56:59], v[174:177], v[206:209], v[56:59]
	v_mfma_f32_16x16x32_bf16 v[44:47], v[144:147], v[214:217], v[44:47]
	v_mfma_f32_16x16x32_bf16 v[40:43], v[174:177], v[214:217], v[40:43]
	v_mfma_f32_16x16x32_bf16 v[28:31], v[144:147], v[222:225], v[28:31]
	v_mfma_f32_16x16x32_bf16 v[24:27], v[174:177], v[222:225], v[24:27]
	v_mfma_f32_16x16x32_bf16 v[12:15], v[144:147], v[230:233], v[12:15]
	v_mfma_f32_16x16x32_bf16 v[8:11], v[174:177], v[230:233], v[8:11]
	v_mfma_f32_16x16x32_bf16 v[60:63], v[170:173], v[210:213], v[60:63]
	v_mfma_f32_16x16x32_bf16 v[56:59], v[178:181], v[210:213], v[56:59]
	v_mfma_f32_16x16x32_bf16 v[44:47], v[170:173], v[218:221], v[44:47]
	v_mfma_f32_16x16x32_bf16 v[40:43], v[178:181], v[218:221], v[40:43]
	v_mfma_f32_16x16x32_bf16 v[28:31], v[170:173], v[226:229], v[28:31]
	v_mfma_f32_16x16x32_bf16 v[24:27], v[178:181], v[226:229], v[24:27]
	v_mfma_f32_16x16x32_bf16 v[12:15], v[170:173], v[234:237], v[12:15]
	v_mfma_f32_16x16x32_bf16 v[8:11], v[178:181], v[234:237], v[8:11]
	v_mfma_f32_16x16x32_bf16 v[52:55], v[182:185], v[206:209], v[52:55]
	v_mfma_f32_16x16x32_bf16 v[48:51], v[198:201], v[206:209], v[48:51]
	v_mfma_f32_16x16x32_bf16 v[36:39], v[182:185], v[214:217], v[36:39]
	v_mfma_f32_16x16x32_bf16 v[32:35], v[198:201], v[214:217], v[32:35]
	v_mfma_f32_16x16x32_bf16 v[20:23], v[182:185], v[222:225], v[20:23]
	v_mfma_f32_16x16x32_bf16 v[16:19], v[198:201], v[222:225], v[16:19]
	v_mfma_f32_16x16x32_bf16 v[4:7], v[182:185], v[230:233], v[4:7]
	v_mfma_f32_16x16x32_bf16 v[0:3], v[198:201], v[230:233], v[0:3]
	v_mfma_f32_16x16x32_bf16 v[52:55], v[186:189], v[210:213], v[52:55]
	v_mfma_f32_16x16x32_bf16 v[48:51], v[202:205], v[210:213], v[48:51]
	v_mfma_f32_16x16x32_bf16 v[36:39], v[186:189], v[218:221], v[36:39]
	v_mfma_f32_16x16x32_bf16 v[32:35], v[202:205], v[218:221], v[32:35]
	v_mfma_f32_16x16x32_bf16 v[20:23], v[186:189], v[226:229], v[20:23]
	v_mfma_f32_16x16x32_bf16 v[16:19], v[202:205], v[226:229], v[16:19]
	v_mfma_f32_16x16x32_bf16 v[4:7], v[186:189], v[234:237], v[4:7]
	v_mfma_f32_16x16x32_bf16 v[0:3], v[202:205], v[234:237], v[0:3]
	s_barrier
	s_add_i32 s72, s72, 2
	s_add_u32 s60, s60, 0x100
	s_addc_u32 s61, s61, 0
	s_add_u32 s69, s69, 0x100
	s_addc_u32 s33, s33, 0
	s_cmp_gt_u32 s72, 13
	s_cbranch_scc0 .LBB0_1698
	s_and_b64 vcc, exec, s[50:51]
	s_cbranch_vccz .LBB0_1701
	s_barrier

; #define PG8_STAGE(bufoff, gbase, voff) do { _Pragma("unroll") for (int _i = 0; _i < 2; ++_i) \
;         __builtin_amdgcn_global_load_lds((const unsigned*)((const char*)(gbase) + (voff)[_i]), (PG8_LAS unsigned*)(lds + (bufoff) + ldsw + _i * 8192), 16, 0, 0); } while (0)
; #define PG8_LDA(dst, b, h) do { _Pragma("unroll") for (int m = 0; m < 4; ++m) _Pragma("unroll") for (int k = 0; k < 2; ++k) dst[m][k] = *(const PG8_LAS bf16x8*)(lds + PG8_SA(b, h) + aoff + m * 2048 + k * 1024); } while (0)
; #define PG8_LDB(dst, b, h) do { _Pragma("unroll") for (int n = 0; n < 2; ++n) _Pragma("unroll") for (int k = 0; k < 2; ++k) dst[n][k] = *(const PG8_LAS bf16x8*)(lds + PG8_SB(b, h) + boff + n * 2048 + k * 1024); } while (0)
; #define PG8_MMA(ai, bj, At, Bt) do { __builtin_amdgcn_s_setprio(1); _Pragma("unroll") for (int m = 0; m < 4; ++m) _Pragma("unroll") for (int n = 0; n < 2; ++n) _Pragma("unroll") for (int k = 0; k < 2; ++k) \
;         acc[ai][bj][m][n] = __builtin_amdgcn_mfma_f32_16x16x32_bf16(Bt[n][k], At[m][k], acc[ai][bj][m][n], 0, 0, 0); __builtin_amdgcn_s_setprio(0); } while (0)
; #define PG8_WAIT_V(n) asm volatile("s_waitcnt vmcnt(" #n ")" ::: "memory")
; #define PG8_BAR __builtin_amdgcn_s_barrier()
; template <class Epi, class Sched, bool ALIGN_EPI = false, bool SP2 = false>
; __device__ __forceinline__ void gemm_phase(PG8_LAS unsigned char* lds, const Gemm g, const Sched& S, const Epi& E) {
;     ...
;         for (int t = 0; t < nt; t += 2) {
;             const bool last = (t == nt - 2);
;             const char* a1 = cA + (size_t)(t + 1) * kstep;
;             const char* a2 = last ? nA : cA + (size_t)(t + 2) * kstep; const char* b2 = last ? nB : cB + (size_t)(t + 2) * kstep;
;             const char* a3 = a2 + kstep; const char* b3 = b2 + kstep;
;             if (last && has_next) S.a_ready(nxt);
;             if constexpr (SP2) {
;             PG8_LDB(B0, 0, 0); PG8_LDB(B1, 0, 1); PG8_SCHED; PG8_LDA(At, 0, 0); PG8_STAGE(PG8_SA(1, 1), a1 + hstep, voffA);
;             PG8_WAIT_V(8); PG8_WAIT_L(0); PG8_BAR; PG8_MMA(0, 0, At, B0); PG8_MMA(0, 1, At, B1); PG8_BAR; PG8_SCHED;
;             PG8_LDA(At, 0, 1); PG8_STAGE(PG8_SB(0, 0), b2, voffB); PG8_STAGE(PG8_SB(0, 1), b2 + hstep, voffB); PG8_STAGE(PG8_SA(0, 0), a2, voffA);
;             PG8_WAIT_V(8); PG8_WAIT_L(0); PG8_BAR; PG8_MMA(1, 0, At, B0); PG8_MMA(1, 1, At, B1); PG8_BAR; PG8_SCHED;
.LBB0_1822:
	ds_read_b128 v[144:147], v154
	ds_read_b128 v[168:171], v154 offset:1024
	ds_read_b128 v[172:175], v154 offset:2048
	ds_read_b128 v[176:179], v154 offset:3072
	ds_read_b128 v[180:183], v155
	ds_read_b128 v[184:187], v155 offset:1024
	ds_read_b128 v[188:191], v155 offset:2048
	ds_read_b128 v[198:201], v155 offset:3072
	s_add_u32 s6, s50, 0xfffc0080
	s_addc_u32 s7, s51, -1
	s_cmp_eq_u32 s72, 12
	s_cselect_b32 s55, s39, s7
	s_cselect_b32 s54, s69, s6
	s_cselect_b32 s53, s37, s33
	s_cselect_b32 s52, s74, s75
	s_add_i32 m0, s27, 0xc000
	ds_read_b128 v[202:205], v156
	ds_read_b128 v[206:209], v156 offset:1024
	ds_read_b128 v[210:213], v156 offset:2048
	ds_read_b128 v[214:217], v156 offset:3072
	ds_read_b128 v[218:221], v156 offset:4096
	ds_read_b128 v[222:225], v156 offset:5120
	ds_read_b128 v[226:229], v156 offset:6144
	ds_read_b128 v[230:233], v156 offset:7168
	global_load_lds_dwordx4 v136, s[50:51]
	s_add_i32 m0, s27, 0xe000
	s_nop 0
	global_load_lds_dwordx4 v138, s[50:51]
	s_waitcnt vmcnt(8)
	s_waitcnt lgkmcnt(0)
	s_barrier
	s_waitcnt lgkmcnt(0)
	v_mfma_f32_16x16x32_bf16 v[124:127], v[144:147], v[202:205], v[124:127]
	v_mfma_f32_16x16x32_bf16 v[116:119], v[172:175], v[202:205], v[116:119]
	v_mfma_f32_16x16x32_bf16 v[108:111], v[144:147], v[210:213], v[108:111]
	v_mfma_f32_16x16x32_bf16 v[100:103], v[172:175], v[210:213], v[100:103]
	v_mfma_f32_16x16x32_bf16 v[92:95], v[144:147], v[218:221], v[92:95]
	v_mfma_f32_16x16x32_bf16 v[84:87], v[172:175], v[218:221], v[84:87]
	v_mfma_f32_16x16x32_bf16 v[76:79], v[144:147], v[226:229], v[76:79]
	v_mfma_f32_16x16x32_bf16 v[68:71], v[172:175], v[226:229], v[68:71]
	v_mfma_f32_16x16x32_bf16 v[124:127], v[168:171], v[206:209], v[124:127]
	v_mfma_f32_16x16x32_bf16 v[116:119], v[176:179], v[206:209], v[116:119]
	v_mfma_f32_16x16x32_bf16 v[108:111], v[168:171], v[214:217], v[108:111]
	v_mfma_f32_16x16x32_bf16 v[100:103], v[176:179], v[214:217], v[100:103]
	v_mfma_f32_16x16x32_bf16 v[92:95], v[168:171], v[222:225], v[92:95]
	v_mfma_f32_16x16x32_bf16 v[84:87], v[176:179], v[222:225], v[84:87]
	v_mfma_f32_16x16x32_bf16 v[76:79], v[168:171], v[230:233], v[76:79]
	v_mfma_f32_16x16x32_bf16 v[68:71], v[176:179], v[230:233], v[68:71]
	v_mfma_f32_16x16x32_bf16 v[120:123], v[180:183], v[202:205], v[120:123]
	v_mfma_f32_16x16x32_bf16 v[112:115], v[188:191], v[202:205], v[112:115]
	v_mfma_f32_16x16x32_bf16 v[104:107], v[180:183], v[210:213], v[104:107]
	v_mfma_f32_16x16x32_bf16 v[96:99], v[188:191], v[210:213], v[96:99]
	v_mfma_f32_16x16x32_bf16 v[88:91], v[180:183], v[218:221], v[88:91]
	v_mfma_f32_16x16x32_bf16 v[80:83], v[188:191], v[218:221], v[80:83]
	v_mfma_f32_16x16x32_bf16 v[72:75], v[180:183], v[226:229], v[72:75]
	v_mfma_f32_16x16x32_bf16 v[64:67], v[188:191], v[226:229], v[64:67]
	v_mfma_f32_16x16x32_bf16 v[120:123], v[184:187], v[206:209], v[120:123]
	v_mfma_f32_16x16x32_bf16 v[112:115], v[198:201], v[206:209], v[112:115]
	v_mfma_f32_16x16x32_bf16 v[104:107], v[184:187], v[214:217], v[104:107]
	v_mfma_f32_16x16x32_bf16 v[96:99], v[198:201], v[214:217], v[96:99]
	v_mfma_f32_16x16x32_bf16 v[88:91], v[184:187], v[222:225], v[88:91]
	v_mfma_f32_16x16x32_bf16 v[80:83], v[198:201], v[222:225], v[80:83]
	v_mfma_f32_16x16x32_bf16 v[72:75], v[184:187], v[230:233], v[72:75]
	v_mfma_f32_16x16x32_bf16 v[64:67], v[198:201], v[230:233], v[64:67]
	s_barrier
	s_add_i32 s6, s59, s26
	v_lshl_add_u64 v[148:149], s[52:53], 0, v[132:133]
	s_mov_b32 m0, s6
	ds_read_b128 v[202:205], v156 offset:16384
	ds_read_b128 v[206:209], v156 offset:17408
	ds_read_b128 v[210:213], v156 offset:18432
	ds_read_b128 v[214:217], v156 offset:19456
	ds_read_b128 v[218:221], v156 offset:20480
	ds_read_b128 v[222:225], v156 offset:21504
	ds_read_b128 v[226:229], v156 offset:22528
	ds_read_b128 v[230:233], v156 offset:23552
	global_load_lds_dwordx4 v[148:149], off
	s_add_i32 m0, s6, 0x2000
	s_add_u32 s6, s52, 0x40000
	v_lshl_add_u64 v[158:159], s[52:53], 0, v[128:129]
	s_addc_u32 s7, s53, 0
	s_add_i32 s73, s60, s26
	global_load_lds_dwordx4 v[158:159], off
	s_mov_b32 m0, s73
	v_lshl_add_u64 v[234:235], s[54:55], 0, v[130:131]
	global_load_lds_dwordx4 v132, s[6:7]
	s_add_i32 m0, s73, 0x2000
	s_nop 0
	global_load_lds_dwordx4 v128, s[6:7]
	v_lshl_add_u64 v[164:165], s[54:55], 0, v[134:135]
	s_mov_b32 m0, s27
	s_nop 0
	global_load_lds_dwordx4 v[164:165], off
	s_mov_b32 m0, s42
	s_nop 0
	global_load_lds_dwordx4 v[234:235], off
	s_waitcnt vmcnt(8)
	s_waitcnt lgkmcnt(0)
	s_barrier
	s_waitcnt lgkmcnt(0)
	v_mfma_f32_16x16x32_bf16 v[60:63], v[144:147], v[202:205], v[60:63]
	v_mfma_f32_16x16x32_bf16 v[52:55], v[172:175], v[202:205], v[52:55]
	v_mfma_f32_16x16x32_bf16 v[44:47], v[144:147], v[210:213], v[44:47]
	v_mfma_f32_16x16x32_bf16 v[36:39], v[172:175], v[210:213], v[36:39]
	v_mfma_f32_16x16x32_bf16 v[28:31], v[144:147], v[218:221], v[28:31]
	v_mfma_f32_16x16x32_bf16 v[20:23], v[172:175], v[218:221], v[20:23]
	v_mfma_f32_16x16x32_bf16 v[12:15], v[144:147], v[226:229], v[12:15]
	v_mfma_f32_16x16x32_bf16 v[4:7], v[172:175], v[226:229], v[4:7]
	v_mfma_f32_16x16x32_bf16 v[60:63], v[168:171], v[206:209], v[60:63]
	v_mfma_f32_16x16x32_bf16 v[52:55], v[176:179], v[206:209], v[52:55]
	v_mfma_f32_16x16x32_bf16 v[44:47], v[168:171], v[214:217], v[44:47]
	v_mfma_f32_16x16x32_bf16 v[36:39], v[176:179], v[214:217], v[36:39]
	v_mfma_f32_16x16x32_bf16 v[28:31], v[168:171], v[222:225], v[28:31]
	v_mfma_f32_16x16x32_bf16 v[20:23], v[176:179], v[222:225], v[20:23]
	v_mfma_f32_16x16x32_bf16 v[12:15], v[168:171], v[230:233], v[12:15]
	v_mfma_f32_16x16x32_bf16 v[4:7], v[176:179], v[230:233], v[4:7]
	v_mfma_f32_16x16x32_bf16 v[56:59], v[180:183], v[202:205], v[56:59]
	v_mfma_f32_16x16x32_bf16 v[48:51], v[188:191], v[202:205], v[48:51]
	v_mfma_f32_16x16x32_bf16 v[40:43], v[180:183], v[210:213], v[40:43]
	v_mfma_f32_16x16x32_bf16 v[32:35], v[188:191], v[210:213], v[32:35]
	v_mfma_f32_16x16x32_bf16 v[24:27], v[180:183], v[218:221], v[24:27]
	v_mfma_f32_16x16x32_bf16 v[16:19], v[188:191], v[218:221], v[16:19]
	v_mfma_f32_16x16x32_bf16 v[8:11], v[180:183], v[226:229], v[8:11]
	v_mfma_f32_16x16x32_bf16 v[0:3], v[188:191], v[226:229], v[0:3]
	v_mfma_f32_16x16x32_bf16 v[56:59], v[184:187], v[206:209], v[56:59]
	v_mfma_f32_16x16x32_bf16 v[48:51], v[198:201], v[206:209], v[48:51]
	v_mfma_f32_16x16x32_bf16 v[40:43], v[184:187], v[214:217], v[40:43]
	v_mfma_f32_16x16x32_bf16 v[32:35], v[198:201], v[214:217], v[32:35]
	v_mfma_f32_16x16x32_bf16 v[24:27], v[184:187], v[222:225], v[24:27]
	v_mfma_f32_16x16x32_bf16 v[16:19], v[198:201], v[222:225], v[16:19]
	v_mfma_f32_16x16x32_bf16 v[8:11], v[184:187], v[230:233], v[8:11]
	v_mfma_f32_16x16x32_bf16 v[0:3], v[198:201], v[230:233], v[0:3]
	s_barrier
; #define PG8_STAGE(bufoff, gbase, voff) do { _Pragma("unroll") for (int _i = 0; _i < 2; ++_i) \
;         __builtin_amdgcn_global_load_lds((const unsigned*)((const char*)(gbase) + (voff)[_i]), (PG8_LAS unsigned*)(lds + (bufoff) + ldsw + _i * 8192), 16, 0, 0); } while (0)
; #define PG8_LDA(dst, b, h) do { _Pragma("unroll") for (int m = 0; m < 4; ++m) _Pragma("unroll") for (int k = 0; k < 2; ++k) dst[m][k] = *(const PG8_LAS bf16x8*)(lds + PG8_SA(b, h) + aoff + m * 2048 + k * 1024); } while (0)
; #define PG8_LDB(dst, b, h) do { _Pragma("unroll") for (int n = 0; n < 2; ++n) _Pragma("unroll") for (int k = 0; k < 2; ++k) dst[n][k] = *(const PG8_LAS bf16x8*)(lds + PG8_SB(b, h) + boff + n * 2048 + k * 1024); } while (0)
; #define PG8_MMA(ai, bj, At, Bt) do { __builtin_amdgcn_s_setprio(1); _Pragma("unroll") for (int m = 0; m < 4; ++m) _Pragma("unroll") for (int n = 0; n < 2; ++n) _Pragma("unroll") for (int k = 0; k < 2; ++k) \
;         acc[ai][bj][m][n] = __builtin_amdgcn_mfma_f32_16x16x32_bf16(Bt[n][k], At[m][k], acc[ai][bj][m][n], 0, 0, 0); __builtin_amdgcn_s_setprio(0); } while (0)
; #define PG8_WAIT_V(n) asm volatile("s_waitcnt vmcnt(" #n ")" ::: "memory")
; #define PG8_WAIT_L(n) asm volatile("s_waitcnt lgkmcnt(" #n ")" ::: "memory")
; #define PG8_BAR __builtin_amdgcn_s_barrier()
; #define PG8_SCHED __builtin_amdgcn_sched_barrier(0)
; template <class Epi, class Sched, bool ALIGN_EPI = false, bool SP2 = false>
; __device__ __forceinline__ void gemm_phase(PG8_LAS unsigned char* lds, const Gemm g, const Sched& S, const Epi& E) {
;     ...
;         for (int t = 0; t < nt; t += 2) {
;             const bool last = (t == nt - 2);
;     ...
;             PG8_LDB(B0, 1, 0); PG8_LDB(B1, 1, 1); PG8_SCHED; PG8_LDA(At, 1, 0); PG8_STAGE(PG8_SA(0, 1), a2 + hstep, voffA);
;             PG8_WAIT_V(8); PG8_WAIT_L(0); PG8_BAR; PG8_MMA(0, 0, At, B0); PG8_MMA(0, 1, At, B1); PG8_BAR; PG8_SCHED;
;             PG8_LDA(At, 1, 1); PG8_STAGE(PG8_SB(1, 0), b3, voffB); PG8_STAGE(PG8_SB(1, 1), b3 + hstep, voffB); PG8_STAGE(PG8_SA(1, 0), a3, voffA);
;             PG8_WAIT_V(8); PG8_WAIT_L(0); PG8_BAR; PG8_MMA(1, 0, At, B0); PG8_MMA(1, 1, At, B1); PG8_BAR; PG8_SCHED;
	s_add_i32 s73, 0, 0x18000
	v_add_u32_e32 v157, s73, v151
	s_add_i32 s76, 0, 0x1c000
	ds_read_b128 v[144:147], v157
	ds_read_b128 v[168:171], v157 offset:1024
	ds_read_b128 v[172:175], v157 offset:2048
	ds_read_b128 v[176:179], v157 offset:3072
	v_add_u32_e32 v157, s76, v151
	ds_read_b128 v[180:183], v157
	ds_read_b128 v[184:187], v157 offset:1024
	ds_read_b128 v[188:191], v157 offset:2048
	ds_read_b128 v[198:201], v157 offset:3072
	s_add_u32 s6, s54, 0x40000
	s_addc_u32 s7, s55, 0
	s_mov_b32 m0, s43
	ds_read_b128 v[202:205], v156 offset:32768
	ds_read_b128 v[206:209], v156 offset:33792
	ds_read_b128 v[210:213], v156 offset:34816
	ds_read_b128 v[214:217], v156 offset:35840
	ds_read_b128 v[218:221], v156 offset:36864
	ds_read_b128 v[222:225], v156 offset:37888
	ds_read_b128 v[226:229], v156 offset:38912
	ds_read_b128 v[230:233], v156 offset:39936
	global_load_lds_dwordx4 v134, s[6:7]
	s_mov_b32 m0, s56
	s_nop 0
	global_load_lds_dwordx4 v130, s[6:7]
	s_waitcnt vmcnt(8)
	s_waitcnt lgkmcnt(0)
	s_barrier
	s_waitcnt lgkmcnt(0)
	v_mfma_f32_16x16x32_bf16 v[124:127], v[144:147], v[202:205], v[124:127]
	v_mfma_f32_16x16x32_bf16 v[116:119], v[172:175], v[202:205], v[116:119]
	v_mfma_f32_16x16x32_bf16 v[108:111], v[144:147], v[210:213], v[108:111]
	v_mfma_f32_16x16x32_bf16 v[100:103], v[172:175], v[210:213], v[100:103]
	v_mfma_f32_16x16x32_bf16 v[92:95], v[144:147], v[218:221], v[92:95]
	v_mfma_f32_16x16x32_bf16 v[84:87], v[172:175], v[218:221], v[84:87]
	v_mfma_f32_16x16x32_bf16 v[76:79], v[144:147], v[226:229], v[76:79]
	v_mfma_f32_16x16x32_bf16 v[68:71], v[172:175], v[226:229], v[68:71]
	v_mfma_f32_16x16x32_bf16 v[124:127], v[168:171], v[206:209], v[124:127]
	v_mfma_f32_16x16x32_bf16 v[116:119], v[176:179], v[206:209], v[116:119]
	v_mfma_f32_16x16x32_bf16 v[108:111], v[168:171], v[214:217], v[108:111]
	v_mfma_f32_16x16x32_bf16 v[100:103], v[176:179], v[214:217], v[100:103]
	v_mfma_f32_16x16x32_bf16 v[92:95], v[168:171], v[222:225], v[92:95]
	v_mfma_f32_16x16x32_bf16 v[84:87], v[176:179], v[222:225], v[84:87]
	v_mfma_f32_16x16x32_bf16 v[76:79], v[168:171], v[230:233], v[76:79]
	v_mfma_f32_16x16x32_bf16 v[68:71], v[176:179], v[230:233], v[68:71]
	v_mfma_f32_16x16x32_bf16 v[120:123], v[180:183], v[202:205], v[120:123]
	v_mfma_f32_16x16x32_bf16 v[112:115], v[188:191], v[202:205], v[112:115]
	v_mfma_f32_16x16x32_bf16 v[104:107], v[180:183], v[210:213], v[104:107]
	v_mfma_f32_16x16x32_bf16 v[96:99], v[188:191], v[210:213], v[96:99]
	v_mfma_f32_16x16x32_bf16 v[88:91], v[180:183], v[218:221], v[88:91]
	v_mfma_f32_16x16x32_bf16 v[80:83], v[188:191], v[218:221], v[80:83]
	v_mfma_f32_16x16x32_bf16 v[72:75], v[180:183], v[226:229], v[72:75]
	v_mfma_f32_16x16x32_bf16 v[64:67], v[188:191], v[226:229], v[64:67]
	v_mfma_f32_16x16x32_bf16 v[120:123], v[184:187], v[206:209], v[120:123]
	v_mfma_f32_16x16x32_bf16 v[112:115], v[198:201], v[206:209], v[112:115]
	v_mfma_f32_16x16x32_bf16 v[104:107], v[184:187], v[214:217], v[104:107]
	v_mfma_f32_16x16x32_bf16 v[96:99], v[198:201], v[214:217], v[96:99]
	v_mfma_f32_16x16x32_bf16 v[88:91], v[184:187], v[222:225], v[88:91]
	v_mfma_f32_16x16x32_bf16 v[80:83], v[198:201], v[222:225], v[80:83]
	v_mfma_f32_16x16x32_bf16 v[72:75], v[184:187], v[230:233], v[72:75]
	v_mfma_f32_16x16x32_bf16 v[64:67], v[198:201], v[230:233], v[64:67]
	s_barrier
	s_add_i32 s6, s73, s26
	v_lshl_add_u64 v[148:149], v[148:149], 0, s[30:31]
	s_mov_b32 m0, s6
	ds_read_b128 v[202:205], v156 offset:49152
	ds_read_b128 v[206:209], v156 offset:50176
	ds_read_b128 v[210:213], v156 offset:51200
	ds_read_b128 v[214:217], v156 offset:52224
	ds_read_b128 v[218:221], v156 offset:53248
	ds_read_b128 v[222:225], v156 offset:54272
	ds_read_b128 v[226:229], v156 offset:55296
	ds_read_b128 v[230:233], v156 offset:56320
	global_load_lds_dwordx4 v[148:149], off
	s_add_i32 m0, s6, 0x2000
	s_add_u32 s6, s52, 0x40080
	v_lshl_add_u64 v[148:149], v[158:159], 0, s[30:31]
	s_addc_u32 s7, s53, 0
	s_add_i32 s52, s76, s26
	global_load_lds_dwordx4 v[148:149], off
	s_mov_b32 m0, s52
	s_nop 0
	global_load_lds_dwordx4 v132, s[6:7]
	s_add_i32 m0, s52, 0x2000
	s_nop 0
	global_load_lds_dwordx4 v128, s[6:7]
	v_lshl_add_u64 v[148:149], v[164:165], 0, s[30:31]
	s_mov_b32 m0, s57
	s_nop 0
	global_load_lds_dwordx4 v[148:149], off
	v_lshl_add_u64 v[148:149], v[234:235], 0, s[30:31]
	s_mov_b32 m0, s58
	s_nop 0
	global_load_lds_dwordx4 v[148:149], off
	s_waitcnt vmcnt(8)
	s_waitcnt lgkmcnt(0)
	s_barrier
	s_waitcnt lgkmcnt(0)
	v_mfma_f32_16x16x32_bf16 v[60:63], v[144:147], v[202:205], v[60:63]
	v_mfma_f32_16x16x32_bf16 v[52:55], v[172:175], v[202:205], v[52:55]
	v_mfma_f32_16x16x32_bf16 v[44:47], v[144:147], v[210:213], v[44:47]
	v_mfma_f32_16x16x32_bf16 v[36:39], v[172:175], v[210:213], v[36:39]
	v_mfma_f32_16x16x32_bf16 v[28:31], v[144:147], v[218:221], v[28:31]
	v_mfma_f32_16x16x32_bf16 v[20:23], v[172:175], v[218:221], v[20:23]
	v_mfma_f32_16x16x32_bf16 v[12:15], v[144:147], v[226:229], v[12:15]
	v_mfma_f32_16x16x32_bf16 v[4:7], v[172:175], v[226:229], v[4:7]
	v_mfma_f32_16x16x32_bf16 v[60:63], v[168:171], v[206:209], v[60:63]
	v_mfma_f32_16x16x32_bf16 v[52:55], v[176:179], v[206:209], v[52:55]
	v_mfma_f32_16x16x32_bf16 v[44:47], v[168:171], v[214:217], v[44:47]
	v_mfma_f32_16x16x32_bf16 v[36:39], v[176:179], v[214:217], v[36:39]
	v_mfma_f32_16x16x32_bf16 v[28:31], v[168:171], v[222:225], v[28:31]
	v_mfma_f32_16x16x32_bf16 v[20:23], v[176:179], v[222:225], v[20:23]
	v_mfma_f32_16x16x32_bf16 v[12:15], v[168:171], v[230:233], v[12:15]
	v_mfma_f32_16x16x32_bf16 v[4:7], v[176:179], v[230:233], v[4:7]
	v_mfma_f32_16x16x32_bf16 v[56:59], v[180:183], v[202:205], v[56:59]
	v_mfma_f32_16x16x32_bf16 v[48:51], v[188:191], v[202:205], v[48:51]
	v_mfma_f32_16x16x32_bf16 v[40:43], v[180:183], v[210:213], v[40:43]
	v_mfma_f32_16x16x32_bf16 v[32:35], v[188:191], v[210:213], v[32:35]
	v_mfma_f32_16x16x32_bf16 v[24:27], v[180:183], v[218:221], v[24:27]
	v_mfma_f32_16x16x32_bf16 v[16:19], v[188:191], v[218:221], v[16:19]
	v_mfma_f32_16x16x32_bf16 v[8:11], v[180:183], v[226:229], v[8:11]
	v_mfma_f32_16x16x32_bf16 v[0:3], v[188:191], v[226:229], v[0:3]
	v_mfma_f32_16x16x32_bf16 v[56:59], v[184:187], v[206:209], v[56:59]
	v_mfma_f32_16x16x32_bf16 v[48:51], v[198:201], v[206:209], v[48:51]
	v_mfma_f32_16x16x32_bf16 v[40:43], v[184:187], v[214:217], v[40:43]
	v_mfma_f32_16x16x32_bf16 v[32:35], v[198:201], v[214:217], v[32:35]
	v_mfma_f32_16x16x32_bf16 v[24:27], v[184:187], v[222:225], v[24:27]
	v_mfma_f32_16x16x32_bf16 v[16:19], v[198:201], v[222:225], v[16:19]
	v_mfma_f32_16x16x32_bf16 v[8:11], v[184:187], v[230:233], v[8:11]
	v_mfma_f32_16x16x32_bf16 v[0:3], v[198:201], v[230:233], v[0:3]
	s_barrier
	s_add_i32 s72, s72, 2
	s_add_u32 s50, s50, 0x100
	s_addc_u32 s51, s51, 0
	s_add_u32 s75, s75, 0x100
	s_addc_u32 s33, s33, 0
	s_cmp_gt_u32 s72, 13
	s_cbranch_scc0 .LBB0_1822
	v_readlane_b32 s74, v243, 57
	s_and_b64 vcc, exec, s[34:35]
	v_readlane_b32 s75, v243, 58
	s_cbranch_vccz .LBB0_1825
	s_barrier

; #define PG8_STAGE(bufoff, gbase, voff) do { _Pragma("unroll") for (int _i = 0; _i < 2; ++_i) \
;         __builtin_amdgcn_global_load_lds((const unsigned*)((const char*)(gbase) + (voff)[_i]), (PG8_LAS unsigned*)(lds + (bufoff) + ldsw + _i * 8192), 16, 0, 0); } while (0)
; #define PG8_LDA(dst, b, h) do { _Pragma("unroll") for (int m = 0; m < 4; ++m) _Pragma("unroll") for (int k = 0; k < 2; ++k) dst[m][k] = *(const PG8_LAS bf16x8*)(lds + PG8_SA(b, h) + aoff + m * 2048 + k * 1024); } while (0)
; #define PG8_LDB(dst, b, h) do { _Pragma("unroll") for (int n = 0; n < 2; ++n) _Pragma("unroll") for (int k = 0; k < 2; ++k) dst[n][k] = *(const PG8_LAS bf16x8*)(lds + PG8_SB(b, h) + boff + n * 2048 + k * 1024); } while (0)
; #define PG8_MMA(ai, bj, At, Bt) do { __builtin_amdgcn_s_setprio(1); _Pragma("unroll") for (int m = 0; m < 4; ++m) _Pragma("unroll") for (int n = 0; n < 2; ++n) _Pragma("unroll") for (int k = 0; k < 2; ++k) \
;         acc[ai][bj][m][n] = __builtin_amdgcn_mfma_f32_16x16x32_bf16(Bt[n][k], At[m][k], acc[ai][bj][m][n], 0, 0, 0); __builtin_amdgcn_s_setprio(0); } while (0)
; #define PG8_WAIT_V(n) asm volatile("s_waitcnt vmcnt(" #n ")" ::: "memory")
; #define PG8_BAR __builtin_amdgcn_s_barrier()
; template <class Epi, class Sched, bool ALIGN_EPI = false, bool SP2 = false>
; __device__ __forceinline__ void gemm_phase(PG8_LAS unsigned char* lds, const Gemm g, const Sched& S, const Epi& E) {
;     ...
;         for (int t = 0; t < nt; t += 2) {
;             const bool last = (t == nt - 2);
;             const char* a1 = cA + (size_t)(t + 1) * kstep;
;             const char* a2 = last ? nA : cA + (size_t)(t + 2) * kstep; const char* b2 = last ? nB : cB + (size_t)(t + 2) * kstep;
;             const char* a3 = a2 + kstep; const char* b3 = b2 + kstep;
;             if (last && has_next) S.a_ready(nxt);
;             if constexpr (SP2) {
;             PG8_LDB(B0, 0, 0); PG8_LDB(B1, 0, 1); PG8_SCHED; PG8_LDA(At, 0, 0); PG8_STAGE(PG8_SA(1, 1), a1 + hstep, voffA);
;             PG8_WAIT_V(8); PG8_WAIT_L(0); PG8_BAR; PG8_MMA(0, 0, At, B0); PG8_MMA(0, 1, At, B1); PG8_BAR; PG8_SCHED;
;             PG8_LDA(At, 0, 1); PG8_STAGE(PG8_SB(0, 0), b2, voffB); PG8_STAGE(PG8_SB(0, 1), b2 + hstep, voffB); PG8_STAGE(PG8_SA(0, 0), a2, voffA);
;             PG8_WAIT_V(8); PG8_WAIT_L(0); PG8_BAR; PG8_MMA(1, 0, At, B0); PG8_MMA(1, 1, At, B1); PG8_BAR; PG8_SCHED;
.LBB0_1935:
	ds_read_b128 v[144:147], v153
	ds_read_b128 v[168:171], v153 offset:1024
	ds_read_b128 v[172:175], v153 offset:2048
	ds_read_b128 v[176:179], v153 offset:3072
	ds_read_b128 v[180:183], v154
	ds_read_b128 v[184:187], v154 offset:1024
	ds_read_b128 v[188:191], v154 offset:2048
	ds_read_b128 v[198:201], v154 offset:3072
	s_add_u32 s50, s48, 0x100
	s_addc_u32 s51, s49, 0
	s_cmp_eq_u32 s72, 40
	s_cselect_b32 s55, s41, s51
	s_cselect_b32 s54, s40, s50
	s_cselect_b32 s53, s47, s77
	s_cselect_b32 s52, s46, s33
	s_add_i32 m0, s58, 0xc000
	ds_read_b128 v[202:205], v155
	ds_read_b128 v[206:209], v155 offset:1024
	ds_read_b128 v[210:213], v155 offset:2048
	ds_read_b128 v[214:217], v155 offset:3072
	ds_read_b128 v[218:221], v155 offset:4096
	ds_read_b128 v[222:225], v155 offset:5120
	ds_read_b128 v[226:229], v155 offset:6144
	ds_read_b128 v[230:233], v155 offset:7168
	global_load_lds_dwordx4 v136, s[48:49]
	s_add_i32 m0, s58, 0xe000
	s_nop 0
	global_load_lds_dwordx4 v138, s[48:49]
	s_waitcnt vmcnt(8)
	s_waitcnt lgkmcnt(0)
	s_barrier
	s_waitcnt lgkmcnt(0)
	v_mfma_f32_16x16x32_bf16 v[124:127], v[144:147], v[202:205], v[124:127]
	v_mfma_f32_16x16x32_bf16 v[120:123], v[172:175], v[202:205], v[120:123]
	v_mfma_f32_16x16x32_bf16 v[108:111], v[144:147], v[210:213], v[108:111]
	v_mfma_f32_16x16x32_bf16 v[104:107], v[172:175], v[210:213], v[104:107]
	v_mfma_f32_16x16x32_bf16 v[92:95], v[144:147], v[218:221], v[92:95]
	v_mfma_f32_16x16x32_bf16 v[88:91], v[172:175], v[218:221], v[88:91]
	v_mfma_f32_16x16x32_bf16 v[76:79], v[144:147], v[226:229], v[76:79]
	v_mfma_f32_16x16x32_bf16 v[72:75], v[172:175], v[226:229], v[72:75]
	v_mfma_f32_16x16x32_bf16 v[124:127], v[168:171], v[206:209], v[124:127]
	v_mfma_f32_16x16x32_bf16 v[120:123], v[176:179], v[206:209], v[120:123]
	v_mfma_f32_16x16x32_bf16 v[108:111], v[168:171], v[214:217], v[108:111]
	v_mfma_f32_16x16x32_bf16 v[104:107], v[176:179], v[214:217], v[104:107]
	v_mfma_f32_16x16x32_bf16 v[92:95], v[168:171], v[222:225], v[92:95]
	v_mfma_f32_16x16x32_bf16 v[88:91], v[176:179], v[222:225], v[88:91]
	v_mfma_f32_16x16x32_bf16 v[76:79], v[168:171], v[230:233], v[76:79]
	v_mfma_f32_16x16x32_bf16 v[72:75], v[176:179], v[230:233], v[72:75]
	v_mfma_f32_16x16x32_bf16 v[116:119], v[180:183], v[202:205], v[116:119]
	v_mfma_f32_16x16x32_bf16 v[112:115], v[188:191], v[202:205], v[112:115]
	v_mfma_f32_16x16x32_bf16 v[100:103], v[180:183], v[210:213], v[100:103]
	v_mfma_f32_16x16x32_bf16 v[96:99], v[188:191], v[210:213], v[96:99]
	v_mfma_f32_16x16x32_bf16 v[84:87], v[180:183], v[218:221], v[84:87]
	v_mfma_f32_16x16x32_bf16 v[80:83], v[188:191], v[218:221], v[80:83]
	v_mfma_f32_16x16x32_bf16 v[68:71], v[180:183], v[226:229], v[68:71]
	v_mfma_f32_16x16x32_bf16 v[64:67], v[188:191], v[226:229], v[64:67]
	v_mfma_f32_16x16x32_bf16 v[116:119], v[184:187], v[206:209], v[116:119]
	v_mfma_f32_16x16x32_bf16 v[112:115], v[198:201], v[206:209], v[112:115]
	v_mfma_f32_16x16x32_bf16 v[100:103], v[184:187], v[214:217], v[100:103]
	v_mfma_f32_16x16x32_bf16 v[96:99], v[198:201], v[214:217], v[96:99]
	v_mfma_f32_16x16x32_bf16 v[84:87], v[184:187], v[222:225], v[84:87]
	v_mfma_f32_16x16x32_bf16 v[80:83], v[198:201], v[222:225], v[80:83]
	v_mfma_f32_16x16x32_bf16 v[68:71], v[184:187], v[230:233], v[68:71]
	v_mfma_f32_16x16x32_bf16 v[64:67], v[198:201], v[230:233], v[64:67]
	s_barrier
	s_add_i32 s6, s26, s57
	v_lshl_add_u64 v[148:149], s[52:53], 0, v[130:131]
	s_mov_b32 m0, s6
	ds_read_b128 v[202:205], v155 offset:16384
	ds_read_b128 v[206:209], v155 offset:17408
	ds_read_b128 v[210:213], v155 offset:18432
	ds_read_b128 v[214:217], v155 offset:19456
	ds_read_b128 v[218:221], v155 offset:20480
	ds_read_b128 v[222:225], v155 offset:21504
	ds_read_b128 v[226:229], v155 offset:22528
	ds_read_b128 v[230:233], v155 offset:23552
	global_load_lds_dwordx4 v[148:149], off
	s_add_i32 m0, s6, 0x2000
	s_add_u32 s6, s52, 0xb0000
	v_lshl_add_u64 v[158:159], s[52:53], 0, v[134:135]
	s_addc_u32 s7, s53, 0
	s_add_i32 s48, s74, s57
	global_load_lds_dwordx4 v[158:159], off
	s_mov_b32 m0, s48
	v_lshl_add_u64 v[234:235], s[54:55], 0, v[132:133]
	global_load_lds_dwordx4 v130, s[6:7]
	s_add_i32 m0, s48, 0x2000
	s_nop 0
	global_load_lds_dwordx4 v134, s[6:7]
	v_lshl_add_u64 v[164:165], s[54:55], 0, v[128:129]
	s_mov_b32 m0, s58
	s_nop 0
	global_load_lds_dwordx4 v[164:165], off
	s_mov_b32 m0, s59
	s_nop 0
	global_load_lds_dwordx4 v[234:235], off
	s_waitcnt vmcnt(8)
	s_waitcnt lgkmcnt(0)
	s_barrier
	s_waitcnt lgkmcnt(0)
	v_mfma_f32_16x16x32_bf16 v[60:63], v[144:147], v[202:205], v[60:63]
	v_mfma_f32_16x16x32_bf16 v[56:59], v[172:175], v[202:205], v[56:59]
	v_mfma_f32_16x16x32_bf16 v[44:47], v[144:147], v[210:213], v[44:47]
	v_mfma_f32_16x16x32_bf16 v[40:43], v[172:175], v[210:213], v[40:43]
	v_mfma_f32_16x16x32_bf16 v[28:31], v[144:147], v[218:221], v[28:31]
	v_mfma_f32_16x16x32_bf16 v[24:27], v[172:175], v[218:221], v[24:27]
	v_mfma_f32_16x16x32_bf16 v[12:15], v[144:147], v[226:229], v[12:15]
	v_mfma_f32_16x16x32_bf16 v[8:11], v[172:175], v[226:229], v[8:11]
	v_mfma_f32_16x16x32_bf16 v[60:63], v[168:171], v[206:209], v[60:63]
	v_mfma_f32_16x16x32_bf16 v[56:59], v[176:179], v[206:209], v[56:59]
	v_mfma_f32_16x16x32_bf16 v[44:47], v[168:171], v[214:217], v[44:47]
	v_mfma_f32_16x16x32_bf16 v[40:43], v[176:179], v[214:217], v[40:43]
	v_mfma_f32_16x16x32_bf16 v[28:31], v[168:171], v[222:225], v[28:31]
	v_mfma_f32_16x16x32_bf16 v[24:27], v[176:179], v[222:225], v[24:27]
	v_mfma_f32_16x16x32_bf16 v[12:15], v[168:171], v[230:233], v[12:15]
	v_mfma_f32_16x16x32_bf16 v[8:11], v[176:179], v[230:233], v[8:11]
	v_mfma_f32_16x16x32_bf16 v[52:55], v[180:183], v[202:205], v[52:55]
	v_mfma_f32_16x16x32_bf16 v[48:51], v[188:191], v[202:205], v[48:51]
	v_mfma_f32_16x16x32_bf16 v[36:39], v[180:183], v[210:213], v[36:39]
	v_mfma_f32_16x16x32_bf16 v[32:35], v[188:191], v[210:213], v[32:35]
	v_mfma_f32_16x16x32_bf16 v[20:23], v[180:183], v[218:221], v[20:23]
	v_mfma_f32_16x16x32_bf16 v[16:19], v[188:191], v[218:221], v[16:19]
	v_mfma_f32_16x16x32_bf16 v[4:7], v[180:183], v[226:229], v[4:7]
	v_mfma_f32_16x16x32_bf16 v[0:3], v[188:191], v[226:229], v[0:3]
	v_mfma_f32_16x16x32_bf16 v[52:55], v[184:187], v[206:209], v[52:55]
	v_mfma_f32_16x16x32_bf16 v[48:51], v[198:201], v[206:209], v[48:51]
	v_mfma_f32_16x16x32_bf16 v[36:39], v[184:187], v[214:217], v[36:39]
	v_mfma_f32_16x16x32_bf16 v[32:35], v[198:201], v[214:217], v[32:35]
	v_mfma_f32_16x16x32_bf16 v[20:23], v[184:187], v[222:225], v[20:23]
	v_mfma_f32_16x16x32_bf16 v[16:19], v[198:201], v[222:225], v[16:19]
	v_mfma_f32_16x16x32_bf16 v[4:7], v[184:187], v[230:233], v[4:7]
	v_mfma_f32_16x16x32_bf16 v[0:3], v[198:201], v[230:233], v[0:3]
	s_barrier
; #define PG8_STAGE(bufoff, gbase, voff) do { _Pragma("unroll") for (int _i = 0; _i < 2; ++_i) \
;         __builtin_amdgcn_global_load_lds((const unsigned*)((const char*)(gbase) + (voff)[_i]), (PG8_LAS unsigned*)(lds + (bufoff) + ldsw + _i * 8192), 16, 0, 0); } while (0)
; #define PG8_LDA(dst, b, h) do { _Pragma("unroll") for (int m = 0; m < 4; ++m) _Pragma("unroll") for (int k = 0; k < 2; ++k) dst[m][k] = *(const PG8_LAS bf16x8*)(lds + PG8_SA(b, h) + aoff + m * 2048 + k * 1024); } while (0)
; #define PG8_LDB(dst, b, h) do { _Pragma("unroll") for (int n = 0; n < 2; ++n) _Pragma("unroll") for (int k = 0; k < 2; ++k) dst[n][k] = *(const PG8_LAS bf16x8*)(lds + PG8_SB(b, h) + boff + n * 2048 + k * 1024); } while (0)
; #define PG8_MMA(ai, bj, At, Bt) do { __builtin_amdgcn_s_setprio(1); _Pragma("unroll") for (int m = 0; m < 4; ++m) _Pragma("unroll") for (int n = 0; n < 2; ++n) _Pragma("unroll") for (int k = 0; k < 2; ++k) \
;         acc[ai][bj][m][n] = __builtin_amdgcn_mfma_f32_16x16x32_bf16(Bt[n][k], At[m][k], acc[ai][bj][m][n], 0, 0, 0); __builtin_amdgcn_s_setprio(0); } while (0)
; #define PG8_WAIT_V(n) asm volatile("s_waitcnt vmcnt(" #n ")" ::: "memory")
; #define PG8_WAIT_L(n) asm volatile("s_waitcnt lgkmcnt(" #n ")" ::: "memory")
; #define PG8_BAR __builtin_amdgcn_s_barrier()
; #define PG8_SCHED __builtin_amdgcn_sched_barrier(0)
; template <class Epi, class Sched, bool ALIGN_EPI = false, bool SP2 = false>
; __device__ __forceinline__ void gemm_phase(PG8_LAS unsigned char* lds, const Gemm g, const Sched& S, const Epi& E) {
;     ...
;         for (int t = 0; t < nt; t += 2) {
;             const bool last = (t == nt - 2);
;     ...
;             PG8_LDB(B0, 1, 0); PG8_LDB(B1, 1, 1); PG8_SCHED; PG8_LDA(At, 1, 0); PG8_STAGE(PG8_SA(0, 1), a2 + hstep, voffA);
;             PG8_WAIT_V(8); PG8_WAIT_L(0); PG8_BAR; PG8_MMA(0, 0, At, B0); PG8_MMA(0, 1, At, B1); PG8_BAR; PG8_SCHED;
;             PG8_LDA(At, 1, 1); PG8_STAGE(PG8_SB(1, 0), b3, voffB); PG8_STAGE(PG8_SB(1, 1), b3 + hstep, voffB); PG8_STAGE(PG8_SA(1, 0), a3, voffA);
;             PG8_WAIT_V(8); PG8_WAIT_L(0); PG8_BAR; PG8_MMA(1, 0, At, B0); PG8_MMA(1, 1, At, B1); PG8_BAR; PG8_SCHED;
	s_add_i32 s48, 0, 0x18000
	v_add_u32_e32 v157, s48, v151
	s_add_i32 s49, 0, 0x1c000
	ds_read_b128 v[144:147], v157
	ds_read_b128 v[168:171], v157 offset:1024
	ds_read_b128 v[172:175], v157 offset:2048
	ds_read_b128 v[176:179], v157 offset:3072
	v_add_u32_e32 v157, s49, v151
	ds_read_b128 v[180:183], v157
	ds_read_b128 v[184:187], v157 offset:1024
	ds_read_b128 v[188:191], v157 offset:2048
	ds_read_b128 v[198:201], v157 offset:3072
	s_add_u32 s6, s54, 0xb0000
	s_addc_u32 s7, s55, 0
	s_mov_b32 m0, s60
	ds_read_b128 v[202:205], v155 offset:32768
	ds_read_b128 v[206:209], v155 offset:33792
	ds_read_b128 v[210:213], v155 offset:34816
	ds_read_b128 v[214:217], v155 offset:35840
	ds_read_b128 v[218:221], v155 offset:36864
	ds_read_b128 v[222:225], v155 offset:37888
	ds_read_b128 v[226:229], v155 offset:38912
	ds_read_b128 v[230:233], v155 offset:39936
	global_load_lds_dwordx4 v128, s[6:7]
	s_mov_b32 m0, s61
	s_nop 0
	global_load_lds_dwordx4 v132, s[6:7]
	s_waitcnt vmcnt(8)
	s_waitcnt lgkmcnt(0)
	s_barrier
	s_waitcnt lgkmcnt(0)
	v_mfma_f32_16x16x32_bf16 v[124:127], v[144:147], v[202:205], v[124:127]
	v_mfma_f32_16x16x32_bf16 v[120:123], v[172:175], v[202:205], v[120:123]
	v_mfma_f32_16x16x32_bf16 v[108:111], v[144:147], v[210:213], v[108:111]
	v_mfma_f32_16x16x32_bf16 v[104:107], v[172:175], v[210:213], v[104:107]
	v_mfma_f32_16x16x32_bf16 v[92:95], v[144:147], v[218:221], v[92:95]
	v_mfma_f32_16x16x32_bf16 v[88:91], v[172:175], v[218:221], v[88:91]
	v_mfma_f32_16x16x32_bf16 v[76:79], v[144:147], v[226:229], v[76:79]
	v_mfma_f32_16x16x32_bf16 v[72:75], v[172:175], v[226:229], v[72:75]
	v_mfma_f32_16x16x32_bf16 v[124:127], v[168:171], v[206:209], v[124:127]
	v_mfma_f32_16x16x32_bf16 v[120:123], v[176:179], v[206:209], v[120:123]
	v_mfma_f32_16x16x32_bf16 v[108:111], v[168:171], v[214:217], v[108:111]
	v_mfma_f32_16x16x32_bf16 v[104:107], v[176:179], v[214:217], v[104:107]
	v_mfma_f32_16x16x32_bf16 v[92:95], v[168:171], v[222:225], v[92:95]
	v_mfma_f32_16x16x32_bf16 v[88:91], v[176:179], v[222:225], v[88:91]
	v_mfma_f32_16x16x32_bf16 v[76:79], v[168:171], v[230:233], v[76:79]
	v_mfma_f32_16x16x32_bf16 v[72:75], v[176:179], v[230:233], v[72:75]
	v_mfma_f32_16x16x32_bf16 v[116:119], v[180:183], v[202:205], v[116:119]
	v_mfma_f32_16x16x32_bf16 v[112:115], v[188:191], v[202:205], v[112:115]
	v_mfma_f32_16x16x32_bf16 v[100:103], v[180:183], v[210:213], v[100:103]
	v_mfma_f32_16x16x32_bf16 v[96:99], v[188:191], v[210:213], v[96:99]
	v_mfma_f32_16x16x32_bf16 v[84:87], v[180:183], v[218:221], v[84:87]
	v_mfma_f32_16x16x32_bf16 v[80:83], v[188:191], v[218:221], v[80:83]
	v_mfma_f32_16x16x32_bf16 v[68:71], v[180:183], v[226:229], v[68:71]
	v_mfma_f32_16x16x32_bf16 v[64:67], v[188:191], v[226:229], v[64:67]
	v_mfma_f32_16x16x32_bf16 v[116:119], v[184:187], v[206:209], v[116:119]
	v_mfma_f32_16x16x32_bf16 v[112:115], v[198:201], v[206:209], v[112:115]
	v_mfma_f32_16x16x32_bf16 v[100:103], v[184:187], v[214:217], v[100:103]
	v_mfma_f32_16x16x32_bf16 v[96:99], v[198:201], v[214:217], v[96:99]
	v_mfma_f32_16x16x32_bf16 v[84:87], v[184:187], v[222:225], v[84:87]
	v_mfma_f32_16x16x32_bf16 v[80:83], v[198:201], v[222:225], v[80:83]
	v_mfma_f32_16x16x32_bf16 v[68:71], v[184:187], v[230:233], v[68:71]
	v_mfma_f32_16x16x32_bf16 v[64:67], v[198:201], v[230:233], v[64:67]
	s_barrier
	s_add_i32 s6, s48, s57
	v_lshl_add_u64 v[148:149], v[148:149], 0, s[36:37]
	s_mov_b32 m0, s6
	ds_read_b128 v[202:205], v155 offset:49152
	ds_read_b128 v[206:209], v155 offset:50176
	ds_read_b128 v[210:213], v155 offset:51200
	ds_read_b128 v[214:217], v155 offset:52224
	ds_read_b128 v[218:221], v155 offset:53248
	ds_read_b128 v[222:225], v155 offset:54272
	ds_read_b128 v[226:229], v155 offset:55296
	ds_read_b128 v[230:233], v155 offset:56320
	global_load_lds_dwordx4 v[148:149], off
	s_add_i32 m0, s6, 0x2000
	s_add_u32 s6, s52, 0xb0080
	v_lshl_add_u64 v[148:149], v[158:159], 0, s[36:37]
	s_addc_u32 s7, s53, 0
	s_add_i32 s48, s49, s57
	global_load_lds_dwordx4 v[148:149], off
	s_mov_b32 m0, s48
	s_nop 0
	global_load_lds_dwordx4 v130, s[6:7]
	s_add_i32 m0, s48, 0x2000
	s_nop 0
	global_load_lds_dwordx4 v134, s[6:7]
	v_lshl_add_u64 v[148:149], v[164:165], 0, s[36:37]
	s_mov_b32 m0, s76
	s_nop 0
	global_load_lds_dwordx4 v[148:149], off
	v_lshl_add_u64 v[148:149], v[234:235], 0, s[36:37]
	s_mov_b32 m0, s4
	s_nop 0
	global_load_lds_dwordx4 v[148:149], off
	s_waitcnt vmcnt(8)
	s_waitcnt lgkmcnt(0)
	s_barrier
	s_waitcnt lgkmcnt(0)
	v_mfma_f32_16x16x32_bf16 v[60:63], v[144:147], v[202:205], v[60:63]
	v_mfma_f32_16x16x32_bf16 v[56:59], v[172:175], v[202:205], v[56:59]
	v_mfma_f32_16x16x32_bf16 v[44:47], v[144:147], v[210:213], v[44:47]
	v_mfma_f32_16x16x32_bf16 v[40:43], v[172:175], v[210:213], v[40:43]
	v_mfma_f32_16x16x32_bf16 v[28:31], v[144:147], v[218:221], v[28:31]
	v_mfma_f32_16x16x32_bf16 v[24:27], v[172:175], v[218:221], v[24:27]
	v_mfma_f32_16x16x32_bf16 v[12:15], v[144:147], v[226:229], v[12:15]
	v_mfma_f32_16x16x32_bf16 v[8:11], v[172:175], v[226:229], v[8:11]
	v_mfma_f32_16x16x32_bf16 v[60:63], v[168:171], v[206:209], v[60:63]
	v_mfma_f32_16x16x32_bf16 v[56:59], v[176:179], v[206:209], v[56:59]
	v_mfma_f32_16x16x32_bf16 v[44:47], v[168:171], v[214:217], v[44:47]
	v_mfma_f32_16x16x32_bf16 v[40:43], v[176:179], v[214:217], v[40:43]
	v_mfma_f32_16x16x32_bf16 v[28:31], v[168:171], v[222:225], v[28:31]
	v_mfma_f32_16x16x32_bf16 v[24:27], v[176:179], v[222:225], v[24:27]
	v_mfma_f32_16x16x32_bf16 v[12:15], v[168:171], v[230:233], v[12:15]
	v_mfma_f32_16x16x32_bf16 v[8:11], v[176:179], v[230:233], v[8:11]
	v_mfma_f32_16x16x32_bf16 v[52:55], v[180:183], v[202:205], v[52:55]
	v_mfma_f32_16x16x32_bf16 v[48:51], v[188:191], v[202:205], v[48:51]
	v_mfma_f32_16x16x32_bf16 v[36:39], v[180:183], v[210:213], v[36:39]
	v_mfma_f32_16x16x32_bf16 v[32:35], v[188:191], v[210:213], v[32:35]
	v_mfma_f32_16x16x32_bf16 v[20:23], v[180:183], v[218:221], v[20:23]
	v_mfma_f32_16x16x32_bf16 v[16:19], v[188:191], v[218:221], v[16:19]
	v_mfma_f32_16x16x32_bf16 v[4:7], v[180:183], v[226:229], v[4:7]
	v_mfma_f32_16x16x32_bf16 v[0:3], v[188:191], v[226:229], v[0:3]
	v_mfma_f32_16x16x32_bf16 v[52:55], v[184:187], v[206:209], v[52:55]
	v_mfma_f32_16x16x32_bf16 v[48:51], v[198:201], v[206:209], v[48:51]
	v_mfma_f32_16x16x32_bf16 v[36:39], v[184:187], v[214:217], v[36:39]
	v_mfma_f32_16x16x32_bf16 v[32:35], v[198:201], v[214:217], v[32:35]
	v_mfma_f32_16x16x32_bf16 v[20:23], v[184:187], v[222:225], v[20:23]
	v_mfma_f32_16x16x32_bf16 v[16:19], v[198:201], v[222:225], v[16:19]
	v_mfma_f32_16x16x32_bf16 v[4:7], v[184:187], v[230:233], v[4:7]
	v_mfma_f32_16x16x32_bf16 v[0:3], v[198:201], v[230:233], v[0:3]
	s_barrier
	s_add_i32 s72, s72, 2
	s_add_u32 s33, s33, 0x100
	s_addc_u32 s77, s77, 0
	s_cmp_gt_u32 s72, 41
	s_mov_b64 s[48:49], s[50:51]
	s_cbranch_scc0 .LBB0_1935
	s_and_b64 vcc, exec, s[38:39]
	s_cbranch_vccz .LBB0_1938
	s_barrier
